# pipelined gate epilogues (branch GEMM) + de-serialized LN vector staging and ctx slab accumulation
# speedup vs baseline: 1.0055x; 1.0055x over previous
; __device__ __forceinline__ unsigned cvt_pk_bf16(float lo, float hi) { const f32x2_t v = {lo, hi}; const bf16x2_t b = __builtin_convertvector(v, bf16x2_t); return __builtin_bit_cast(unsigned, b); }
; __device__ __forceinline__ float bf_lo(unsigned w) { return __uint_as_float(w << 16); }
; __device__ __forceinline__ float bf_hi(unsigned w) { return __uint_as_float(w & 0xffff0000u); }
;     __device__ __forceinline__ void operator()(const f32x4 (&acc)[2][2][4][2], const Unit& u, int wr, int wc, int fr, int fq) const {
;         const int row0 = u.pm * BM + wr * 64 + fr; const int col0 = u.pn * BM + wc * 32 + 8 * fq;
; #pragma unroll
;         for (int ai = 0; ai < 2; ++ai)
; #pragma unroll
;             for (int m = 0; m < 4; ++m) { const size_t row = (size_t)(row0 + ai * HALF + m * 16); bf16_t* rowp = U + (ACCUM ? (size_t)0 : (size_t)u.z * zsU) + row * ldc + col0; const bf16_t* gp = GT + row * ldg + (size_t)u.z * 2048 + col0;
; #pragma unroll
;                 for (int bj = 0; bj < 2; ++bj) { const u32x4 gw = *(const u32x4*)(gp + bj * HALF); u32x4 pw = (u32x4){0u, 0u, 0u, 0u}; if (ACCUM && u.z > 0) pw = *(const u32x4*)(rowp + bj * HALF);
;                     const f32x4 v0 = acc[ai][bj][m][0], v1 = acc[ai][bj][m][1]; const float a[8] = {v0[0], v0[1], v0[2], v0[3], v1[0], v1[1], v1[2], v1[3]};
;                     float o[8];
; #pragma unroll
;                     for (int j = 0; j < 4; ++j) { const unsigned g2 = gw[j], p2 = pw[j];
;                         const float s0 = __builtin_amdgcn_rcpf(1.f + __expf(-bf_lo(g2))), s1 = __builtin_amdgcn_rcpf(1.f + __expf(-bf_hi(g2)));
;                         o[2 * j] = bf_lo(p2) + s0 * a[2 * j]; o[2 * j + 1] = bf_hi(p2) + s1 * a[2 * j + 1]; }
;                     u32x4 w; w.x = cvt_pk_bf16(o[0], o[1]); w.y = cvt_pk_bf16(o[2], o[3]); w.z = cvt_pk_bf16(o[4], o[5]); w.w = cvt_pk_bf16(o[6], o[7]);
;                     *(u32x4*)(rowp + bj * HALF) = w; } }
.LBB0_1181:
	v_readlane_b32 s18, v251, 46
	v_readlane_b32 s19, v251, 47
	v_readlane_b32 s16, v246, 33
	v_readlane_b32 s17, v246, 34
	v_lshl_or_b32 v161, s15, 8, v158
	v_lshl_add_u32 v160, s30, 8, v156
	s_ashr_i32 s15, s14, 31
	s_lshl_b64 s[2:3], s[14:15], 12
	s_cmp_gt_i32 s14, 0
	s_mov_b32 s42, 0x0c0c0c0c
	s_mov_b32 s43, s42
	s_cselect_b32 s42, 0x01000c0c, s42
	s_cselect_b32 s43, 0x03020c0c, s43
	s_mov_b32 s100, 0xbfb8aa3b
	s_mov_b64 s[34:35], 0x45000
	v_lshlrev_b32_e32 v161, 1, v161
	v_lshl_add_u32 v252, v160, 12, v161
	v_mul_u32_u24_e32 v160, 0x8a00, v160
	v_add3_u32 v160, v160, v161, s2
	v_mov_b32_e32 v161, v252
	s_nop 3
	v_mov_b32_e32 v130, v160
	v_mov_b32_e32 v134, v161
	global_load_dwordx4 v[130:133], v130, s[18:19]
	global_load_dwordx4 v[134:137], v134, s[16:17]
	v_mov_b32_e32 v148, v160
	v_mov_b32_e32 v152, v161
	global_load_dwordx4 v[148:151], v148, s[18:19] offset:256
	global_load_dwordx4 v[152:155], v152, s[16:17] offset:256
	v_add_u32_e32 v178, 0x8a000, v160
	v_add_u32_e32 v182, 0x10000, v161
	global_load_dwordx4 v[178:181], v178, s[18:19]
	global_load_dwordx4 v[182:185], v182, s[16:17]
	v_add_u32_e32 v186, 0x8a000, v160
	v_add_u32_e32 v190, 0x10000, v161
	global_load_dwordx4 v[186:189], v186, s[18:19] offset:256
	global_load_dwordx4 v[190:193], v190, s[16:17] offset:256
	v_add_u32_e32 v194, 0x114000, v160
	v_add_u32_e32 v208, 0x20000, v161
	global_load_dwordx4 v[194:197], v194, s[18:19]
	global_load_dwordx4 v[208:211], v208, s[16:17]
	v_add_u32_e32 v212, 0x114000, v160
	v_add_u32_e32 v216, 0x20000, v161
	global_load_dwordx4 v[212:215], v212, s[18:19] offset:256
	global_load_dwordx4 v[216:219], v216, s[16:17] offset:256
	v_add_u32_e32 v220, 0x19e000, v160
	v_add_u32_e32 v224, 0x30000, v161
	global_load_dwordx4 v[220:223], v220, s[18:19]
	global_load_dwordx4 v[224:227], v224, s[16:17]
	v_add_u32_e32 v228, 0x19e000, v160
	v_add_u32_e32 v232, 0x30000, v161
	global_load_dwordx4 v[228:231], v228, s[18:19] offset:256
	global_load_dwordx4 v[232:235], v232, s[16:17] offset:256
	s_waitcnt vmcnt(14)
	v_lshlrev_b32_e32 v252, 16, v130
	v_and_b32_e32 v253, 0xffff0000, v130
	v_mul_f32_e32 v252, s100, v252
	v_mul_f32_e32 v253, s100, v253
	v_exp_f32_e32 v252, v252
	v_exp_f32_e32 v253, v253
	v_perm_b32 v254, v134, v134, s42
	v_perm_b32 v255, v134, v134, s43
	v_add_f32_e32 v252, 1.0, v252
	v_add_f32_e32 v253, 1.0, v253
	v_rcp_f32_e32 v252, v252
	v_rcp_f32_e32 v253, v253
	s_nop 0
	v_pk_fma_f32 v[126:127], v[126:127], v[252:253], v[254:255]
	v_lshlrev_b32_e32 v252, 16, v131
	v_and_b32_e32 v253, 0xffff0000, v131
	v_mul_f32_e32 v252, s100, v252
	v_mul_f32_e32 v253, s100, v253
	v_exp_f32_e32 v252, v252
	v_exp_f32_e32 v253, v253
	v_perm_b32 v254, v135, v135, s42
	v_perm_b32 v255, v135, v135, s43
	v_add_f32_e32 v252, 1.0, v252
	v_add_f32_e32 v253, 1.0, v253
	v_rcp_f32_e32 v252, v252
	v_rcp_f32_e32 v253, v253
	s_nop 0
	v_pk_fma_f32 v[128:129], v[128:129], v[252:253], v[254:255]
	v_lshlrev_b32_e32 v252, 16, v132
	v_and_b32_e32 v253, 0xffff0000, v132
	v_mul_f32_e32 v252, s100, v252
	v_mul_f32_e32 v253, s100, v253
	v_exp_f32_e32 v252, v252
	v_exp_f32_e32 v253, v253
	v_perm_b32 v254, v136, v136, s42
	v_perm_b32 v255, v136, v136, s43
	v_add_f32_e32 v252, 1.0, v252
	v_add_f32_e32 v253, 1.0, v253
	v_rcp_f32_e32 v252, v252
	v_rcp_f32_e32 v253, v253
	s_nop 0
	v_pk_fma_f32 v[122:123], v[122:123], v[252:253], v[254:255]
	v_lshlrev_b32_e32 v252, 16, v133
	v_and_b32_e32 v253, 0xffff0000, v133
	v_mul_f32_e32 v252, s100, v252
	v_mul_f32_e32 v253, s100, v253
	v_exp_f32_e32 v252, v252
	v_exp_f32_e32 v253, v253
	v_perm_b32 v254, v137, v137, s42
	v_perm_b32 v255, v137, v137, s43
	v_add_f32_e32 v252, 1.0, v252
	v_add_f32_e32 v253, 1.0, v253
	v_rcp_f32_e32 v252, v252
	v_rcp_f32_e32 v253, v253
	s_nop 0
	v_pk_fma_f32 v[124:125], v[124:125], v[252:253], v[254:255]
	v_cvt_pk_bf16_f32 v126, v126, v127
	v_cvt_pk_bf16_f32 v127, v128, v129
	v_cvt_pk_bf16_f32 v128, v122, v123
	v_cvt_pk_bf16_f32 v129, v124, v125
	v_mov_b32_e32 v252, v161
	global_store_dwordx4 v252, v[126:129], s[16:17]
	v_add_u32_e32 v130, 0x450000, v160
	v_add_u32_e32 v134, 0x80000, v161
	global_load_dwordx4 v[130:133], v130, s[18:19]
	global_load_dwordx4 v[134:137], v134, s[16:17]
	s_waitcnt vmcnt(15)
	v_lshlrev_b32_e32 v252, 16, v148
	v_and_b32_e32 v253, 0xffff0000, v148
	v_mul_f32_e32 v252, s100, v252
	v_mul_f32_e32 v253, s100, v253
	v_exp_f32_e32 v252, v252
	v_exp_f32_e32 v253, v253
	v_perm_b32 v254, v152, v152, s42
	v_perm_b32 v255, v152, v152, s43
	v_add_f32_e32 v252, 1.0, v252
	v_add_f32_e32 v253, 1.0, v253
	v_rcp_f32_e32 v252, v252
	v_rcp_f32_e32 v253, v253
	s_nop 0
	v_pk_fma_f32 v[118:119], v[118:119], v[252:253], v[254:255]
	v_lshlrev_b32_e32 v252, 16, v149
	v_and_b32_e32 v253, 0xffff0000, v149
	v_mul_f32_e32 v252, s100, v252
	v_mul_f32_e32 v253, s100, v253
	v_exp_f32_e32 v252, v252
	v_exp_f32_e32 v253, v253
	v_perm_b32 v254, v153, v153, s42
	v_perm_b32 v255, v153, v153, s43
	v_add_f32_e32 v252, 1.0, v252
	v_add_f32_e32 v253, 1.0, v253
	v_rcp_f32_e32 v252, v252
	v_rcp_f32_e32 v253, v253
	s_nop 0
	v_pk_fma_f32 v[120:121], v[120:121], v[252:253], v[254:255]
	v_lshlrev_b32_e32 v252, 16, v150
	v_and_b32_e32 v253, 0xffff0000, v150
	v_mul_f32_e32 v252, s100, v252
	v_mul_f32_e32 v253, s100, v253
	v_exp_f32_e32 v252, v252
	v_exp_f32_e32 v253, v253
	v_perm_b32 v254, v154, v154, s42
	v_perm_b32 v255, v154, v154, s43
	v_add_f32_e32 v252, 1.0, v252
	v_add_f32_e32 v253, 1.0, v253
	v_rcp_f32_e32 v252, v252
	v_rcp_f32_e32 v253, v253
	s_nop 0
	v_pk_fma_f32 v[114:115], v[114:115], v[252:253], v[254:255]
	v_lshlrev_b32_e32 v252, 16, v151
	v_and_b32_e32 v253, 0xffff0000, v151
	v_mul_f32_e32 v252, s100, v252
	v_mul_f32_e32 v253, s100, v253
	v_exp_f32_e32 v252, v252
	v_exp_f32_e32 v253, v253
	v_perm_b32 v254, v155, v155, s42
	v_perm_b32 v255, v155, v155, s43
	v_add_f32_e32 v252, 1.0, v252
	v_add_f32_e32 v253, 1.0, v253
	v_rcp_f32_e32 v252, v252
	v_rcp_f32_e32 v253, v253
	s_nop 0
	v_pk_fma_f32 v[116:117], v[116:117], v[252:253], v[254:255]
	v_cvt_pk_bf16_f32 v118, v118, v119
	v_cvt_pk_bf16_f32 v119, v120, v121
	v_cvt_pk_bf16_f32 v120, v114, v115
	v_cvt_pk_bf16_f32 v121, v116, v117
	v_mov_b32_e32 v252, v161
	global_store_dwordx4 v252, v[118:121], s[16:17] offset:256
	v_add_u32_e32 v148, 0x450000, v160
	v_add_u32_e32 v152, 0x80000, v161
	global_load_dwordx4 v[148:151], v148, s[18:19] offset:256
	global_load_dwordx4 v[152:155], v152, s[16:17] offset:256
	s_waitcnt vmcnt(16)
; __device__ __forceinline__ unsigned cvt_pk_bf16(float lo, float hi) { const f32x2_t v = {lo, hi}; const bf16x2_t b = __builtin_convertvector(v, bf16x2_t); return __builtin_bit_cast(unsigned, b); }
; __device__ __forceinline__ float bf_lo(unsigned w) { return __uint_as_float(w << 16); }
; __device__ __forceinline__ float bf_hi(unsigned w) { return __uint_as_float(w & 0xffff0000u); }
;     __device__ __forceinline__ void operator()(const f32x4 (&acc)[2][2][4][2], const Unit& u, int wr, int wc, int fr, int fq) const {
;     ...
;             for (int m = 0; m < 4; ++m) { const size_t row = (size_t)(row0 + ai * HALF + m * 16); bf16_t* rowp = U + (ACCUM ? (size_t)0 : (size_t)u.z * zsU) + row * ldc + col0; const bf16_t* gp = GT + row * ldg + (size_t)u.z * 2048 + col0;
; #pragma unroll
;                 for (int bj = 0; bj < 2; ++bj) { const u32x4 gw = *(const u32x4*)(gp + bj * HALF); u32x4 pw = (u32x4){0u, 0u, 0u, 0u}; if (ACCUM && u.z > 0) pw = *(const u32x4*)(rowp + bj * HALF);
;                     const f32x4 v0 = acc[ai][bj][m][0], v1 = acc[ai][bj][m][1]; const float a[8] = {v0[0], v0[1], v0[2], v0[3], v1[0], v1[1], v1[2], v1[3]};
;                     float o[8];
; #pragma unroll
;                     for (int j = 0; j < 4; ++j) { const unsigned g2 = gw[j], p2 = pw[j];
;                         const float s0 = __builtin_amdgcn_rcpf(1.f + __expf(-bf_lo(g2))), s1 = __builtin_amdgcn_rcpf(1.f + __expf(-bf_hi(g2)));
;                         o[2 * j] = bf_lo(p2) + s0 * a[2 * j]; o[2 * j + 1] = bf_hi(p2) + s1 * a[2 * j + 1]; }
;                     u32x4 w; w.x = cvt_pk_bf16(o[0], o[1]); w.y = cvt_pk_bf16(o[2], o[3]); w.z = cvt_pk_bf16(o[4], o[5]); w.w = cvt_pk_bf16(o[6], o[7]);
;                     *(u32x4*)(rowp + bj * HALF) = w; } }
	v_lshlrev_b32_e32 v252, 16, v178
	v_and_b32_e32 v253, 0xffff0000, v178
	v_mul_f32_e32 v252, s100, v252
	v_mul_f32_e32 v253, s100, v253
	v_exp_f32_e32 v252, v252
	v_exp_f32_e32 v253, v253
	v_perm_b32 v254, v182, v182, s42
	v_perm_b32 v255, v182, v182, s43
	v_add_f32_e32 v252, 1.0, v252
	v_add_f32_e32 v253, 1.0, v253
	v_rcp_f32_e32 v252, v252
	v_rcp_f32_e32 v253, v253
	s_nop 0
	v_pk_fma_f32 v[110:111], v[110:111], v[252:253], v[254:255]
	v_lshlrev_b32_e32 v252, 16, v179
	v_and_b32_e32 v253, 0xffff0000, v179
	v_mul_f32_e32 v252, s100, v252
	v_mul_f32_e32 v253, s100, v253
	v_exp_f32_e32 v252, v252
	v_exp_f32_e32 v253, v253
	v_perm_b32 v254, v183, v183, s42
	v_perm_b32 v255, v183, v183, s43
	v_add_f32_e32 v252, 1.0, v252
	v_add_f32_e32 v253, 1.0, v253
	v_rcp_f32_e32 v252, v252
	v_rcp_f32_e32 v253, v253
	s_nop 0
	v_pk_fma_f32 v[112:113], v[112:113], v[252:253], v[254:255]
	v_lshlrev_b32_e32 v252, 16, v180
	v_and_b32_e32 v253, 0xffff0000, v180
	v_mul_f32_e32 v252, s100, v252
	v_mul_f32_e32 v253, s100, v253
	v_exp_f32_e32 v252, v252
	v_exp_f32_e32 v253, v253
	v_perm_b32 v254, v184, v184, s42
	v_perm_b32 v255, v184, v184, s43
	v_add_f32_e32 v252, 1.0, v252
	v_add_f32_e32 v253, 1.0, v253
	v_rcp_f32_e32 v252, v252
	v_rcp_f32_e32 v253, v253
	s_nop 0
	v_pk_fma_f32 v[106:107], v[106:107], v[252:253], v[254:255]
	v_lshlrev_b32_e32 v252, 16, v181
	v_and_b32_e32 v253, 0xffff0000, v181
	v_mul_f32_e32 v252, s100, v252
	v_mul_f32_e32 v253, s100, v253
	v_exp_f32_e32 v252, v252
	v_exp_f32_e32 v253, v253
	v_perm_b32 v254, v185, v185, s42
	v_perm_b32 v255, v185, v185, s43
	v_add_f32_e32 v252, 1.0, v252
	v_add_f32_e32 v253, 1.0, v253
	v_rcp_f32_e32 v252, v252
	v_rcp_f32_e32 v253, v253
	s_nop 0
	v_pk_fma_f32 v[108:109], v[108:109], v[252:253], v[254:255]
	v_cvt_pk_bf16_f32 v110, v110, v111
	v_cvt_pk_bf16_f32 v111, v112, v113
	v_cvt_pk_bf16_f32 v112, v106, v107
	v_cvt_pk_bf16_f32 v113, v108, v109
	v_add_u32_e32 v252, 0x10000, v161
	global_store_dwordx4 v252, v[110:113], s[16:17]
	v_add_u32_e32 v178, 0x4da000, v160
	v_add_u32_e32 v182, 0x90000, v161
	global_load_dwordx4 v[178:181], v178, s[18:19]
	global_load_dwordx4 v[182:185], v182, s[16:17]
	s_waitcnt vmcnt(17)
	v_lshlrev_b32_e32 v252, 16, v186
	v_and_b32_e32 v253, 0xffff0000, v186
	v_mul_f32_e32 v252, s100, v252
	v_mul_f32_e32 v253, s100, v253
	v_exp_f32_e32 v252, v252
	v_exp_f32_e32 v253, v253
	v_perm_b32 v254, v190, v190, s42
	v_perm_b32 v255, v190, v190, s43
	v_add_f32_e32 v252, 1.0, v252
	v_add_f32_e32 v253, 1.0, v253
	v_rcp_f32_e32 v252, v252
	v_rcp_f32_e32 v253, v253
	s_nop 0
	v_pk_fma_f32 v[102:103], v[102:103], v[252:253], v[254:255]
	v_lshlrev_b32_e32 v252, 16, v187
	v_and_b32_e32 v253, 0xffff0000, v187
	v_mul_f32_e32 v252, s100, v252
	v_mul_f32_e32 v253, s100, v253
	v_exp_f32_e32 v252, v252
	v_exp_f32_e32 v253, v253
	v_perm_b32 v254, v191, v191, s42
	v_perm_b32 v255, v191, v191, s43
	v_add_f32_e32 v252, 1.0, v252
	v_add_f32_e32 v253, 1.0, v253
	v_rcp_f32_e32 v252, v252
	v_rcp_f32_e32 v253, v253
	s_nop 0
	v_pk_fma_f32 v[104:105], v[104:105], v[252:253], v[254:255]
	v_lshlrev_b32_e32 v252, 16, v188
	v_and_b32_e32 v253, 0xffff0000, v188
	v_mul_f32_e32 v252, s100, v252
	v_mul_f32_e32 v253, s100, v253
	v_exp_f32_e32 v252, v252
	v_exp_f32_e32 v253, v253
	v_perm_b32 v254, v192, v192, s42
	v_perm_b32 v255, v192, v192, s43
	v_add_f32_e32 v252, 1.0, v252
	v_add_f32_e32 v253, 1.0, v253
	v_rcp_f32_e32 v252, v252
	v_rcp_f32_e32 v253, v253
	s_nop 0
	v_pk_fma_f32 v[98:99], v[98:99], v[252:253], v[254:255]
	v_lshlrev_b32_e32 v252, 16, v189
	v_and_b32_e32 v253, 0xffff0000, v189
	v_mul_f32_e32 v252, s100, v252
	v_mul_f32_e32 v253, s100, v253
	v_exp_f32_e32 v252, v252
	v_exp_f32_e32 v253, v253
	v_perm_b32 v254, v193, v193, s42
	v_perm_b32 v255, v193, v193, s43
	v_add_f32_e32 v252, 1.0, v252
	v_add_f32_e32 v253, 1.0, v253
	v_rcp_f32_e32 v252, v252
	v_rcp_f32_e32 v253, v253
	s_nop 0
	v_pk_fma_f32 v[100:101], v[100:101], v[252:253], v[254:255]
	v_cvt_pk_bf16_f32 v102, v102, v103
	v_cvt_pk_bf16_f32 v103, v104, v105
	v_cvt_pk_bf16_f32 v104, v98, v99
	v_cvt_pk_bf16_f32 v105, v100, v101
	v_add_u32_e32 v252, 0x10000, v161
	global_store_dwordx4 v252, v[102:105], s[16:17] offset:256
	v_add_u32_e32 v186, 0x4da000, v160
	v_add_u32_e32 v190, 0x90000, v161
	global_load_dwordx4 v[186:189], v186, s[18:19] offset:256
	global_load_dwordx4 v[190:193], v190, s[16:17] offset:256
	s_waitcnt vmcnt(18)
	v_lshlrev_b32_e32 v252, 16, v194
	v_and_b32_e32 v253, 0xffff0000, v194
	v_mul_f32_e32 v252, s100, v252
	v_mul_f32_e32 v253, s100, v253
	v_exp_f32_e32 v252, v252
	v_exp_f32_e32 v253, v253
	v_perm_b32 v254, v208, v208, s42
	v_perm_b32 v255, v208, v208, s43
	v_add_f32_e32 v252, 1.0, v252
	v_add_f32_e32 v253, 1.0, v253
	v_rcp_f32_e32 v252, v252
	v_rcp_f32_e32 v253, v253
	s_nop 0
	v_pk_fma_f32 v[94:95], v[94:95], v[252:253], v[254:255]
	v_lshlrev_b32_e32 v252, 16, v195
	v_and_b32_e32 v253, 0xffff0000, v195
	v_mul_f32_e32 v252, s100, v252
	v_mul_f32_e32 v253, s100, v253
	v_exp_f32_e32 v252, v252
	v_exp_f32_e32 v253, v253
	v_perm_b32 v254, v209, v209, s42
	v_perm_b32 v255, v209, v209, s43
	v_add_f32_e32 v252, 1.0, v252
	v_add_f32_e32 v253, 1.0, v253
	v_rcp_f32_e32 v252, v252
	v_rcp_f32_e32 v253, v253
	s_nop 0
	v_pk_fma_f32 v[96:97], v[96:97], v[252:253], v[254:255]
	v_lshlrev_b32_e32 v252, 16, v196
	v_and_b32_e32 v253, 0xffff0000, v196
	v_mul_f32_e32 v252, s100, v252
	v_mul_f32_e32 v253, s100, v253
	v_exp_f32_e32 v252, v252
	v_exp_f32_e32 v253, v253
	v_perm_b32 v254, v210, v210, s42
	v_perm_b32 v255, v210, v210, s43
	v_add_f32_e32 v252, 1.0, v252
	v_add_f32_e32 v253, 1.0, v253
	v_rcp_f32_e32 v252, v252
	v_rcp_f32_e32 v253, v253
	s_nop 0
	v_pk_fma_f32 v[90:91], v[90:91], v[252:253], v[254:255]
	v_lshlrev_b32_e32 v252, 16, v197
	v_and_b32_e32 v253, 0xffff0000, v197
	v_mul_f32_e32 v252, s100, v252
	v_mul_f32_e32 v253, s100, v253
	v_exp_f32_e32 v252, v252
	v_exp_f32_e32 v253, v253
	v_perm_b32 v254, v211, v211, s42
	v_perm_b32 v255, v211, v211, s43
	v_add_f32_e32 v252, 1.0, v252
	v_add_f32_e32 v253, 1.0, v253
	v_rcp_f32_e32 v252, v252
	v_rcp_f32_e32 v253, v253
	s_nop 0
	v_pk_fma_f32 v[92:93], v[92:93], v[252:253], v[254:255]
	v_cvt_pk_bf16_f32 v94, v94, v95
	v_cvt_pk_bf16_f32 v95, v96, v97
	v_cvt_pk_bf16_f32 v96, v90, v91
	v_cvt_pk_bf16_f32 v97, v92, v93
	v_add_u32_e32 v252, 0x20000, v161
	global_store_dwordx4 v252, v[94:97], s[16:17]
	v_add_u32_e32 v194, 0x564000, v160
	v_add_u32_e32 v208, 0xa0000, v161
	global_load_dwordx4 v[194:197], v194, s[18:19]
	global_load_dwordx4 v[208:211], v208, s[16:17]
	s_waitcnt vmcnt(19)
; __device__ __forceinline__ unsigned cvt_pk_bf16(float lo, float hi) { const f32x2_t v = {lo, hi}; const bf16x2_t b = __builtin_convertvector(v, bf16x2_t); return __builtin_bit_cast(unsigned, b); }
; __device__ __forceinline__ float bf_lo(unsigned w) { return __uint_as_float(w << 16); }
; __device__ __forceinline__ float bf_hi(unsigned w) { return __uint_as_float(w & 0xffff0000u); }
;     __device__ __forceinline__ void operator()(const f32x4 (&acc)[2][2][4][2], const Unit& u, int wr, int wc, int fr, int fq) const {
;     ...
;             for (int m = 0; m < 4; ++m) { const size_t row = (size_t)(row0 + ai * HALF + m * 16); bf16_t* rowp = U + (ACCUM ? (size_t)0 : (size_t)u.z * zsU) + row * ldc + col0; const bf16_t* gp = GT + row * ldg + (size_t)u.z * 2048 + col0;
; #pragma unroll
;                 for (int bj = 0; bj < 2; ++bj) { const u32x4 gw = *(const u32x4*)(gp + bj * HALF); u32x4 pw = (u32x4){0u, 0u, 0u, 0u}; if (ACCUM && u.z > 0) pw = *(const u32x4*)(rowp + bj * HALF);
;                     const f32x4 v0 = acc[ai][bj][m][0], v1 = acc[ai][bj][m][1]; const float a[8] = {v0[0], v0[1], v0[2], v0[3], v1[0], v1[1], v1[2], v1[3]};
;                     float o[8];
; #pragma unroll
;                     for (int j = 0; j < 4; ++j) { const unsigned g2 = gw[j], p2 = pw[j];
;                         const float s0 = __builtin_amdgcn_rcpf(1.f + __expf(-bf_lo(g2))), s1 = __builtin_amdgcn_rcpf(1.f + __expf(-bf_hi(g2)));
;                         o[2 * j] = bf_lo(p2) + s0 * a[2 * j]; o[2 * j + 1] = bf_hi(p2) + s1 * a[2 * j + 1]; }
;                     u32x4 w; w.x = cvt_pk_bf16(o[0], o[1]); w.y = cvt_pk_bf16(o[2], o[3]); w.z = cvt_pk_bf16(o[4], o[5]); w.w = cvt_pk_bf16(o[6], o[7]);
;                     *(u32x4*)(rowp + bj * HALF) = w; } }
	v_lshlrev_b32_e32 v252, 16, v212
	v_and_b32_e32 v253, 0xffff0000, v212
	v_mul_f32_e32 v252, s100, v252
	v_mul_f32_e32 v253, s100, v253
	v_exp_f32_e32 v252, v252
	v_exp_f32_e32 v253, v253
	v_perm_b32 v254, v216, v216, s42
	v_perm_b32 v255, v216, v216, s43
	v_add_f32_e32 v252, 1.0, v252
	v_add_f32_e32 v253, 1.0, v253
	v_rcp_f32_e32 v252, v252
	v_rcp_f32_e32 v253, v253
	s_nop 0
	v_pk_fma_f32 v[86:87], v[86:87], v[252:253], v[254:255]
	v_lshlrev_b32_e32 v252, 16, v213
	v_and_b32_e32 v253, 0xffff0000, v213
	v_mul_f32_e32 v252, s100, v252
	v_mul_f32_e32 v253, s100, v253
	v_exp_f32_e32 v252, v252
	v_exp_f32_e32 v253, v253
	v_perm_b32 v254, v217, v217, s42
	v_perm_b32 v255, v217, v217, s43
	v_add_f32_e32 v252, 1.0, v252
	v_add_f32_e32 v253, 1.0, v253
	v_rcp_f32_e32 v252, v252
	v_rcp_f32_e32 v253, v253
	s_nop 0
	v_pk_fma_f32 v[88:89], v[88:89], v[252:253], v[254:255]
	v_lshlrev_b32_e32 v252, 16, v214
	v_and_b32_e32 v253, 0xffff0000, v214
	v_mul_f32_e32 v252, s100, v252
	v_mul_f32_e32 v253, s100, v253
	v_exp_f32_e32 v252, v252
	v_exp_f32_e32 v253, v253
	v_perm_b32 v254, v218, v218, s42
	v_perm_b32 v255, v218, v218, s43
	v_add_f32_e32 v252, 1.0, v252
	v_add_f32_e32 v253, 1.0, v253
	v_rcp_f32_e32 v252, v252
	v_rcp_f32_e32 v253, v253
	s_nop 0
	v_pk_fma_f32 v[82:83], v[82:83], v[252:253], v[254:255]
	v_lshlrev_b32_e32 v252, 16, v215
	v_and_b32_e32 v253, 0xffff0000, v215
	v_mul_f32_e32 v252, s100, v252
	v_mul_f32_e32 v253, s100, v253
	v_exp_f32_e32 v252, v252
	v_exp_f32_e32 v253, v253
	v_perm_b32 v254, v219, v219, s42
	v_perm_b32 v255, v219, v219, s43
	v_add_f32_e32 v252, 1.0, v252
	v_add_f32_e32 v253, 1.0, v253
	v_rcp_f32_e32 v252, v252
	v_rcp_f32_e32 v253, v253
	s_nop 0
	v_pk_fma_f32 v[84:85], v[84:85], v[252:253], v[254:255]
	v_cvt_pk_bf16_f32 v86, v86, v87
	v_cvt_pk_bf16_f32 v87, v88, v89
	v_cvt_pk_bf16_f32 v88, v82, v83
	v_cvt_pk_bf16_f32 v89, v84, v85
	v_add_u32_e32 v252, 0x20000, v161
	global_store_dwordx4 v252, v[86:89], s[16:17] offset:256
	v_add_u32_e32 v212, 0x564000, v160
	v_add_u32_e32 v216, 0xa0000, v161
	global_load_dwordx4 v[212:215], v212, s[18:19] offset:256
	global_load_dwordx4 v[216:219], v216, s[16:17] offset:256
	s_waitcnt vmcnt(20)
	v_lshlrev_b32_e32 v252, 16, v220
	v_and_b32_e32 v253, 0xffff0000, v220
	v_mul_f32_e32 v252, s100, v252
	v_mul_f32_e32 v253, s100, v253
	v_exp_f32_e32 v252, v252
	v_exp_f32_e32 v253, v253
	v_perm_b32 v254, v224, v224, s42
	v_perm_b32 v255, v224, v224, s43
	v_add_f32_e32 v252, 1.0, v252
	v_add_f32_e32 v253, 1.0, v253
	v_rcp_f32_e32 v252, v252
	v_rcp_f32_e32 v253, v253
	s_nop 0
	v_pk_fma_f32 v[78:79], v[78:79], v[252:253], v[254:255]
	v_lshlrev_b32_e32 v252, 16, v221
	v_and_b32_e32 v253, 0xffff0000, v221
	v_mul_f32_e32 v252, s100, v252
	v_mul_f32_e32 v253, s100, v253
	v_exp_f32_e32 v252, v252
	v_exp_f32_e32 v253, v253
	v_perm_b32 v254, v225, v225, s42
	v_perm_b32 v255, v225, v225, s43
	v_add_f32_e32 v252, 1.0, v252
	v_add_f32_e32 v253, 1.0, v253
	v_rcp_f32_e32 v252, v252
	v_rcp_f32_e32 v253, v253
	s_nop 0
	v_pk_fma_f32 v[80:81], v[80:81], v[252:253], v[254:255]
	v_lshlrev_b32_e32 v252, 16, v222
	v_and_b32_e32 v253, 0xffff0000, v222
	v_mul_f32_e32 v252, s100, v252
	v_mul_f32_e32 v253, s100, v253
	v_exp_f32_e32 v252, v252
	v_exp_f32_e32 v253, v253
	v_perm_b32 v254, v226, v226, s42
	v_perm_b32 v255, v226, v226, s43
	v_add_f32_e32 v252, 1.0, v252
	v_add_f32_e32 v253, 1.0, v253
	v_rcp_f32_e32 v252, v252
	v_rcp_f32_e32 v253, v253
	s_nop 0
	v_pk_fma_f32 v[74:75], v[74:75], v[252:253], v[254:255]
	v_lshlrev_b32_e32 v252, 16, v223
	v_and_b32_e32 v253, 0xffff0000, v223
	v_mul_f32_e32 v252, s100, v252
	v_mul_f32_e32 v253, s100, v253
	v_exp_f32_e32 v252, v252
	v_exp_f32_e32 v253, v253
	v_perm_b32 v254, v227, v227, s42
	v_perm_b32 v255, v227, v227, s43
	v_add_f32_e32 v252, 1.0, v252
	v_add_f32_e32 v253, 1.0, v253
	v_rcp_f32_e32 v252, v252
	v_rcp_f32_e32 v253, v253
	s_nop 0
	v_pk_fma_f32 v[76:77], v[76:77], v[252:253], v[254:255]
	v_cvt_pk_bf16_f32 v78, v78, v79
	v_cvt_pk_bf16_f32 v79, v80, v81
	v_cvt_pk_bf16_f32 v80, v74, v75
	v_cvt_pk_bf16_f32 v81, v76, v77
	v_add_u32_e32 v252, 0x30000, v161
	global_store_dwordx4 v252, v[78:81], s[16:17]
	v_add_u32_e32 v220, 0x5ee000, v160
	v_add_u32_e32 v224, 0xb0000, v161
	global_load_dwordx4 v[220:223], v220, s[18:19]
	global_load_dwordx4 v[224:227], v224, s[16:17]
	s_waitcnt vmcnt(21)
	v_lshlrev_b32_e32 v252, 16, v228
	v_and_b32_e32 v253, 0xffff0000, v228
	v_mul_f32_e32 v252, s100, v252
	v_mul_f32_e32 v253, s100, v253
	v_exp_f32_e32 v252, v252
	v_exp_f32_e32 v253, v253
	v_perm_b32 v254, v232, v232, s42
	v_perm_b32 v255, v232, v232, s43
	v_add_f32_e32 v252, 1.0, v252
	v_add_f32_e32 v253, 1.0, v253
	v_rcp_f32_e32 v252, v252
	v_rcp_f32_e32 v253, v253
	s_nop 0
	v_pk_fma_f32 v[70:71], v[70:71], v[252:253], v[254:255]
	v_lshlrev_b32_e32 v252, 16, v229
	v_and_b32_e32 v253, 0xffff0000, v229
	v_mul_f32_e32 v252, s100, v252
	v_mul_f32_e32 v253, s100, v253
	v_exp_f32_e32 v252, v252
	v_exp_f32_e32 v253, v253
	v_perm_b32 v254, v233, v233, s42
	v_perm_b32 v255, v233, v233, s43
	v_add_f32_e32 v252, 1.0, v252
	v_add_f32_e32 v253, 1.0, v253
	v_rcp_f32_e32 v252, v252
	v_rcp_f32_e32 v253, v253
	s_nop 0
	v_pk_fma_f32 v[72:73], v[72:73], v[252:253], v[254:255]
	v_lshlrev_b32_e32 v252, 16, v230
	v_and_b32_e32 v253, 0xffff0000, v230
	v_mul_f32_e32 v252, s100, v252
	v_mul_f32_e32 v253, s100, v253
	v_exp_f32_e32 v252, v252
	v_exp_f32_e32 v253, v253
	v_perm_b32 v254, v234, v234, s42
	v_perm_b32 v255, v234, v234, s43
	v_add_f32_e32 v252, 1.0, v252
	v_add_f32_e32 v253, 1.0, v253
	v_rcp_f32_e32 v252, v252
	v_rcp_f32_e32 v253, v253
	s_nop 0
	v_pk_fma_f32 v[66:67], v[66:67], v[252:253], v[254:255]
	v_lshlrev_b32_e32 v252, 16, v231
	v_and_b32_e32 v253, 0xffff0000, v231
	v_mul_f32_e32 v252, s100, v252
	v_mul_f32_e32 v253, s100, v253
	v_exp_f32_e32 v252, v252
	v_exp_f32_e32 v253, v253
	v_perm_b32 v254, v235, v235, s42
	v_perm_b32 v255, v235, v235, s43
	v_add_f32_e32 v252, 1.0, v252
	v_add_f32_e32 v253, 1.0, v253
	v_rcp_f32_e32 v252, v252
	v_rcp_f32_e32 v253, v253
	s_nop 0
	v_pk_fma_f32 v[68:69], v[68:69], v[252:253], v[254:255]
	v_cvt_pk_bf16_f32 v70, v70, v71
	v_cvt_pk_bf16_f32 v71, v72, v73
	v_cvt_pk_bf16_f32 v72, v66, v67
	v_cvt_pk_bf16_f32 v73, v68, v69
	v_add_u32_e32 v252, 0x30000, v161
	global_store_dwordx4 v252, v[70:73], s[16:17] offset:256
	v_add_u32_e32 v228, 0x5ee000, v160
	v_add_u32_e32 v232, 0xb0000, v161
	global_load_dwordx4 v[228:231], v228, s[18:19] offset:256
	global_load_dwordx4 v[232:235], v232, s[16:17] offset:256
	s_waitcnt vmcnt(21)
; __device__ __forceinline__ unsigned cvt_pk_bf16(float lo, float hi) { const f32x2_t v = {lo, hi}; const bf16x2_t b = __builtin_convertvector(v, bf16x2_t); return __builtin_bit_cast(unsigned, b); }
; __device__ __forceinline__ float bf_lo(unsigned w) { return __uint_as_float(w << 16); }
; __device__ __forceinline__ float bf_hi(unsigned w) { return __uint_as_float(w & 0xffff0000u); }
;     __device__ __forceinline__ void operator()(const f32x4 (&acc)[2][2][4][2], const Unit& u, int wr, int wc, int fr, int fq) const {
;     ...
;             for (int m = 0; m < 4; ++m) { const size_t row = (size_t)(row0 + ai * HALF + m * 16); bf16_t* rowp = U + (ACCUM ? (size_t)0 : (size_t)u.z * zsU) + row * ldc + col0; const bf16_t* gp = GT + row * ldg + (size_t)u.z * 2048 + col0;
; #pragma unroll
;                 for (int bj = 0; bj < 2; ++bj) { const u32x4 gw = *(const u32x4*)(gp + bj * HALF); u32x4 pw = (u32x4){0u, 0u, 0u, 0u}; if (ACCUM && u.z > 0) pw = *(const u32x4*)(rowp + bj * HALF);
;                     const f32x4 v0 = acc[ai][bj][m][0], v1 = acc[ai][bj][m][1]; const float a[8] = {v0[0], v0[1], v0[2], v0[3], v1[0], v1[1], v1[2], v1[3]};
;                     float o[8];
; #pragma unroll
;                     for (int j = 0; j < 4; ++j) { const unsigned g2 = gw[j], p2 = pw[j];
;                         const float s0 = __builtin_amdgcn_rcpf(1.f + __expf(-bf_lo(g2))), s1 = __builtin_amdgcn_rcpf(1.f + __expf(-bf_hi(g2)));
;                         o[2 * j] = bf_lo(p2) + s0 * a[2 * j]; o[2 * j + 1] = bf_hi(p2) + s1 * a[2 * j + 1]; }
;                     u32x4 w; w.x = cvt_pk_bf16(o[0], o[1]); w.y = cvt_pk_bf16(o[2], o[3]); w.z = cvt_pk_bf16(o[4], o[5]); w.w = cvt_pk_bf16(o[6], o[7]);
;                     *(u32x4*)(rowp + bj * HALF) = w; } }
	v_lshlrev_b32_e32 v252, 16, v130
	v_and_b32_e32 v253, 0xffff0000, v130
	v_mul_f32_e32 v252, s100, v252
	v_mul_f32_e32 v253, s100, v253
	v_exp_f32_e32 v252, v252
	v_exp_f32_e32 v253, v253
	v_perm_b32 v254, v134, v134, s42
	v_perm_b32 v255, v134, v134, s43
	v_add_f32_e32 v252, 1.0, v252
	v_add_f32_e32 v253, 1.0, v253
	v_rcp_f32_e32 v252, v252
	v_rcp_f32_e32 v253, v253
	s_nop 0
	v_pk_fma_f32 v[60:61], v[60:61], v[252:253], v[254:255]
	v_lshlrev_b32_e32 v252, 16, v131
	v_and_b32_e32 v253, 0xffff0000, v131
	v_mul_f32_e32 v252, s100, v252
	v_mul_f32_e32 v253, s100, v253
	v_exp_f32_e32 v252, v252
	v_exp_f32_e32 v253, v253
	v_perm_b32 v254, v135, v135, s42
	v_perm_b32 v255, v135, v135, s43
	v_add_f32_e32 v252, 1.0, v252
	v_add_f32_e32 v253, 1.0, v253
	v_rcp_f32_e32 v252, v252
	v_rcp_f32_e32 v253, v253
	s_nop 0
	v_pk_fma_f32 v[62:63], v[62:63], v[252:253], v[254:255]
	v_lshlrev_b32_e32 v252, 16, v132
	v_and_b32_e32 v253, 0xffff0000, v132
	v_mul_f32_e32 v252, s100, v252
	v_mul_f32_e32 v253, s100, v253
	v_exp_f32_e32 v252, v252
	v_exp_f32_e32 v253, v253
	v_perm_b32 v254, v136, v136, s42
	v_perm_b32 v255, v136, v136, s43
	v_add_f32_e32 v252, 1.0, v252
	v_add_f32_e32 v253, 1.0, v253
	v_rcp_f32_e32 v252, v252
	v_rcp_f32_e32 v253, v253
	s_nop 0
	v_pk_fma_f32 v[56:57], v[56:57], v[252:253], v[254:255]
	v_lshlrev_b32_e32 v252, 16, v133
	v_and_b32_e32 v253, 0xffff0000, v133
	v_mul_f32_e32 v252, s100, v252
	v_mul_f32_e32 v253, s100, v253
	v_exp_f32_e32 v252, v252
	v_exp_f32_e32 v253, v253
	v_perm_b32 v254, v137, v137, s42
	v_perm_b32 v255, v137, v137, s43
	v_add_f32_e32 v252, 1.0, v252
	v_add_f32_e32 v253, 1.0, v253
	v_rcp_f32_e32 v252, v252
	v_rcp_f32_e32 v253, v253
	s_nop 0
	v_pk_fma_f32 v[58:59], v[58:59], v[252:253], v[254:255]
	v_cvt_pk_bf16_f32 v60, v60, v61
	v_cvt_pk_bf16_f32 v61, v62, v63
	v_cvt_pk_bf16_f32 v62, v56, v57
	v_cvt_pk_bf16_f32 v63, v58, v59
	v_add_u32_e32 v252, 0x80000, v161
	global_store_dwordx4 v252, v[60:63], s[16:17]
	s_waitcnt vmcnt(19)
	v_lshlrev_b32_e32 v252, 16, v148
	v_and_b32_e32 v253, 0xffff0000, v148
	v_mul_f32_e32 v252, s100, v252
	v_mul_f32_e32 v253, s100, v253
	v_exp_f32_e32 v252, v252
	v_exp_f32_e32 v253, v253
	v_perm_b32 v254, v152, v152, s42
	v_perm_b32 v255, v152, v152, s43
	v_add_f32_e32 v252, 1.0, v252
	v_add_f32_e32 v253, 1.0, v253
	v_rcp_f32_e32 v252, v252
	v_rcp_f32_e32 v253, v253
	s_nop 0
	v_pk_fma_f32 v[52:53], v[52:53], v[252:253], v[254:255]
	v_lshlrev_b32_e32 v252, 16, v149
	v_and_b32_e32 v253, 0xffff0000, v149
	v_mul_f32_e32 v252, s100, v252
	v_mul_f32_e32 v253, s100, v253
	v_exp_f32_e32 v252, v252
	v_exp_f32_e32 v253, v253
	v_perm_b32 v254, v153, v153, s42
	v_perm_b32 v255, v153, v153, s43
	v_add_f32_e32 v252, 1.0, v252
	v_add_f32_e32 v253, 1.0, v253
	v_rcp_f32_e32 v252, v252
	v_rcp_f32_e32 v253, v253
	s_nop 0
	v_pk_fma_f32 v[54:55], v[54:55], v[252:253], v[254:255]
	v_lshlrev_b32_e32 v252, 16, v150
	v_and_b32_e32 v253, 0xffff0000, v150
	v_mul_f32_e32 v252, s100, v252
	v_mul_f32_e32 v253, s100, v253
	v_exp_f32_e32 v252, v252
	v_exp_f32_e32 v253, v253
	v_perm_b32 v254, v154, v154, s42
	v_perm_b32 v255, v154, v154, s43
	v_add_f32_e32 v252, 1.0, v252
	v_add_f32_e32 v253, 1.0, v253
	v_rcp_f32_e32 v252, v252
	v_rcp_f32_e32 v253, v253
	s_nop 0
	v_pk_fma_f32 v[48:49], v[48:49], v[252:253], v[254:255]
	v_lshlrev_b32_e32 v252, 16, v151
	v_and_b32_e32 v253, 0xffff0000, v151
	v_mul_f32_e32 v252, s100, v252
	v_mul_f32_e32 v253, s100, v253
	v_exp_f32_e32 v252, v252
	v_exp_f32_e32 v253, v253
	v_perm_b32 v254, v155, v155, s42
	v_perm_b32 v255, v155, v155, s43
	v_add_f32_e32 v252, 1.0, v252
	v_add_f32_e32 v253, 1.0, v253
	v_rcp_f32_e32 v252, v252
	v_rcp_f32_e32 v253, v253
	s_nop 0
	v_pk_fma_f32 v[50:51], v[50:51], v[252:253], v[254:255]
	v_cvt_pk_bf16_f32 v52, v52, v53
	v_cvt_pk_bf16_f32 v53, v54, v55
	v_cvt_pk_bf16_f32 v54, v48, v49
	v_cvt_pk_bf16_f32 v55, v50, v51
	v_add_u32_e32 v252, 0x80000, v161
	global_store_dwordx4 v252, v[52:55], s[16:17] offset:256
	s_waitcnt vmcnt(17)
	v_lshlrev_b32_e32 v252, 16, v178
	v_and_b32_e32 v253, 0xffff0000, v178
	v_mul_f32_e32 v252, s100, v252
	v_mul_f32_e32 v253, s100, v253
	v_exp_f32_e32 v252, v252
	v_exp_f32_e32 v253, v253
	v_perm_b32 v254, v182, v182, s42
	v_perm_b32 v255, v182, v182, s43
	v_add_f32_e32 v252, 1.0, v252
	v_add_f32_e32 v253, 1.0, v253
	v_rcp_f32_e32 v252, v252
	v_rcp_f32_e32 v253, v253
	s_nop 0
	v_pk_fma_f32 v[44:45], v[44:45], v[252:253], v[254:255]
	v_lshlrev_b32_e32 v252, 16, v179
	v_and_b32_e32 v253, 0xffff0000, v179
	v_mul_f32_e32 v252, s100, v252
	v_mul_f32_e32 v253, s100, v253
	v_exp_f32_e32 v252, v252
	v_exp_f32_e32 v253, v253
	v_perm_b32 v254, v183, v183, s42
	v_perm_b32 v255, v183, v183, s43
	v_add_f32_e32 v252, 1.0, v252
	v_add_f32_e32 v253, 1.0, v253
	v_rcp_f32_e32 v252, v252
	v_rcp_f32_e32 v253, v253
	s_nop 0
	v_pk_fma_f32 v[46:47], v[46:47], v[252:253], v[254:255]
	v_lshlrev_b32_e32 v252, 16, v180
	v_and_b32_e32 v253, 0xffff0000, v180
	v_mul_f32_e32 v252, s100, v252
	v_mul_f32_e32 v253, s100, v253
	v_exp_f32_e32 v252, v252
	v_exp_f32_e32 v253, v253
	v_perm_b32 v254, v184, v184, s42
	v_perm_b32 v255, v184, v184, s43
	v_add_f32_e32 v252, 1.0, v252
	v_add_f32_e32 v253, 1.0, v253
	v_rcp_f32_e32 v252, v252
	v_rcp_f32_e32 v253, v253
	s_nop 0
	v_pk_fma_f32 v[40:41], v[40:41], v[252:253], v[254:255]
	v_lshlrev_b32_e32 v252, 16, v181
	v_and_b32_e32 v253, 0xffff0000, v181
	v_mul_f32_e32 v252, s100, v252
	v_mul_f32_e32 v253, s100, v253
	v_exp_f32_e32 v252, v252
	v_exp_f32_e32 v253, v253
	v_perm_b32 v254, v185, v185, s42
	v_perm_b32 v255, v185, v185, s43
	v_add_f32_e32 v252, 1.0, v252
	v_add_f32_e32 v253, 1.0, v253
	v_rcp_f32_e32 v252, v252
	v_rcp_f32_e32 v253, v253
	s_nop 0
	v_pk_fma_f32 v[42:43], v[42:43], v[252:253], v[254:255]
	v_cvt_pk_bf16_f32 v44, v44, v45
	v_cvt_pk_bf16_f32 v45, v46, v47
	v_cvt_pk_bf16_f32 v46, v40, v41
	v_cvt_pk_bf16_f32 v47, v42, v43
	v_add_u32_e32 v252, 0x90000, v161
	global_store_dwordx4 v252, v[44:47], s[16:17]
	s_waitcnt vmcnt(15)
; __device__ __forceinline__ unsigned cvt_pk_bf16(float lo, float hi) { const f32x2_t v = {lo, hi}; const bf16x2_t b = __builtin_convertvector(v, bf16x2_t); return __builtin_bit_cast(unsigned, b); }
; __device__ __forceinline__ float bf_lo(unsigned w) { return __uint_as_float(w << 16); }
; __device__ __forceinline__ float bf_hi(unsigned w) { return __uint_as_float(w & 0xffff0000u); }
;     __device__ __forceinline__ void operator()(const f32x4 (&acc)[2][2][4][2], const Unit& u, int wr, int wc, int fr, int fq) const {
;     ...
;             for (int m = 0; m < 4; ++m) { const size_t row = (size_t)(row0 + ai * HALF + m * 16); bf16_t* rowp = U + (ACCUM ? (size_t)0 : (size_t)u.z * zsU) + row * ldc + col0; const bf16_t* gp = GT + row * ldg + (size_t)u.z * 2048 + col0;
; #pragma unroll
;                 for (int bj = 0; bj < 2; ++bj) { const u32x4 gw = *(const u32x4*)(gp + bj * HALF); u32x4 pw = (u32x4){0u, 0u, 0u, 0u}; if (ACCUM && u.z > 0) pw = *(const u32x4*)(rowp + bj * HALF);
;                     const f32x4 v0 = acc[ai][bj][m][0], v1 = acc[ai][bj][m][1]; const float a[8] = {v0[0], v0[1], v0[2], v0[3], v1[0], v1[1], v1[2], v1[3]};
;                     float o[8];
; #pragma unroll
;                     for (int j = 0; j < 4; ++j) { const unsigned g2 = gw[j], p2 = pw[j];
;                         const float s0 = __builtin_amdgcn_rcpf(1.f + __expf(-bf_lo(g2))), s1 = __builtin_amdgcn_rcpf(1.f + __expf(-bf_hi(g2)));
;                         o[2 * j] = bf_lo(p2) + s0 * a[2 * j]; o[2 * j + 1] = bf_hi(p2) + s1 * a[2 * j + 1]; }
;                     u32x4 w; w.x = cvt_pk_bf16(o[0], o[1]); w.y = cvt_pk_bf16(o[2], o[3]); w.z = cvt_pk_bf16(o[4], o[5]); w.w = cvt_pk_bf16(o[6], o[7]);
;                     *(u32x4*)(rowp + bj * HALF) = w; } }
	v_lshlrev_b32_e32 v252, 16, v186
	v_and_b32_e32 v253, 0xffff0000, v186
	v_mul_f32_e32 v252, s100, v252
	v_mul_f32_e32 v253, s100, v253
	v_exp_f32_e32 v252, v252
	v_exp_f32_e32 v253, v253
	v_perm_b32 v254, v190, v190, s42
	v_perm_b32 v255, v190, v190, s43
	v_add_f32_e32 v252, 1.0, v252
	v_add_f32_e32 v253, 1.0, v253
	v_rcp_f32_e32 v252, v252
	v_rcp_f32_e32 v253, v253
	s_nop 0
	v_pk_fma_f32 v[36:37], v[36:37], v[252:253], v[254:255]
	v_lshlrev_b32_e32 v252, 16, v187
	v_and_b32_e32 v253, 0xffff0000, v187
	v_mul_f32_e32 v252, s100, v252
	v_mul_f32_e32 v253, s100, v253
	v_exp_f32_e32 v252, v252
	v_exp_f32_e32 v253, v253
	v_perm_b32 v254, v191, v191, s42
	v_perm_b32 v255, v191, v191, s43
	v_add_f32_e32 v252, 1.0, v252
	v_add_f32_e32 v253, 1.0, v253
	v_rcp_f32_e32 v252, v252
	v_rcp_f32_e32 v253, v253
	s_nop 0
	v_pk_fma_f32 v[38:39], v[38:39], v[252:253], v[254:255]
	v_lshlrev_b32_e32 v252, 16, v188
	v_and_b32_e32 v253, 0xffff0000, v188
	v_mul_f32_e32 v252, s100, v252
	v_mul_f32_e32 v253, s100, v253
	v_exp_f32_e32 v252, v252
	v_exp_f32_e32 v253, v253
	v_perm_b32 v254, v192, v192, s42
	v_perm_b32 v255, v192, v192, s43
	v_add_f32_e32 v252, 1.0, v252
	v_add_f32_e32 v253, 1.0, v253
	v_rcp_f32_e32 v252, v252
	v_rcp_f32_e32 v253, v253
	s_nop 0
	v_pk_fma_f32 v[32:33], v[32:33], v[252:253], v[254:255]
	v_lshlrev_b32_e32 v252, 16, v189
	v_and_b32_e32 v253, 0xffff0000, v189
	v_mul_f32_e32 v252, s100, v252
	v_mul_f32_e32 v253, s100, v253
	v_exp_f32_e32 v252, v252
	v_exp_f32_e32 v253, v253
	v_perm_b32 v254, v193, v193, s42
	v_perm_b32 v255, v193, v193, s43
	v_add_f32_e32 v252, 1.0, v252
	v_add_f32_e32 v253, 1.0, v253
	v_rcp_f32_e32 v252, v252
	v_rcp_f32_e32 v253, v253
	s_nop 0
	v_pk_fma_f32 v[34:35], v[34:35], v[252:253], v[254:255]
	v_cvt_pk_bf16_f32 v36, v36, v37
	v_cvt_pk_bf16_f32 v37, v38, v39
	v_cvt_pk_bf16_f32 v38, v32, v33
	v_cvt_pk_bf16_f32 v39, v34, v35
	v_add_u32_e32 v252, 0x90000, v161
	global_store_dwordx4 v252, v[36:39], s[16:17] offset:256
	s_waitcnt vmcnt(13)
	v_lshlrev_b32_e32 v252, 16, v194
	v_and_b32_e32 v253, 0xffff0000, v194
	v_mul_f32_e32 v252, s100, v252
	v_mul_f32_e32 v253, s100, v253
	v_exp_f32_e32 v252, v252
	v_exp_f32_e32 v253, v253
	v_perm_b32 v254, v208, v208, s42
	v_perm_b32 v255, v208, v208, s43
	v_add_f32_e32 v252, 1.0, v252
	v_add_f32_e32 v253, 1.0, v253
	v_rcp_f32_e32 v252, v252
	v_rcp_f32_e32 v253, v253
	s_nop 0
	v_pk_fma_f32 v[28:29], v[28:29], v[252:253], v[254:255]
	v_lshlrev_b32_e32 v252, 16, v195
	v_and_b32_e32 v253, 0xffff0000, v195
	v_mul_f32_e32 v252, s100, v252
	v_mul_f32_e32 v253, s100, v253
	v_exp_f32_e32 v252, v252
	v_exp_f32_e32 v253, v253
	v_perm_b32 v254, v209, v209, s42
	v_perm_b32 v255, v209, v209, s43
	v_add_f32_e32 v252, 1.0, v252
	v_add_f32_e32 v253, 1.0, v253
	v_rcp_f32_e32 v252, v252
	v_rcp_f32_e32 v253, v253
	s_nop 0
	v_pk_fma_f32 v[30:31], v[30:31], v[252:253], v[254:255]
	v_lshlrev_b32_e32 v252, 16, v196
	v_and_b32_e32 v253, 0xffff0000, v196
	v_mul_f32_e32 v252, s100, v252
	v_mul_f32_e32 v253, s100, v253
	v_exp_f32_e32 v252, v252
	v_exp_f32_e32 v253, v253
	v_perm_b32 v254, v210, v210, s42
	v_perm_b32 v255, v210, v210, s43
	v_add_f32_e32 v252, 1.0, v252
	v_add_f32_e32 v253, 1.0, v253
	v_rcp_f32_e32 v252, v252
	v_rcp_f32_e32 v253, v253
	s_nop 0
	v_pk_fma_f32 v[24:25], v[24:25], v[252:253], v[254:255]
	v_lshlrev_b32_e32 v252, 16, v197
	v_and_b32_e32 v253, 0xffff0000, v197
	v_mul_f32_e32 v252, s100, v252
	v_mul_f32_e32 v253, s100, v253
	v_exp_f32_e32 v252, v252
	v_exp_f32_e32 v253, v253
	v_perm_b32 v254, v211, v211, s42
	v_perm_b32 v255, v211, v211, s43
	v_add_f32_e32 v252, 1.0, v252
	v_add_f32_e32 v253, 1.0, v253
	v_rcp_f32_e32 v252, v252
	v_rcp_f32_e32 v253, v253
	s_nop 0
	v_pk_fma_f32 v[26:27], v[26:27], v[252:253], v[254:255]
	v_cvt_pk_bf16_f32 v28, v28, v29
	v_cvt_pk_bf16_f32 v29, v30, v31
	v_cvt_pk_bf16_f32 v30, v24, v25
	v_cvt_pk_bf16_f32 v31, v26, v27
	v_add_u32_e32 v252, 0xa0000, v161
	global_store_dwordx4 v252, v[28:31], s[16:17]
	s_waitcnt vmcnt(11)
	v_lshlrev_b32_e32 v252, 16, v212
	v_and_b32_e32 v253, 0xffff0000, v212
	v_mul_f32_e32 v252, s100, v252
	v_mul_f32_e32 v253, s100, v253
	v_exp_f32_e32 v252, v252
	v_exp_f32_e32 v253, v253
	v_perm_b32 v254, v216, v216, s42
	v_perm_b32 v255, v216, v216, s43
	v_add_f32_e32 v252, 1.0, v252
	v_add_f32_e32 v253, 1.0, v253
	v_rcp_f32_e32 v252, v252
	v_rcp_f32_e32 v253, v253
	s_nop 0
	v_pk_fma_f32 v[20:21], v[20:21], v[252:253], v[254:255]
	v_lshlrev_b32_e32 v252, 16, v213
	v_and_b32_e32 v253, 0xffff0000, v213
	v_mul_f32_e32 v252, s100, v252
	v_mul_f32_e32 v253, s100, v253
	v_exp_f32_e32 v252, v252
	v_exp_f32_e32 v253, v253
	v_perm_b32 v254, v217, v217, s42
	v_perm_b32 v255, v217, v217, s43
	v_add_f32_e32 v252, 1.0, v252
	v_add_f32_e32 v253, 1.0, v253
	v_rcp_f32_e32 v252, v252
	v_rcp_f32_e32 v253, v253
	s_nop 0
	v_pk_fma_f32 v[22:23], v[22:23], v[252:253], v[254:255]
	v_lshlrev_b32_e32 v252, 16, v214
	v_and_b32_e32 v253, 0xffff0000, v214
	v_mul_f32_e32 v252, s100, v252
	v_mul_f32_e32 v253, s100, v253
	v_exp_f32_e32 v252, v252
	v_exp_f32_e32 v253, v253
	v_perm_b32 v254, v218, v218, s42
	v_perm_b32 v255, v218, v218, s43
	v_add_f32_e32 v252, 1.0, v252
	v_add_f32_e32 v253, 1.0, v253
	v_rcp_f32_e32 v252, v252
	v_rcp_f32_e32 v253, v253
	s_nop 0
	v_pk_fma_f32 v[16:17], v[16:17], v[252:253], v[254:255]
	v_lshlrev_b32_e32 v252, 16, v215
	v_and_b32_e32 v253, 0xffff0000, v215
	v_mul_f32_e32 v252, s100, v252
	v_mul_f32_e32 v253, s100, v253
	v_exp_f32_e32 v252, v252
	v_exp_f32_e32 v253, v253
	v_perm_b32 v254, v219, v219, s42
	v_perm_b32 v255, v219, v219, s43
	v_add_f32_e32 v252, 1.0, v252
	v_add_f32_e32 v253, 1.0, v253
	v_rcp_f32_e32 v252, v252
	v_rcp_f32_e32 v253, v253
	s_nop 0
	v_pk_fma_f32 v[18:19], v[18:19], v[252:253], v[254:255]
	v_cvt_pk_bf16_f32 v20, v20, v21
	v_cvt_pk_bf16_f32 v21, v22, v23
	v_cvt_pk_bf16_f32 v22, v16, v17
	v_cvt_pk_bf16_f32 v23, v18, v19
	v_add_u32_e32 v252, 0xa0000, v161
	global_store_dwordx4 v252, v[20:23], s[16:17] offset:256
	s_waitcnt vmcnt(9)
; __device__ __forceinline__ unsigned cvt_pk_bf16(float lo, float hi) { const f32x2_t v = {lo, hi}; const bf16x2_t b = __builtin_convertvector(v, bf16x2_t); return __builtin_bit_cast(unsigned, b); }
; __device__ __forceinline__ float bf_lo(unsigned w) { return __uint_as_float(w << 16); }
; __device__ __forceinline__ float bf_hi(unsigned w) { return __uint_as_float(w & 0xffff0000u); }
;     __device__ __forceinline__ void operator()(const f32x4 (&acc)[2][2][4][2], const Unit& u, int wr, int wc, int fr, int fq) const {
;     ...
;             for (int m = 0; m < 4; ++m) { const size_t row = (size_t)(row0 + ai * HALF + m * 16); bf16_t* rowp = U + (ACCUM ? (size_t)0 : (size_t)u.z * zsU) + row * ldc + col0; const bf16_t* gp = GT + row * ldg + (size_t)u.z * 2048 + col0;
; #pragma unroll
;                 for (int bj = 0; bj < 2; ++bj) { const u32x4 gw = *(const u32x4*)(gp + bj * HALF); u32x4 pw = (u32x4){0u, 0u, 0u, 0u}; if (ACCUM && u.z > 0) pw = *(const u32x4*)(rowp + bj * HALF);
;                     const f32x4 v0 = acc[ai][bj][m][0], v1 = acc[ai][bj][m][1]; const float a[8] = {v0[0], v0[1], v0[2], v0[3], v1[0], v1[1], v1[2], v1[3]};
;                     float o[8];
; #pragma unroll
;                     for (int j = 0; j < 4; ++j) { const unsigned g2 = gw[j], p2 = pw[j];
;                         const float s0 = __builtin_amdgcn_rcpf(1.f + __expf(-bf_lo(g2))), s1 = __builtin_amdgcn_rcpf(1.f + __expf(-bf_hi(g2)));
;                         o[2 * j] = bf_lo(p2) + s0 * a[2 * j]; o[2 * j + 1] = bf_hi(p2) + s1 * a[2 * j + 1]; }
;                     u32x4 w; w.x = cvt_pk_bf16(o[0], o[1]); w.y = cvt_pk_bf16(o[2], o[3]); w.z = cvt_pk_bf16(o[4], o[5]); w.w = cvt_pk_bf16(o[6], o[7]);
;                     *(u32x4*)(rowp + bj * HALF) = w; } }
	v_lshlrev_b32_e32 v252, 16, v220
	v_and_b32_e32 v253, 0xffff0000, v220
	v_mul_f32_e32 v252, s100, v252
	v_mul_f32_e32 v253, s100, v253
	v_exp_f32_e32 v252, v252
	v_exp_f32_e32 v253, v253
	v_perm_b32 v254, v224, v224, s42
	v_perm_b32 v255, v224, v224, s43
	v_add_f32_e32 v252, 1.0, v252
	v_add_f32_e32 v253, 1.0, v253
	v_rcp_f32_e32 v252, v252
	v_rcp_f32_e32 v253, v253
	s_nop 0
	v_pk_fma_f32 v[12:13], v[12:13], v[252:253], v[254:255]
	v_lshlrev_b32_e32 v252, 16, v221
	v_and_b32_e32 v253, 0xffff0000, v221
	v_mul_f32_e32 v252, s100, v252
	v_mul_f32_e32 v253, s100, v253
	v_exp_f32_e32 v252, v252
	v_exp_f32_e32 v253, v253
	v_perm_b32 v254, v225, v225, s42
	v_perm_b32 v255, v225, v225, s43
	v_add_f32_e32 v252, 1.0, v252
	v_add_f32_e32 v253, 1.0, v253
	v_rcp_f32_e32 v252, v252
	v_rcp_f32_e32 v253, v253
	s_nop 0
	v_pk_fma_f32 v[14:15], v[14:15], v[252:253], v[254:255]
	v_lshlrev_b32_e32 v252, 16, v222
	v_and_b32_e32 v253, 0xffff0000, v222
	v_mul_f32_e32 v252, s100, v252
	v_mul_f32_e32 v253, s100, v253
	v_exp_f32_e32 v252, v252
	v_exp_f32_e32 v253, v253
	v_perm_b32 v254, v226, v226, s42
	v_perm_b32 v255, v226, v226, s43
	v_add_f32_e32 v252, 1.0, v252
	v_add_f32_e32 v253, 1.0, v253
	v_rcp_f32_e32 v252, v252
	v_rcp_f32_e32 v253, v253
	s_nop 0
	v_pk_fma_f32 v[8:9], v[8:9], v[252:253], v[254:255]
	v_lshlrev_b32_e32 v252, 16, v223
	v_and_b32_e32 v253, 0xffff0000, v223
	v_mul_f32_e32 v252, s100, v252
	v_mul_f32_e32 v253, s100, v253
	v_exp_f32_e32 v252, v252
	v_exp_f32_e32 v253, v253
	v_perm_b32 v254, v227, v227, s42
	v_perm_b32 v255, v227, v227, s43
	v_add_f32_e32 v252, 1.0, v252
	v_add_f32_e32 v253, 1.0, v253
	v_rcp_f32_e32 v252, v252
	v_rcp_f32_e32 v253, v253
	s_nop 0
	v_pk_fma_f32 v[10:11], v[10:11], v[252:253], v[254:255]
	v_cvt_pk_bf16_f32 v12, v12, v13
	v_cvt_pk_bf16_f32 v13, v14, v15
	v_cvt_pk_bf16_f32 v14, v8, v9
	v_cvt_pk_bf16_f32 v15, v10, v11
	v_add_u32_e32 v252, 0xb0000, v161
	global_store_dwordx4 v252, v[12:15], s[16:17]
	s_waitcnt vmcnt(7)
	v_lshlrev_b32_e32 v252, 16, v228
	v_and_b32_e32 v253, 0xffff0000, v228
	v_mul_f32_e32 v252, s100, v252
	v_mul_f32_e32 v253, s100, v253
	v_exp_f32_e32 v252, v252
	v_exp_f32_e32 v253, v253
	v_perm_b32 v254, v232, v232, s42
	v_perm_b32 v255, v232, v232, s43
	v_add_f32_e32 v252, 1.0, v252
	v_add_f32_e32 v253, 1.0, v253
	v_rcp_f32_e32 v252, v252
	v_rcp_f32_e32 v253, v253
	s_nop 0
	v_pk_fma_f32 v[4:5], v[4:5], v[252:253], v[254:255]
	v_lshlrev_b32_e32 v252, 16, v229
	v_and_b32_e32 v253, 0xffff0000, v229
	v_mul_f32_e32 v252, s100, v252
	v_mul_f32_e32 v253, s100, v253
	v_exp_f32_e32 v252, v252
	v_exp_f32_e32 v253, v253
	v_perm_b32 v254, v233, v233, s42
	v_perm_b32 v255, v233, v233, s43
	v_add_f32_e32 v252, 1.0, v252
	v_add_f32_e32 v253, 1.0, v253
	v_rcp_f32_e32 v252, v252
	v_rcp_f32_e32 v253, v253
	s_nop 0
	v_pk_fma_f32 v[6:7], v[6:7], v[252:253], v[254:255]
	v_lshlrev_b32_e32 v252, 16, v230
	v_and_b32_e32 v253, 0xffff0000, v230
	v_mul_f32_e32 v252, s100, v252
	v_mul_f32_e32 v253, s100, v253
	v_exp_f32_e32 v252, v252
	v_exp_f32_e32 v253, v253
	v_perm_b32 v254, v234, v234, s42
	v_perm_b32 v255, v234, v234, s43
	v_add_f32_e32 v252, 1.0, v252
	v_add_f32_e32 v253, 1.0, v253
	v_rcp_f32_e32 v252, v252
	v_rcp_f32_e32 v253, v253
	s_nop 0
	v_pk_fma_f32 v[0:1], v[0:1], v[252:253], v[254:255]
	v_lshlrev_b32_e32 v252, 16, v231
	v_and_b32_e32 v253, 0xffff0000, v231
	v_mul_f32_e32 v252, s100, v252
	v_mul_f32_e32 v253, s100, v253
	v_exp_f32_e32 v252, v252
	v_exp_f32_e32 v253, v253
	v_perm_b32 v254, v235, v235, s42
	v_perm_b32 v255, v235, v235, s43
	v_add_f32_e32 v252, 1.0, v252
	v_add_f32_e32 v253, 1.0, v253
	v_rcp_f32_e32 v252, v252
	v_rcp_f32_e32 v253, v253
	s_nop 0
	v_pk_fma_f32 v[2:3], v[2:3], v[252:253], v[254:255]
	v_cvt_pk_bf16_f32 v4, v4, v5
	v_cvt_pk_bf16_f32 v5, v6, v7
	v_cvt_pk_bf16_f32 v6, v0, v1
	v_cvt_pk_bf16_f32 v7, v2, v3
	v_add_u32_e32 v252, 0xb0000, v161
	global_store_dwordx4 v252, v[4:7], s[16:17] offset:256
	s_cmp_gt_i32 s14, 0
	s_cselect_b64 s[42:43], 0, -1
	s_and_b64 vcc, exec, s[40:41]
	s_mov_b64 s[0:1], -1
	s_cbranch_vccnz .LBB0_1168
	s_andn2_b64 vcc, exec, s[4:5]
	s_cbranch_vccnz .LBB0_1167
	s_barrier
	s_branch .LBB0_1167

; __device__ __forceinline__ unsigned cvt_pk_bf16(float lo, float hi) { const f32x2_t v = {lo, hi}; const bf16x2_t b = __builtin_convertvector(v, bf16x2_t); return __builtin_bit_cast(unsigned, b); }
; __device__ __forceinline__ float bf_lo(unsigned w) { return __uint_as_float(w << 16); }
; __device__ __forceinline__ float bf_hi(unsigned w) { return __uint_as_float(w & 0xffff0000u); }
;     __device__ __forceinline__ void operator()(const f32x4 (&acc)[2][2][4][2], const Unit& u, int wr, int wc, int fr, int fq) const {
;     ...
;             for (int m = 0; m < 4; ++m) { const size_t row = (size_t)(row0 + ai * HALF + m * 16); bf16_t* rowp = U + (ACCUM ? (size_t)0 : (size_t)u.z * zsU) + row * ldc + col0; const bf16_t* gp = GT + row * ldg + (size_t)u.z * 2048 + col0;
; #pragma unroll
;                 for (int bj = 0; bj < 2; ++bj) { const u32x4 gw = *(const u32x4*)(gp + bj * HALF); u32x4 pw = (u32x4){0u, 0u, 0u, 0u}; if (ACCUM && u.z > 0) pw = *(const u32x4*)(rowp + bj * HALF);
;                     const f32x4 v0 = acc[ai][bj][m][0], v1 = acc[ai][bj][m][1]; const float a[8] = {v0[0], v0[1], v0[2], v0[3], v1[0], v1[1], v1[2], v1[3]};
;                     float o[8];
; #pragma unroll
;                     for (int j = 0; j < 4; ++j) { const unsigned g2 = gw[j], p2 = pw[j];
;                         const float s0 = __builtin_amdgcn_rcpf(1.f + __expf(-bf_lo(g2))), s1 = __builtin_amdgcn_rcpf(1.f + __expf(-bf_hi(g2)));
;                         o[2 * j] = bf_lo(p2) + s0 * a[2 * j]; o[2 * j + 1] = bf_hi(p2) + s1 * a[2 * j + 1]; }
;                     u32x4 w; w.x = cvt_pk_bf16(o[0], o[1]); w.y = cvt_pk_bf16(o[2], o[3]); w.z = cvt_pk_bf16(o[4], o[5]); w.w = cvt_pk_bf16(o[6], o[7]);
;                     *(u32x4*)(rowp + bj * HALF) = w; } }
.LBB0_1234:
	v_lshl_or_b32 v149, s15, 8, v152
	v_lshl_add_u32 v148, s30, 8, v150
	s_ashr_i32 s15, s14, 31
	s_lshl_b64 s[0:1], s[14:15], 22
	v_readlane_b32 s2, v247, 18
	v_readlane_b32 s3, v247, 19
	s_nop 0
	s_add_u32 s2, s2, s0
	s_addc_u32 s3, s3, s1
	v_readlane_b32 s0, v251, 46
	v_readlane_b32 s1, v251, 47
	s_lshl_b64 s[46:47], s[14:15], 12
	s_mov_b32 s100, 0xbfb8aa3b
	s_mov_b64 s[34:35], 0x45000
	v_lshlrev_b32_e32 v149, 1, v149
	v_lshl_add_u32 v252, v148, 12, v149
	v_mul_u32_u24_e32 v148, 0x8a00, v148
	v_add3_u32 v148, v148, v149, s46
	v_mov_b32_e32 v149, v252
	s_nop 3
	v_mov_b32_e32 v140, v148
	global_load_dwordx4 v[140:143], v140, s[0:1]
	v_mov_b32_e32 v144, v148
	global_load_dwordx4 v[144:147], v144, s[0:1] offset:256
	v_add_u32_e32 v154, 0x8a000, v148
	global_load_dwordx4 v[154:157], v154, s[0:1]
	v_add_u32_e32 v158, 0x8a000, v148
	global_load_dwordx4 v[158:161], v158, s[0:1] offset:256
	v_add_u32_e32 v178, 0x114000, v148
	global_load_dwordx4 v[178:181], v178, s[0:1]
	v_add_u32_e32 v182, 0x114000, v148
	global_load_dwordx4 v[182:185], v182, s[0:1] offset:256
	v_add_u32_e32 v186, 0x19e000, v148
	global_load_dwordx4 v[186:189], v186, s[0:1]
	v_add_u32_e32 v190, 0x19e000, v148
	global_load_dwordx4 v[190:193], v190, s[0:1] offset:256
	v_add_u32_e32 v194, 0x450000, v148
	global_load_dwordx4 v[194:197], v194, s[0:1]
	v_add_u32_e32 v208, 0x450000, v148
	global_load_dwordx4 v[208:211], v208, s[0:1] offset:256
	v_add_u32_e32 v212, 0x4da000, v148
	global_load_dwordx4 v[212:215], v212, s[0:1]
	v_add_u32_e32 v216, 0x4da000, v148
	global_load_dwordx4 v[216:219], v216, s[0:1] offset:256
	v_add_u32_e32 v220, 0x564000, v148
	global_load_dwordx4 v[220:223], v220, s[0:1]
	v_add_u32_e32 v224, 0x564000, v148
	global_load_dwordx4 v[224:227], v224, s[0:1] offset:256
	v_add_u32_e32 v228, 0x5ee000, v148
	global_load_dwordx4 v[228:231], v228, s[0:1]
	v_add_u32_e32 v232, 0x5ee000, v148
	global_load_dwordx4 v[232:235], v232, s[0:1] offset:256
	s_waitcnt vmcnt(15)
	v_lshlrev_b32_e32 v252, 16, v140
	v_and_b32_e32 v253, 0xffff0000, v140
	v_mul_f32_e32 v252, s100, v252
	v_mul_f32_e32 v253, s100, v253
	v_exp_f32_e32 v252, v252
	v_exp_f32_e32 v253, v253
	v_add_f32_e32 v252, 1.0, v252
	v_add_f32_e32 v253, 1.0, v253
	v_rcp_f32_e32 v252, v252
	v_rcp_f32_e32 v253, v253
	s_nop 0
	v_pk_fma_f32 v[126:127], v[126:127], v[252:253], 0 op_sel_hi:[1,1,0]
	v_lshlrev_b32_e32 v252, 16, v141
	v_and_b32_e32 v253, 0xffff0000, v141
	v_mul_f32_e32 v252, s100, v252
	v_mul_f32_e32 v253, s100, v253
	v_exp_f32_e32 v252, v252
	v_exp_f32_e32 v253, v253
	v_add_f32_e32 v252, 1.0, v252
	v_add_f32_e32 v253, 1.0, v253
	v_rcp_f32_e32 v252, v252
	v_rcp_f32_e32 v253, v253
	s_nop 0
	v_pk_fma_f32 v[128:129], v[128:129], v[252:253], 0 op_sel_hi:[1,1,0]
	v_lshlrev_b32_e32 v252, 16, v142
	v_and_b32_e32 v253, 0xffff0000, v142
	v_mul_f32_e32 v252, s100, v252
	v_mul_f32_e32 v253, s100, v253
	v_exp_f32_e32 v252, v252
	v_exp_f32_e32 v253, v253
	v_add_f32_e32 v252, 1.0, v252
	v_add_f32_e32 v253, 1.0, v253
	v_rcp_f32_e32 v252, v252
	v_rcp_f32_e32 v253, v253
	s_nop 0
	v_pk_fma_f32 v[122:123], v[122:123], v[252:253], 0 op_sel_hi:[1,1,0]
	v_lshlrev_b32_e32 v252, 16, v143
	v_and_b32_e32 v253, 0xffff0000, v143
	v_mul_f32_e32 v252, s100, v252
	v_mul_f32_e32 v253, s100, v253
	v_exp_f32_e32 v252, v252
	v_exp_f32_e32 v253, v253
	v_add_f32_e32 v252, 1.0, v252
	v_add_f32_e32 v253, 1.0, v253
	v_rcp_f32_e32 v252, v252
	v_rcp_f32_e32 v253, v253
	s_nop 0
	v_pk_fma_f32 v[124:125], v[124:125], v[252:253], 0 op_sel_hi:[1,1,0]
	v_cvt_pk_bf16_f32 v126, v126, v127
	v_cvt_pk_bf16_f32 v127, v128, v129
	v_cvt_pk_bf16_f32 v128, v122, v123
	v_cvt_pk_bf16_f32 v129, v124, v125
	v_mov_b32_e32 v252, v149
	global_store_dwordx4 v252, v[126:129], s[2:3]
	s_waitcnt vmcnt(15)
	v_lshlrev_b32_e32 v252, 16, v144
	v_and_b32_e32 v253, 0xffff0000, v144
	v_mul_f32_e32 v252, s100, v252
	v_mul_f32_e32 v253, s100, v253
	v_exp_f32_e32 v252, v252
	v_exp_f32_e32 v253, v253
	v_add_f32_e32 v252, 1.0, v252
	v_add_f32_e32 v253, 1.0, v253
	v_rcp_f32_e32 v252, v252
	v_rcp_f32_e32 v253, v253
	s_nop 0
	v_pk_fma_f32 v[118:119], v[118:119], v[252:253], 0 op_sel_hi:[1,1,0]
	v_lshlrev_b32_e32 v252, 16, v145
	v_and_b32_e32 v253, 0xffff0000, v145
	v_mul_f32_e32 v252, s100, v252
	v_mul_f32_e32 v253, s100, v253
	v_exp_f32_e32 v252, v252
	v_exp_f32_e32 v253, v253
	v_add_f32_e32 v252, 1.0, v252
	v_add_f32_e32 v253, 1.0, v253
	v_rcp_f32_e32 v252, v252
	v_rcp_f32_e32 v253, v253
	s_nop 0
	v_pk_fma_f32 v[120:121], v[120:121], v[252:253], 0 op_sel_hi:[1,1,0]
	v_lshlrev_b32_e32 v252, 16, v146
	v_and_b32_e32 v253, 0xffff0000, v146
	v_mul_f32_e32 v252, s100, v252
	v_mul_f32_e32 v253, s100, v253
	v_exp_f32_e32 v252, v252
	v_exp_f32_e32 v253, v253
	v_add_f32_e32 v252, 1.0, v252
	v_add_f32_e32 v253, 1.0, v253
	v_rcp_f32_e32 v252, v252
	v_rcp_f32_e32 v253, v253
	s_nop 0
	v_pk_fma_f32 v[114:115], v[114:115], v[252:253], 0 op_sel_hi:[1,1,0]
	v_lshlrev_b32_e32 v252, 16, v147
	v_and_b32_e32 v253, 0xffff0000, v147
	v_mul_f32_e32 v252, s100, v252
	v_mul_f32_e32 v253, s100, v253
	v_exp_f32_e32 v252, v252
	v_exp_f32_e32 v253, v253
	v_add_f32_e32 v252, 1.0, v252
	v_add_f32_e32 v253, 1.0, v253
	v_rcp_f32_e32 v252, v252
	v_rcp_f32_e32 v253, v253
	s_nop 0
	v_pk_fma_f32 v[116:117], v[116:117], v[252:253], 0 op_sel_hi:[1,1,0]
	v_cvt_pk_bf16_f32 v118, v118, v119
	v_cvt_pk_bf16_f32 v119, v120, v121
	v_cvt_pk_bf16_f32 v120, v114, v115
	v_cvt_pk_bf16_f32 v121, v116, v117
	v_mov_b32_e32 v252, v149
	global_store_dwordx4 v252, v[118:121], s[2:3] offset:256
	s_waitcnt vmcnt(15)
; __device__ __forceinline__ unsigned cvt_pk_bf16(float lo, float hi) { const f32x2_t v = {lo, hi}; const bf16x2_t b = __builtin_convertvector(v, bf16x2_t); return __builtin_bit_cast(unsigned, b); }
; __device__ __forceinline__ float bf_lo(unsigned w) { return __uint_as_float(w << 16); }
; __device__ __forceinline__ float bf_hi(unsigned w) { return __uint_as_float(w & 0xffff0000u); }
;     __device__ __forceinline__ void operator()(const f32x4 (&acc)[2][2][4][2], const Unit& u, int wr, int wc, int fr, int fq) const {
;     ...
;             for (int m = 0; m < 4; ++m) { const size_t row = (size_t)(row0 + ai * HALF + m * 16); bf16_t* rowp = U + (ACCUM ? (size_t)0 : (size_t)u.z * zsU) + row * ldc + col0; const bf16_t* gp = GT + row * ldg + (size_t)u.z * 2048 + col0;
; #pragma unroll
;                 for (int bj = 0; bj < 2; ++bj) { const u32x4 gw = *(const u32x4*)(gp + bj * HALF); u32x4 pw = (u32x4){0u, 0u, 0u, 0u}; if (ACCUM && u.z > 0) pw = *(const u32x4*)(rowp + bj * HALF);
;                     const f32x4 v0 = acc[ai][bj][m][0], v1 = acc[ai][bj][m][1]; const float a[8] = {v0[0], v0[1], v0[2], v0[3], v1[0], v1[1], v1[2], v1[3]};
;                     float o[8];
; #pragma unroll
;                     for (int j = 0; j < 4; ++j) { const unsigned g2 = gw[j], p2 = pw[j];
;                         const float s0 = __builtin_amdgcn_rcpf(1.f + __expf(-bf_lo(g2))), s1 = __builtin_amdgcn_rcpf(1.f + __expf(-bf_hi(g2)));
;                         o[2 * j] = bf_lo(p2) + s0 * a[2 * j]; o[2 * j + 1] = bf_hi(p2) + s1 * a[2 * j + 1]; }
;                     u32x4 w; w.x = cvt_pk_bf16(o[0], o[1]); w.y = cvt_pk_bf16(o[2], o[3]); w.z = cvt_pk_bf16(o[4], o[5]); w.w = cvt_pk_bf16(o[6], o[7]);
;                     *(u32x4*)(rowp + bj * HALF) = w; } }
	v_lshlrev_b32_e32 v252, 16, v154
	v_and_b32_e32 v253, 0xffff0000, v154
	v_mul_f32_e32 v252, s100, v252
	v_mul_f32_e32 v253, s100, v253
	v_exp_f32_e32 v252, v252
	v_exp_f32_e32 v253, v253
	v_add_f32_e32 v252, 1.0, v252
	v_add_f32_e32 v253, 1.0, v253
	v_rcp_f32_e32 v252, v252
	v_rcp_f32_e32 v253, v253
	s_nop 0
	v_pk_fma_f32 v[110:111], v[110:111], v[252:253], 0 op_sel_hi:[1,1,0]
	v_lshlrev_b32_e32 v252, 16, v155
	v_and_b32_e32 v253, 0xffff0000, v155
	v_mul_f32_e32 v252, s100, v252
	v_mul_f32_e32 v253, s100, v253
	v_exp_f32_e32 v252, v252
	v_exp_f32_e32 v253, v253
	v_add_f32_e32 v252, 1.0, v252
	v_add_f32_e32 v253, 1.0, v253
	v_rcp_f32_e32 v252, v252
	v_rcp_f32_e32 v253, v253
	s_nop 0
	v_pk_fma_f32 v[112:113], v[112:113], v[252:253], 0 op_sel_hi:[1,1,0]
	v_lshlrev_b32_e32 v252, 16, v156
	v_and_b32_e32 v253, 0xffff0000, v156
	v_mul_f32_e32 v252, s100, v252
	v_mul_f32_e32 v253, s100, v253
	v_exp_f32_e32 v252, v252
	v_exp_f32_e32 v253, v253
	v_add_f32_e32 v252, 1.0, v252
	v_add_f32_e32 v253, 1.0, v253
	v_rcp_f32_e32 v252, v252
	v_rcp_f32_e32 v253, v253
	s_nop 0
	v_pk_fma_f32 v[106:107], v[106:107], v[252:253], 0 op_sel_hi:[1,1,0]
	v_lshlrev_b32_e32 v252, 16, v157
	v_and_b32_e32 v253, 0xffff0000, v157
	v_mul_f32_e32 v252, s100, v252
	v_mul_f32_e32 v253, s100, v253
	v_exp_f32_e32 v252, v252
	v_exp_f32_e32 v253, v253
	v_add_f32_e32 v252, 1.0, v252
	v_add_f32_e32 v253, 1.0, v253
	v_rcp_f32_e32 v252, v252
	v_rcp_f32_e32 v253, v253
	s_nop 0
	v_pk_fma_f32 v[108:109], v[108:109], v[252:253], 0 op_sel_hi:[1,1,0]
	v_cvt_pk_bf16_f32 v110, v110, v111
	v_cvt_pk_bf16_f32 v111, v112, v113
	v_cvt_pk_bf16_f32 v112, v106, v107
	v_cvt_pk_bf16_f32 v113, v108, v109
	v_add_u32_e32 v252, 0x10000, v149
	global_store_dwordx4 v252, v[110:113], s[2:3]
	s_waitcnt vmcnt(15)
	v_lshlrev_b32_e32 v252, 16, v158
	v_and_b32_e32 v253, 0xffff0000, v158
	v_mul_f32_e32 v252, s100, v252
	v_mul_f32_e32 v253, s100, v253
	v_exp_f32_e32 v252, v252
	v_exp_f32_e32 v253, v253
	v_add_f32_e32 v252, 1.0, v252
	v_add_f32_e32 v253, 1.0, v253
	v_rcp_f32_e32 v252, v252
	v_rcp_f32_e32 v253, v253
	s_nop 0
	v_pk_fma_f32 v[102:103], v[102:103], v[252:253], 0 op_sel_hi:[1,1,0]
	v_lshlrev_b32_e32 v252, 16, v159
	v_and_b32_e32 v253, 0xffff0000, v159
	v_mul_f32_e32 v252, s100, v252
	v_mul_f32_e32 v253, s100, v253
	v_exp_f32_e32 v252, v252
	v_exp_f32_e32 v253, v253
	v_add_f32_e32 v252, 1.0, v252
	v_add_f32_e32 v253, 1.0, v253
	v_rcp_f32_e32 v252, v252
	v_rcp_f32_e32 v253, v253
	s_nop 0
	v_pk_fma_f32 v[104:105], v[104:105], v[252:253], 0 op_sel_hi:[1,1,0]
	v_lshlrev_b32_e32 v252, 16, v160
	v_and_b32_e32 v253, 0xffff0000, v160
	v_mul_f32_e32 v252, s100, v252
	v_mul_f32_e32 v253, s100, v253
	v_exp_f32_e32 v252, v252
	v_exp_f32_e32 v253, v253
	v_add_f32_e32 v252, 1.0, v252
	v_add_f32_e32 v253, 1.0, v253
	v_rcp_f32_e32 v252, v252
	v_rcp_f32_e32 v253, v253
	s_nop 0
	v_pk_fma_f32 v[98:99], v[98:99], v[252:253], 0 op_sel_hi:[1,1,0]
	v_lshlrev_b32_e32 v252, 16, v161
	v_and_b32_e32 v253, 0xffff0000, v161
	v_mul_f32_e32 v252, s100, v252
	v_mul_f32_e32 v253, s100, v253
	v_exp_f32_e32 v252, v252
	v_exp_f32_e32 v253, v253
	v_add_f32_e32 v252, 1.0, v252
	v_add_f32_e32 v253, 1.0, v253
	v_rcp_f32_e32 v252, v252
	v_rcp_f32_e32 v253, v253
	s_nop 0
	v_pk_fma_f32 v[100:101], v[100:101], v[252:253], 0 op_sel_hi:[1,1,0]
	v_cvt_pk_bf16_f32 v102, v102, v103
	v_cvt_pk_bf16_f32 v103, v104, v105
	v_cvt_pk_bf16_f32 v104, v98, v99
	v_cvt_pk_bf16_f32 v105, v100, v101
	v_add_u32_e32 v252, 0x10000, v149
	global_store_dwordx4 v252, v[102:105], s[2:3] offset:256
	s_waitcnt vmcnt(15)
	v_lshlrev_b32_e32 v252, 16, v178
	v_and_b32_e32 v253, 0xffff0000, v178
	v_mul_f32_e32 v252, s100, v252
	v_mul_f32_e32 v253, s100, v253
	v_exp_f32_e32 v252, v252
	v_exp_f32_e32 v253, v253
	v_add_f32_e32 v252, 1.0, v252
	v_add_f32_e32 v253, 1.0, v253
	v_rcp_f32_e32 v252, v252
	v_rcp_f32_e32 v253, v253
	s_nop 0
	v_pk_fma_f32 v[94:95], v[94:95], v[252:253], 0 op_sel_hi:[1,1,0]
	v_lshlrev_b32_e32 v252, 16, v179
	v_and_b32_e32 v253, 0xffff0000, v179
	v_mul_f32_e32 v252, s100, v252
	v_mul_f32_e32 v253, s100, v253
	v_exp_f32_e32 v252, v252
	v_exp_f32_e32 v253, v253
	v_add_f32_e32 v252, 1.0, v252
	v_add_f32_e32 v253, 1.0, v253
	v_rcp_f32_e32 v252, v252
	v_rcp_f32_e32 v253, v253
	s_nop 0
	v_pk_fma_f32 v[96:97], v[96:97], v[252:253], 0 op_sel_hi:[1,1,0]
	v_lshlrev_b32_e32 v252, 16, v180
	v_and_b32_e32 v253, 0xffff0000, v180
	v_mul_f32_e32 v252, s100, v252
	v_mul_f32_e32 v253, s100, v253
	v_exp_f32_e32 v252, v252
	v_exp_f32_e32 v253, v253
	v_add_f32_e32 v252, 1.0, v252
	v_add_f32_e32 v253, 1.0, v253
	v_rcp_f32_e32 v252, v252
	v_rcp_f32_e32 v253, v253
	s_nop 0
	v_pk_fma_f32 v[90:91], v[90:91], v[252:253], 0 op_sel_hi:[1,1,0]
	v_lshlrev_b32_e32 v252, 16, v181
	v_and_b32_e32 v253, 0xffff0000, v181
	v_mul_f32_e32 v252, s100, v252
	v_mul_f32_e32 v253, s100, v253
	v_exp_f32_e32 v252, v252
	v_exp_f32_e32 v253, v253
	v_add_f32_e32 v252, 1.0, v252
	v_add_f32_e32 v253, 1.0, v253
	v_rcp_f32_e32 v252, v252
	v_rcp_f32_e32 v253, v253
	s_nop 0
	v_pk_fma_f32 v[92:93], v[92:93], v[252:253], 0 op_sel_hi:[1,1,0]
	v_cvt_pk_bf16_f32 v94, v94, v95
	v_cvt_pk_bf16_f32 v95, v96, v97
	v_cvt_pk_bf16_f32 v96, v90, v91
	v_cvt_pk_bf16_f32 v97, v92, v93
	v_add_u32_e32 v252, 0x20000, v149
	global_store_dwordx4 v252, v[94:97], s[2:3]
	s_waitcnt vmcnt(15)
; __device__ __forceinline__ unsigned cvt_pk_bf16(float lo, float hi) { const f32x2_t v = {lo, hi}; const bf16x2_t b = __builtin_convertvector(v, bf16x2_t); return __builtin_bit_cast(unsigned, b); }
; __device__ __forceinline__ float bf_lo(unsigned w) { return __uint_as_float(w << 16); }
; __device__ __forceinline__ float bf_hi(unsigned w) { return __uint_as_float(w & 0xffff0000u); }
;     __device__ __forceinline__ void operator()(const f32x4 (&acc)[2][2][4][2], const Unit& u, int wr, int wc, int fr, int fq) const {
;     ...
;             for (int m = 0; m < 4; ++m) { const size_t row = (size_t)(row0 + ai * HALF + m * 16); bf16_t* rowp = U + (ACCUM ? (size_t)0 : (size_t)u.z * zsU) + row * ldc + col0; const bf16_t* gp = GT + row * ldg + (size_t)u.z * 2048 + col0;
; #pragma unroll
;                 for (int bj = 0; bj < 2; ++bj) { const u32x4 gw = *(const u32x4*)(gp + bj * HALF); u32x4 pw = (u32x4){0u, 0u, 0u, 0u}; if (ACCUM && u.z > 0) pw = *(const u32x4*)(rowp + bj * HALF);
;                     const f32x4 v0 = acc[ai][bj][m][0], v1 = acc[ai][bj][m][1]; const float a[8] = {v0[0], v0[1], v0[2], v0[3], v1[0], v1[1], v1[2], v1[3]};
;                     float o[8];
; #pragma unroll
;                     for (int j = 0; j < 4; ++j) { const unsigned g2 = gw[j], p2 = pw[j];
;                         const float s0 = __builtin_amdgcn_rcpf(1.f + __expf(-bf_lo(g2))), s1 = __builtin_amdgcn_rcpf(1.f + __expf(-bf_hi(g2)));
;                         o[2 * j] = bf_lo(p2) + s0 * a[2 * j]; o[2 * j + 1] = bf_hi(p2) + s1 * a[2 * j + 1]; }
;                     u32x4 w; w.x = cvt_pk_bf16(o[0], o[1]); w.y = cvt_pk_bf16(o[2], o[3]); w.z = cvt_pk_bf16(o[4], o[5]); w.w = cvt_pk_bf16(o[6], o[7]);
;                     *(u32x4*)(rowp + bj * HALF) = w; } }
	v_lshlrev_b32_e32 v252, 16, v182
	v_and_b32_e32 v253, 0xffff0000, v182
	v_mul_f32_e32 v252, s100, v252
	v_mul_f32_e32 v253, s100, v253
	v_exp_f32_e32 v252, v252
	v_exp_f32_e32 v253, v253
	v_add_f32_e32 v252, 1.0, v252
	v_add_f32_e32 v253, 1.0, v253
	v_rcp_f32_e32 v252, v252
	v_rcp_f32_e32 v253, v253
	s_nop 0
	v_pk_fma_f32 v[86:87], v[86:87], v[252:253], 0 op_sel_hi:[1,1,0]
	v_lshlrev_b32_e32 v252, 16, v183
	v_and_b32_e32 v253, 0xffff0000, v183
	v_mul_f32_e32 v252, s100, v252
	v_mul_f32_e32 v253, s100, v253
	v_exp_f32_e32 v252, v252
	v_exp_f32_e32 v253, v253
	v_add_f32_e32 v252, 1.0, v252
	v_add_f32_e32 v253, 1.0, v253
	v_rcp_f32_e32 v252, v252
	v_rcp_f32_e32 v253, v253
	s_nop 0
	v_pk_fma_f32 v[88:89], v[88:89], v[252:253], 0 op_sel_hi:[1,1,0]
	v_lshlrev_b32_e32 v252, 16, v184
	v_and_b32_e32 v253, 0xffff0000, v184
	v_mul_f32_e32 v252, s100, v252
	v_mul_f32_e32 v253, s100, v253
	v_exp_f32_e32 v252, v252
	v_exp_f32_e32 v253, v253
	v_add_f32_e32 v252, 1.0, v252
	v_add_f32_e32 v253, 1.0, v253
	v_rcp_f32_e32 v252, v252
	v_rcp_f32_e32 v253, v253
	s_nop 0
	v_pk_fma_f32 v[82:83], v[82:83], v[252:253], 0 op_sel_hi:[1,1,0]
	v_lshlrev_b32_e32 v252, 16, v185
	v_and_b32_e32 v253, 0xffff0000, v185
	v_mul_f32_e32 v252, s100, v252
	v_mul_f32_e32 v253, s100, v253
	v_exp_f32_e32 v252, v252
	v_exp_f32_e32 v253, v253
	v_add_f32_e32 v252, 1.0, v252
	v_add_f32_e32 v253, 1.0, v253
	v_rcp_f32_e32 v252, v252
	v_rcp_f32_e32 v253, v253
	s_nop 0
	v_pk_fma_f32 v[84:85], v[84:85], v[252:253], 0 op_sel_hi:[1,1,0]
	v_cvt_pk_bf16_f32 v86, v86, v87
	v_cvt_pk_bf16_f32 v87, v88, v89
	v_cvt_pk_bf16_f32 v88, v82, v83
	v_cvt_pk_bf16_f32 v89, v84, v85
	v_add_u32_e32 v252, 0x20000, v149
	global_store_dwordx4 v252, v[86:89], s[2:3] offset:256
	s_waitcnt vmcnt(15)
	v_lshlrev_b32_e32 v252, 16, v186
	v_and_b32_e32 v253, 0xffff0000, v186
	v_mul_f32_e32 v252, s100, v252
	v_mul_f32_e32 v253, s100, v253
	v_exp_f32_e32 v252, v252
	v_exp_f32_e32 v253, v253
	v_add_f32_e32 v252, 1.0, v252
	v_add_f32_e32 v253, 1.0, v253
	v_rcp_f32_e32 v252, v252
	v_rcp_f32_e32 v253, v253
	s_nop 0
	v_pk_fma_f32 v[78:79], v[78:79], v[252:253], 0 op_sel_hi:[1,1,0]
	v_lshlrev_b32_e32 v252, 16, v187
	v_and_b32_e32 v253, 0xffff0000, v187
	v_mul_f32_e32 v252, s100, v252
	v_mul_f32_e32 v253, s100, v253
	v_exp_f32_e32 v252, v252
	v_exp_f32_e32 v253, v253
	v_add_f32_e32 v252, 1.0, v252
	v_add_f32_e32 v253, 1.0, v253
	v_rcp_f32_e32 v252, v252
	v_rcp_f32_e32 v253, v253
	s_nop 0
	v_pk_fma_f32 v[80:81], v[80:81], v[252:253], 0 op_sel_hi:[1,1,0]
	v_lshlrev_b32_e32 v252, 16, v188
	v_and_b32_e32 v253, 0xffff0000, v188
	v_mul_f32_e32 v252, s100, v252
	v_mul_f32_e32 v253, s100, v253
	v_exp_f32_e32 v252, v252
	v_exp_f32_e32 v253, v253
	v_add_f32_e32 v252, 1.0, v252
	v_add_f32_e32 v253, 1.0, v253
	v_rcp_f32_e32 v252, v252
	v_rcp_f32_e32 v253, v253
	s_nop 0
	v_pk_fma_f32 v[74:75], v[74:75], v[252:253], 0 op_sel_hi:[1,1,0]
	v_lshlrev_b32_e32 v252, 16, v189
	v_and_b32_e32 v253, 0xffff0000, v189
	v_mul_f32_e32 v252, s100, v252
	v_mul_f32_e32 v253, s100, v253
	v_exp_f32_e32 v252, v252
	v_exp_f32_e32 v253, v253
	v_add_f32_e32 v252, 1.0, v252
	v_add_f32_e32 v253, 1.0, v253
	v_rcp_f32_e32 v252, v252
	v_rcp_f32_e32 v253, v253
	s_nop 0
	v_pk_fma_f32 v[76:77], v[76:77], v[252:253], 0 op_sel_hi:[1,1,0]
	v_cvt_pk_bf16_f32 v78, v78, v79
	v_cvt_pk_bf16_f32 v79, v80, v81
	v_cvt_pk_bf16_f32 v80, v74, v75
	v_cvt_pk_bf16_f32 v81, v76, v77
	v_add_u32_e32 v252, 0x30000, v149
	global_store_dwordx4 v252, v[78:81], s[2:3]
	s_waitcnt vmcnt(15)
	v_lshlrev_b32_e32 v252, 16, v190
	v_and_b32_e32 v253, 0xffff0000, v190
	v_mul_f32_e32 v252, s100, v252
	v_mul_f32_e32 v253, s100, v253
	v_exp_f32_e32 v252, v252
	v_exp_f32_e32 v253, v253
	v_add_f32_e32 v252, 1.0, v252
	v_add_f32_e32 v253, 1.0, v253
	v_rcp_f32_e32 v252, v252
	v_rcp_f32_e32 v253, v253
	s_nop 0
	v_pk_fma_f32 v[70:71], v[70:71], v[252:253], 0 op_sel_hi:[1,1,0]
	v_lshlrev_b32_e32 v252, 16, v191
	v_and_b32_e32 v253, 0xffff0000, v191
	v_mul_f32_e32 v252, s100, v252
	v_mul_f32_e32 v253, s100, v253
	v_exp_f32_e32 v252, v252
	v_exp_f32_e32 v253, v253
	v_add_f32_e32 v252, 1.0, v252
	v_add_f32_e32 v253, 1.0, v253
	v_rcp_f32_e32 v252, v252
	v_rcp_f32_e32 v253, v253
	s_nop 0
	v_pk_fma_f32 v[72:73], v[72:73], v[252:253], 0 op_sel_hi:[1,1,0]
	v_lshlrev_b32_e32 v252, 16, v192
	v_and_b32_e32 v253, 0xffff0000, v192
	v_mul_f32_e32 v252, s100, v252
	v_mul_f32_e32 v253, s100, v253
	v_exp_f32_e32 v252, v252
	v_exp_f32_e32 v253, v253
	v_add_f32_e32 v252, 1.0, v252
	v_add_f32_e32 v253, 1.0, v253
	v_rcp_f32_e32 v252, v252
	v_rcp_f32_e32 v253, v253
	s_nop 0
	v_pk_fma_f32 v[66:67], v[66:67], v[252:253], 0 op_sel_hi:[1,1,0]
	v_lshlrev_b32_e32 v252, 16, v193
	v_and_b32_e32 v253, 0xffff0000, v193
	v_mul_f32_e32 v252, s100, v252
	v_mul_f32_e32 v253, s100, v253
	v_exp_f32_e32 v252, v252
	v_exp_f32_e32 v253, v253
	v_add_f32_e32 v252, 1.0, v252
	v_add_f32_e32 v253, 1.0, v253
	v_rcp_f32_e32 v252, v252
	v_rcp_f32_e32 v253, v253
	s_nop 0
	v_pk_fma_f32 v[68:69], v[68:69], v[252:253], 0 op_sel_hi:[1,1,0]
	v_cvt_pk_bf16_f32 v70, v70, v71
	v_cvt_pk_bf16_f32 v71, v72, v73
	v_cvt_pk_bf16_f32 v72, v66, v67
	v_cvt_pk_bf16_f32 v73, v68, v69
	v_add_u32_e32 v252, 0x30000, v149
	global_store_dwordx4 v252, v[70:73], s[2:3] offset:256
	s_waitcnt vmcnt(15)
; __device__ __forceinline__ unsigned cvt_pk_bf16(float lo, float hi) { const f32x2_t v = {lo, hi}; const bf16x2_t b = __builtin_convertvector(v, bf16x2_t); return __builtin_bit_cast(unsigned, b); }
; __device__ __forceinline__ float bf_lo(unsigned w) { return __uint_as_float(w << 16); }
; __device__ __forceinline__ float bf_hi(unsigned w) { return __uint_as_float(w & 0xffff0000u); }
;     __device__ __forceinline__ void operator()(const f32x4 (&acc)[2][2][4][2], const Unit& u, int wr, int wc, int fr, int fq) const {
;     ...
;             for (int m = 0; m < 4; ++m) { const size_t row = (size_t)(row0 + ai * HALF + m * 16); bf16_t* rowp = U + (ACCUM ? (size_t)0 : (size_t)u.z * zsU) + row * ldc + col0; const bf16_t* gp = GT + row * ldg + (size_t)u.z * 2048 + col0;
; #pragma unroll
;                 for (int bj = 0; bj < 2; ++bj) { const u32x4 gw = *(const u32x4*)(gp + bj * HALF); u32x4 pw = (u32x4){0u, 0u, 0u, 0u}; if (ACCUM && u.z > 0) pw = *(const u32x4*)(rowp + bj * HALF);
;                     const f32x4 v0 = acc[ai][bj][m][0], v1 = acc[ai][bj][m][1]; const float a[8] = {v0[0], v0[1], v0[2], v0[3], v1[0], v1[1], v1[2], v1[3]};
;                     float o[8];
; #pragma unroll
;                     for (int j = 0; j < 4; ++j) { const unsigned g2 = gw[j], p2 = pw[j];
;                         const float s0 = __builtin_amdgcn_rcpf(1.f + __expf(-bf_lo(g2))), s1 = __builtin_amdgcn_rcpf(1.f + __expf(-bf_hi(g2)));
;                         o[2 * j] = bf_lo(p2) + s0 * a[2 * j]; o[2 * j + 1] = bf_hi(p2) + s1 * a[2 * j + 1]; }
;                     u32x4 w; w.x = cvt_pk_bf16(o[0], o[1]); w.y = cvt_pk_bf16(o[2], o[3]); w.z = cvt_pk_bf16(o[4], o[5]); w.w = cvt_pk_bf16(o[6], o[7]);
;                     *(u32x4*)(rowp + bj * HALF) = w; } }
	v_lshlrev_b32_e32 v252, 16, v194
	v_and_b32_e32 v253, 0xffff0000, v194
	v_mul_f32_e32 v252, s100, v252
	v_mul_f32_e32 v253, s100, v253
	v_exp_f32_e32 v252, v252
	v_exp_f32_e32 v253, v253
	v_add_f32_e32 v252, 1.0, v252
	v_add_f32_e32 v253, 1.0, v253
	v_rcp_f32_e32 v252, v252
	v_rcp_f32_e32 v253, v253
	s_nop 0
	v_pk_fma_f32 v[60:61], v[60:61], v[252:253], 0 op_sel_hi:[1,1,0]
	v_lshlrev_b32_e32 v252, 16, v195
	v_and_b32_e32 v253, 0xffff0000, v195
	v_mul_f32_e32 v252, s100, v252
	v_mul_f32_e32 v253, s100, v253
	v_exp_f32_e32 v252, v252
	v_exp_f32_e32 v253, v253
	v_add_f32_e32 v252, 1.0, v252
	v_add_f32_e32 v253, 1.0, v253
	v_rcp_f32_e32 v252, v252
	v_rcp_f32_e32 v253, v253
	s_nop 0
	v_pk_fma_f32 v[62:63], v[62:63], v[252:253], 0 op_sel_hi:[1,1,0]
	v_lshlrev_b32_e32 v252, 16, v196
	v_and_b32_e32 v253, 0xffff0000, v196
	v_mul_f32_e32 v252, s100, v252
	v_mul_f32_e32 v253, s100, v253
	v_exp_f32_e32 v252, v252
	v_exp_f32_e32 v253, v253
	v_add_f32_e32 v252, 1.0, v252
	v_add_f32_e32 v253, 1.0, v253
	v_rcp_f32_e32 v252, v252
	v_rcp_f32_e32 v253, v253
	s_nop 0
	v_pk_fma_f32 v[56:57], v[56:57], v[252:253], 0 op_sel_hi:[1,1,0]
	v_lshlrev_b32_e32 v252, 16, v197
	v_and_b32_e32 v253, 0xffff0000, v197
	v_mul_f32_e32 v252, s100, v252
	v_mul_f32_e32 v253, s100, v253
	v_exp_f32_e32 v252, v252
	v_exp_f32_e32 v253, v253
	v_add_f32_e32 v252, 1.0, v252
	v_add_f32_e32 v253, 1.0, v253
	v_rcp_f32_e32 v252, v252
	v_rcp_f32_e32 v253, v253
	s_nop 0
	v_pk_fma_f32 v[58:59], v[58:59], v[252:253], 0 op_sel_hi:[1,1,0]
	v_cvt_pk_bf16_f32 v60, v60, v61
	v_cvt_pk_bf16_f32 v61, v62, v63
	v_cvt_pk_bf16_f32 v62, v56, v57
	v_cvt_pk_bf16_f32 v63, v58, v59
	v_add_u32_e32 v252, 0x80000, v149
	global_store_dwordx4 v252, v[60:63], s[2:3]
	s_waitcnt vmcnt(15)
	v_lshlrev_b32_e32 v252, 16, v208
	v_and_b32_e32 v253, 0xffff0000, v208
	v_mul_f32_e32 v252, s100, v252
	v_mul_f32_e32 v253, s100, v253
	v_exp_f32_e32 v252, v252
	v_exp_f32_e32 v253, v253
	v_add_f32_e32 v252, 1.0, v252
	v_add_f32_e32 v253, 1.0, v253
	v_rcp_f32_e32 v252, v252
	v_rcp_f32_e32 v253, v253
	s_nop 0
	v_pk_fma_f32 v[52:53], v[52:53], v[252:253], 0 op_sel_hi:[1,1,0]
	v_lshlrev_b32_e32 v252, 16, v209
	v_and_b32_e32 v253, 0xffff0000, v209
	v_mul_f32_e32 v252, s100, v252
	v_mul_f32_e32 v253, s100, v253
	v_exp_f32_e32 v252, v252
	v_exp_f32_e32 v253, v253
	v_add_f32_e32 v252, 1.0, v252
	v_add_f32_e32 v253, 1.0, v253
	v_rcp_f32_e32 v252, v252
	v_rcp_f32_e32 v253, v253
	s_nop 0
	v_pk_fma_f32 v[54:55], v[54:55], v[252:253], 0 op_sel_hi:[1,1,0]
	v_lshlrev_b32_e32 v252, 16, v210
	v_and_b32_e32 v253, 0xffff0000, v210
	v_mul_f32_e32 v252, s100, v252
	v_mul_f32_e32 v253, s100, v253
	v_exp_f32_e32 v252, v252
	v_exp_f32_e32 v253, v253
	v_add_f32_e32 v252, 1.0, v252
	v_add_f32_e32 v253, 1.0, v253
	v_rcp_f32_e32 v252, v252
	v_rcp_f32_e32 v253, v253
	s_nop 0
	v_pk_fma_f32 v[48:49], v[48:49], v[252:253], 0 op_sel_hi:[1,1,0]
	v_lshlrev_b32_e32 v252, 16, v211
	v_and_b32_e32 v253, 0xffff0000, v211
	v_mul_f32_e32 v252, s100, v252
	v_mul_f32_e32 v253, s100, v253
	v_exp_f32_e32 v252, v252
	v_exp_f32_e32 v253, v253
	v_add_f32_e32 v252, 1.0, v252
	v_add_f32_e32 v253, 1.0, v253
	v_rcp_f32_e32 v252, v252
	v_rcp_f32_e32 v253, v253
	s_nop 0
	v_pk_fma_f32 v[50:51], v[50:51], v[252:253], 0 op_sel_hi:[1,1,0]
	v_cvt_pk_bf16_f32 v52, v52, v53
	v_cvt_pk_bf16_f32 v53, v54, v55
	v_cvt_pk_bf16_f32 v54, v48, v49
	v_cvt_pk_bf16_f32 v55, v50, v51
	v_add_u32_e32 v252, 0x80000, v149
	global_store_dwordx4 v252, v[52:55], s[2:3] offset:256
	s_waitcnt vmcnt(15)
	v_lshlrev_b32_e32 v252, 16, v212
	v_and_b32_e32 v253, 0xffff0000, v212
	v_mul_f32_e32 v252, s100, v252
	v_mul_f32_e32 v253, s100, v253
	v_exp_f32_e32 v252, v252
	v_exp_f32_e32 v253, v253
	v_add_f32_e32 v252, 1.0, v252
	v_add_f32_e32 v253, 1.0, v253
	v_rcp_f32_e32 v252, v252
	v_rcp_f32_e32 v253, v253
	s_nop 0
	v_pk_fma_f32 v[44:45], v[44:45], v[252:253], 0 op_sel_hi:[1,1,0]
	v_lshlrev_b32_e32 v252, 16, v213
	v_and_b32_e32 v253, 0xffff0000, v213
	v_mul_f32_e32 v252, s100, v252
	v_mul_f32_e32 v253, s100, v253
	v_exp_f32_e32 v252, v252
	v_exp_f32_e32 v253, v253
	v_add_f32_e32 v252, 1.0, v252
	v_add_f32_e32 v253, 1.0, v253
	v_rcp_f32_e32 v252, v252
	v_rcp_f32_e32 v253, v253
	s_nop 0
	v_pk_fma_f32 v[46:47], v[46:47], v[252:253], 0 op_sel_hi:[1,1,0]
	v_lshlrev_b32_e32 v252, 16, v214
	v_and_b32_e32 v253, 0xffff0000, v214
	v_mul_f32_e32 v252, s100, v252
	v_mul_f32_e32 v253, s100, v253
	v_exp_f32_e32 v252, v252
	v_exp_f32_e32 v253, v253
	v_add_f32_e32 v252, 1.0, v252
	v_add_f32_e32 v253, 1.0, v253
	v_rcp_f32_e32 v252, v252
	v_rcp_f32_e32 v253, v253
	s_nop 0
	v_pk_fma_f32 v[40:41], v[40:41], v[252:253], 0 op_sel_hi:[1,1,0]
	v_lshlrev_b32_e32 v252, 16, v215
	v_and_b32_e32 v253, 0xffff0000, v215
	v_mul_f32_e32 v252, s100, v252
	v_mul_f32_e32 v253, s100, v253
	v_exp_f32_e32 v252, v252
	v_exp_f32_e32 v253, v253
	v_add_f32_e32 v252, 1.0, v252
	v_add_f32_e32 v253, 1.0, v253
	v_rcp_f32_e32 v252, v252
	v_rcp_f32_e32 v253, v253
	s_nop 0
	v_pk_fma_f32 v[42:43], v[42:43], v[252:253], 0 op_sel_hi:[1,1,0]
	v_cvt_pk_bf16_f32 v44, v44, v45
	v_cvt_pk_bf16_f32 v45, v46, v47
	v_cvt_pk_bf16_f32 v46, v40, v41
	v_cvt_pk_bf16_f32 v47, v42, v43
	v_add_u32_e32 v252, 0x90000, v149
	global_store_dwordx4 v252, v[44:47], s[2:3]
	s_waitcnt vmcnt(15)
; __device__ __forceinline__ unsigned cvt_pk_bf16(float lo, float hi) { const f32x2_t v = {lo, hi}; const bf16x2_t b = __builtin_convertvector(v, bf16x2_t); return __builtin_bit_cast(unsigned, b); }
; __device__ __forceinline__ float bf_lo(unsigned w) { return __uint_as_float(w << 16); }
; __device__ __forceinline__ float bf_hi(unsigned w) { return __uint_as_float(w & 0xffff0000u); }
;     __device__ __forceinline__ void operator()(const f32x4 (&acc)[2][2][4][2], const Unit& u, int wr, int wc, int fr, int fq) const {
;     ...
;             for (int m = 0; m < 4; ++m) { const size_t row = (size_t)(row0 + ai * HALF + m * 16); bf16_t* rowp = U + (ACCUM ? (size_t)0 : (size_t)u.z * zsU) + row * ldc + col0; const bf16_t* gp = GT + row * ldg + (size_t)u.z * 2048 + col0;
; #pragma unroll
;                 for (int bj = 0; bj < 2; ++bj) { const u32x4 gw = *(const u32x4*)(gp + bj * HALF); u32x4 pw = (u32x4){0u, 0u, 0u, 0u}; if (ACCUM && u.z > 0) pw = *(const u32x4*)(rowp + bj * HALF);
;                     const f32x4 v0 = acc[ai][bj][m][0], v1 = acc[ai][bj][m][1]; const float a[8] = {v0[0], v0[1], v0[2], v0[3], v1[0], v1[1], v1[2], v1[3]};
;                     float o[8];
; #pragma unroll
;                     for (int j = 0; j < 4; ++j) { const unsigned g2 = gw[j], p2 = pw[j];
;                         const float s0 = __builtin_amdgcn_rcpf(1.f + __expf(-bf_lo(g2))), s1 = __builtin_amdgcn_rcpf(1.f + __expf(-bf_hi(g2)));
;                         o[2 * j] = bf_lo(p2) + s0 * a[2 * j]; o[2 * j + 1] = bf_hi(p2) + s1 * a[2 * j + 1]; }
;                     u32x4 w; w.x = cvt_pk_bf16(o[0], o[1]); w.y = cvt_pk_bf16(o[2], o[3]); w.z = cvt_pk_bf16(o[4], o[5]); w.w = cvt_pk_bf16(o[6], o[7]);
;                     *(u32x4*)(rowp + bj * HALF) = w; } }
	v_lshlrev_b32_e32 v252, 16, v216
	v_and_b32_e32 v253, 0xffff0000, v216
	v_mul_f32_e32 v252, s100, v252
	v_mul_f32_e32 v253, s100, v253
	v_exp_f32_e32 v252, v252
	v_exp_f32_e32 v253, v253
	v_add_f32_e32 v252, 1.0, v252
	v_add_f32_e32 v253, 1.0, v253
	v_rcp_f32_e32 v252, v252
	v_rcp_f32_e32 v253, v253
	s_nop 0
	v_pk_fma_f32 v[36:37], v[36:37], v[252:253], 0 op_sel_hi:[1,1,0]
	v_lshlrev_b32_e32 v252, 16, v217
	v_and_b32_e32 v253, 0xffff0000, v217
	v_mul_f32_e32 v252, s100, v252
	v_mul_f32_e32 v253, s100, v253
	v_exp_f32_e32 v252, v252
	v_exp_f32_e32 v253, v253
	v_add_f32_e32 v252, 1.0, v252
	v_add_f32_e32 v253, 1.0, v253
	v_rcp_f32_e32 v252, v252
	v_rcp_f32_e32 v253, v253
	s_nop 0
	v_pk_fma_f32 v[38:39], v[38:39], v[252:253], 0 op_sel_hi:[1,1,0]
	v_lshlrev_b32_e32 v252, 16, v218
	v_and_b32_e32 v253, 0xffff0000, v218
	v_mul_f32_e32 v252, s100, v252
	v_mul_f32_e32 v253, s100, v253
	v_exp_f32_e32 v252, v252
	v_exp_f32_e32 v253, v253
	v_add_f32_e32 v252, 1.0, v252
	v_add_f32_e32 v253, 1.0, v253
	v_rcp_f32_e32 v252, v252
	v_rcp_f32_e32 v253, v253
	s_nop 0
	v_pk_fma_f32 v[32:33], v[32:33], v[252:253], 0 op_sel_hi:[1,1,0]
	v_lshlrev_b32_e32 v252, 16, v219
	v_and_b32_e32 v253, 0xffff0000, v219
	v_mul_f32_e32 v252, s100, v252
	v_mul_f32_e32 v253, s100, v253
	v_exp_f32_e32 v252, v252
	v_exp_f32_e32 v253, v253
	v_add_f32_e32 v252, 1.0, v252
	v_add_f32_e32 v253, 1.0, v253
	v_rcp_f32_e32 v252, v252
	v_rcp_f32_e32 v253, v253
	s_nop 0
	v_pk_fma_f32 v[34:35], v[34:35], v[252:253], 0 op_sel_hi:[1,1,0]
	v_cvt_pk_bf16_f32 v36, v36, v37
	v_cvt_pk_bf16_f32 v37, v38, v39
	v_cvt_pk_bf16_f32 v38, v32, v33
	v_cvt_pk_bf16_f32 v39, v34, v35
	v_add_u32_e32 v252, 0x90000, v149
	global_store_dwordx4 v252, v[36:39], s[2:3] offset:256
	s_waitcnt vmcnt(15)
	v_lshlrev_b32_e32 v252, 16, v220
	v_and_b32_e32 v253, 0xffff0000, v220
	v_mul_f32_e32 v252, s100, v252
	v_mul_f32_e32 v253, s100, v253
	v_exp_f32_e32 v252, v252
	v_exp_f32_e32 v253, v253
	v_add_f32_e32 v252, 1.0, v252
	v_add_f32_e32 v253, 1.0, v253
	v_rcp_f32_e32 v252, v252
	v_rcp_f32_e32 v253, v253
	s_nop 0
	v_pk_fma_f32 v[28:29], v[28:29], v[252:253], 0 op_sel_hi:[1,1,0]
	v_lshlrev_b32_e32 v252, 16, v221
	v_and_b32_e32 v253, 0xffff0000, v221
	v_mul_f32_e32 v252, s100, v252
	v_mul_f32_e32 v253, s100, v253
	v_exp_f32_e32 v252, v252
	v_exp_f32_e32 v253, v253
	v_add_f32_e32 v252, 1.0, v252
	v_add_f32_e32 v253, 1.0, v253
	v_rcp_f32_e32 v252, v252
	v_rcp_f32_e32 v253, v253
	s_nop 0
	v_pk_fma_f32 v[30:31], v[30:31], v[252:253], 0 op_sel_hi:[1,1,0]
	v_lshlrev_b32_e32 v252, 16, v222
	v_and_b32_e32 v253, 0xffff0000, v222
	v_mul_f32_e32 v252, s100, v252
	v_mul_f32_e32 v253, s100, v253
	v_exp_f32_e32 v252, v252
	v_exp_f32_e32 v253, v253
	v_add_f32_e32 v252, 1.0, v252
	v_add_f32_e32 v253, 1.0, v253
	v_rcp_f32_e32 v252, v252
	v_rcp_f32_e32 v253, v253
	s_nop 0
	v_pk_fma_f32 v[24:25], v[24:25], v[252:253], 0 op_sel_hi:[1,1,0]
	v_lshlrev_b32_e32 v252, 16, v223
	v_and_b32_e32 v253, 0xffff0000, v223
	v_mul_f32_e32 v252, s100, v252
	v_mul_f32_e32 v253, s100, v253
	v_exp_f32_e32 v252, v252
	v_exp_f32_e32 v253, v253
	v_add_f32_e32 v252, 1.0, v252
	v_add_f32_e32 v253, 1.0, v253
	v_rcp_f32_e32 v252, v252
	v_rcp_f32_e32 v253, v253
	s_nop 0
	v_pk_fma_f32 v[26:27], v[26:27], v[252:253], 0 op_sel_hi:[1,1,0]
	v_cvt_pk_bf16_f32 v28, v28, v29
	v_cvt_pk_bf16_f32 v29, v30, v31
	v_cvt_pk_bf16_f32 v30, v24, v25
	v_cvt_pk_bf16_f32 v31, v26, v27
	v_add_u32_e32 v252, 0xa0000, v149
	global_store_dwordx4 v252, v[28:31], s[2:3]
	s_waitcnt vmcnt(15)
	v_lshlrev_b32_e32 v252, 16, v224
	v_and_b32_e32 v253, 0xffff0000, v224
	v_mul_f32_e32 v252, s100, v252
	v_mul_f32_e32 v253, s100, v253
	v_exp_f32_e32 v252, v252
	v_exp_f32_e32 v253, v253
	v_add_f32_e32 v252, 1.0, v252
	v_add_f32_e32 v253, 1.0, v253
	v_rcp_f32_e32 v252, v252
	v_rcp_f32_e32 v253, v253
	s_nop 0
	v_pk_fma_f32 v[20:21], v[20:21], v[252:253], 0 op_sel_hi:[1,1,0]
	v_lshlrev_b32_e32 v252, 16, v225
	v_and_b32_e32 v253, 0xffff0000, v225
	v_mul_f32_e32 v252, s100, v252
	v_mul_f32_e32 v253, s100, v253
	v_exp_f32_e32 v252, v252
	v_exp_f32_e32 v253, v253
	v_add_f32_e32 v252, 1.0, v252
	v_add_f32_e32 v253, 1.0, v253
	v_rcp_f32_e32 v252, v252
	v_rcp_f32_e32 v253, v253
	s_nop 0
	v_pk_fma_f32 v[22:23], v[22:23], v[252:253], 0 op_sel_hi:[1,1,0]
	v_lshlrev_b32_e32 v252, 16, v226
	v_and_b32_e32 v253, 0xffff0000, v226
	v_mul_f32_e32 v252, s100, v252
	v_mul_f32_e32 v253, s100, v253
	v_exp_f32_e32 v252, v252
	v_exp_f32_e32 v253, v253
	v_add_f32_e32 v252, 1.0, v252
	v_add_f32_e32 v253, 1.0, v253
	v_rcp_f32_e32 v252, v252
	v_rcp_f32_e32 v253, v253
	s_nop 0
	v_pk_fma_f32 v[16:17], v[16:17], v[252:253], 0 op_sel_hi:[1,1,0]
	v_lshlrev_b32_e32 v252, 16, v227
	v_and_b32_e32 v253, 0xffff0000, v227
	v_mul_f32_e32 v252, s100, v252
	v_mul_f32_e32 v253, s100, v253
	v_exp_f32_e32 v252, v252
	v_exp_f32_e32 v253, v253
	v_add_f32_e32 v252, 1.0, v252
	v_add_f32_e32 v253, 1.0, v253
	v_rcp_f32_e32 v252, v252
	v_rcp_f32_e32 v253, v253
	s_nop 0
	v_pk_fma_f32 v[18:19], v[18:19], v[252:253], 0 op_sel_hi:[1,1,0]
	v_cvt_pk_bf16_f32 v20, v20, v21
	v_cvt_pk_bf16_f32 v21, v22, v23
	v_cvt_pk_bf16_f32 v22, v16, v17
	v_cvt_pk_bf16_f32 v23, v18, v19
	v_add_u32_e32 v252, 0xa0000, v149
	global_store_dwordx4 v252, v[20:23], s[2:3] offset:256
	s_waitcnt vmcnt(15)
; __device__ __forceinline__ unsigned cvt_pk_bf16(float lo, float hi) { const f32x2_t v = {lo, hi}; const bf16x2_t b = __builtin_convertvector(v, bf16x2_t); return __builtin_bit_cast(unsigned, b); }
; __device__ __forceinline__ float bf_lo(unsigned w) { return __uint_as_float(w << 16); }
; __device__ __forceinline__ float bf_hi(unsigned w) { return __uint_as_float(w & 0xffff0000u); }
;     __device__ __forceinline__ void operator()(const f32x4 (&acc)[2][2][4][2], const Unit& u, int wr, int wc, int fr, int fq) const {
;     ...
;             for (int m = 0; m < 4; ++m) { const size_t row = (size_t)(row0 + ai * HALF + m * 16); bf16_t* rowp = U + (ACCUM ? (size_t)0 : (size_t)u.z * zsU) + row * ldc + col0; const bf16_t* gp = GT + row * ldg + (size_t)u.z * 2048 + col0;
; #pragma unroll
;                 for (int bj = 0; bj < 2; ++bj) { const u32x4 gw = *(const u32x4*)(gp + bj * HALF); u32x4 pw = (u32x4){0u, 0u, 0u, 0u}; if (ACCUM && u.z > 0) pw = *(const u32x4*)(rowp + bj * HALF);
;                     const f32x4 v0 = acc[ai][bj][m][0], v1 = acc[ai][bj][m][1]; const float a[8] = {v0[0], v0[1], v0[2], v0[3], v1[0], v1[1], v1[2], v1[3]};
;                     float o[8];
; #pragma unroll
;                     for (int j = 0; j < 4; ++j) { const unsigned g2 = gw[j], p2 = pw[j];
;                         const float s0 = __builtin_amdgcn_rcpf(1.f + __expf(-bf_lo(g2))), s1 = __builtin_amdgcn_rcpf(1.f + __expf(-bf_hi(g2)));
;                         o[2 * j] = bf_lo(p2) + s0 * a[2 * j]; o[2 * j + 1] = bf_hi(p2) + s1 * a[2 * j + 1]; }
;                     u32x4 w; w.x = cvt_pk_bf16(o[0], o[1]); w.y = cvt_pk_bf16(o[2], o[3]); w.z = cvt_pk_bf16(o[4], o[5]); w.w = cvt_pk_bf16(o[6], o[7]);
;                     *(u32x4*)(rowp + bj * HALF) = w; } }
	v_lshlrev_b32_e32 v252, 16, v228
	v_and_b32_e32 v253, 0xffff0000, v228
	v_mul_f32_e32 v252, s100, v252
	v_mul_f32_e32 v253, s100, v253
	v_exp_f32_e32 v252, v252
	v_exp_f32_e32 v253, v253
	v_add_f32_e32 v252, 1.0, v252
	v_add_f32_e32 v253, 1.0, v253
	v_rcp_f32_e32 v252, v252
	v_rcp_f32_e32 v253, v253
	s_nop 0
	v_pk_fma_f32 v[12:13], v[12:13], v[252:253], 0 op_sel_hi:[1,1,0]
	v_lshlrev_b32_e32 v252, 16, v229
	v_and_b32_e32 v253, 0xffff0000, v229
	v_mul_f32_e32 v252, s100, v252
	v_mul_f32_e32 v253, s100, v253
	v_exp_f32_e32 v252, v252
	v_exp_f32_e32 v253, v253
	v_add_f32_e32 v252, 1.0, v252
	v_add_f32_e32 v253, 1.0, v253
	v_rcp_f32_e32 v252, v252
	v_rcp_f32_e32 v253, v253
	s_nop 0
	v_pk_fma_f32 v[14:15], v[14:15], v[252:253], 0 op_sel_hi:[1,1,0]
	v_lshlrev_b32_e32 v252, 16, v230
	v_and_b32_e32 v253, 0xffff0000, v230
	v_mul_f32_e32 v252, s100, v252
	v_mul_f32_e32 v253, s100, v253
	v_exp_f32_e32 v252, v252
	v_exp_f32_e32 v253, v253
	v_add_f32_e32 v252, 1.0, v252
	v_add_f32_e32 v253, 1.0, v253
	v_rcp_f32_e32 v252, v252
	v_rcp_f32_e32 v253, v253
	s_nop 0
	v_pk_fma_f32 v[8:9], v[8:9], v[252:253], 0 op_sel_hi:[1,1,0]
	v_lshlrev_b32_e32 v252, 16, v231
	v_and_b32_e32 v253, 0xffff0000, v231
	v_mul_f32_e32 v252, s100, v252
	v_mul_f32_e32 v253, s100, v253
	v_exp_f32_e32 v252, v252
	v_exp_f32_e32 v253, v253
	v_add_f32_e32 v252, 1.0, v252
	v_add_f32_e32 v253, 1.0, v253
	v_rcp_f32_e32 v252, v252
	v_rcp_f32_e32 v253, v253
	s_nop 0
	v_pk_fma_f32 v[10:11], v[10:11], v[252:253], 0 op_sel_hi:[1,1,0]
	v_cvt_pk_bf16_f32 v12, v12, v13
	v_cvt_pk_bf16_f32 v13, v14, v15
	v_cvt_pk_bf16_f32 v14, v8, v9
	v_cvt_pk_bf16_f32 v15, v10, v11
	v_add_u32_e32 v252, 0xb0000, v149
	global_store_dwordx4 v252, v[12:15], s[2:3]
	s_waitcnt vmcnt(15)
	v_lshlrev_b32_e32 v252, 16, v232
	v_and_b32_e32 v253, 0xffff0000, v232
	v_mul_f32_e32 v252, s100, v252
	v_mul_f32_e32 v253, s100, v253
	v_exp_f32_e32 v252, v252
	v_exp_f32_e32 v253, v253
	v_add_f32_e32 v252, 1.0, v252
	v_add_f32_e32 v253, 1.0, v253
	v_rcp_f32_e32 v252, v252
	v_rcp_f32_e32 v253, v253
	s_nop 0
	v_pk_fma_f32 v[4:5], v[4:5], v[252:253], 0 op_sel_hi:[1,1,0]
	v_lshlrev_b32_e32 v252, 16, v233
	v_and_b32_e32 v253, 0xffff0000, v233
	v_mul_f32_e32 v252, s100, v252
	v_mul_f32_e32 v253, s100, v253
	v_exp_f32_e32 v252, v252
	v_exp_f32_e32 v253, v253
	v_add_f32_e32 v252, 1.0, v252
	v_add_f32_e32 v253, 1.0, v253
	v_rcp_f32_e32 v252, v252
	v_rcp_f32_e32 v253, v253
	s_nop 0
	v_pk_fma_f32 v[6:7], v[6:7], v[252:253], 0 op_sel_hi:[1,1,0]
	v_lshlrev_b32_e32 v252, 16, v234
	v_and_b32_e32 v253, 0xffff0000, v234
	v_mul_f32_e32 v252, s100, v252
	v_mul_f32_e32 v253, s100, v253
	v_exp_f32_e32 v252, v252
	v_exp_f32_e32 v253, v253
	v_add_f32_e32 v252, 1.0, v252
	v_add_f32_e32 v253, 1.0, v253
	v_rcp_f32_e32 v252, v252
	v_rcp_f32_e32 v253, v253
	s_nop 0
	v_pk_fma_f32 v[0:1], v[0:1], v[252:253], 0 op_sel_hi:[1,1,0]
	v_lshlrev_b32_e32 v252, 16, v235
	v_and_b32_e32 v253, 0xffff0000, v235
	v_mul_f32_e32 v252, s100, v252
	v_mul_f32_e32 v253, s100, v253
	v_exp_f32_e32 v252, v252
	v_exp_f32_e32 v253, v253
	v_add_f32_e32 v252, 1.0, v252
	v_add_f32_e32 v253, 1.0, v253
	v_rcp_f32_e32 v252, v252
	v_rcp_f32_e32 v253, v253
	s_nop 0
	v_pk_fma_f32 v[2:3], v[2:3], v[252:253], 0 op_sel_hi:[1,1,0]
	v_cvt_pk_bf16_f32 v4, v4, v5
	v_cvt_pk_bf16_f32 v5, v6, v7
	v_cvt_pk_bf16_f32 v6, v0, v1
	v_cvt_pk_bf16_f32 v7, v2, v3
	v_add_u32_e32 v252, 0xb0000, v149
	global_store_dwordx4 v252, v[4:7], s[2:3] offset:256
	s_and_b64 vcc, exec, s[40:41]
	s_mov_b64 s[0:1], -1
	s_cbranch_vccnz .LBB0_1225
	s_andn2_b64 vcc, exec, s[4:5]
	s_cbranch_vccnz .LBB0_1224
	s_barrier
	s_branch .LBB0_1224

; #define GAS __attribute__((address_space(1)))
; #define LAS __attribute__((address_space(3)))
; #define LDS_WAIT() asm volatile("s_waitcnt lgkmcnt(0)" ::: "memory")
; __device__ __forceinline__ void ln_phase(Frame& FF, int l, int gi, const float* lng, const float* lnb, int lh, int hmod, bool first, bool to_out, int nrows, bool dry, int nslab) {
;     ...
;         __syncthreads();
;         { const float* gv = mo + ((size_t)l * 5 + mb) * 12288 + gi * 2048; const float* mh = mo + ((size_t)(hmod >= 0 ? lh : l) * 5 + mb) * 12288; const int c = 4 * F.tid;
;           *(LAS f32x4*)(V + 0 * 2048 + c) = *(const GAS f32x4*)(gv + c); *(LAS f32x4*)(V + 1 * 2048 + c) = *(const GAS f32x4*)(lng + c); *(LAS f32x4*)(V + 2 * 2048 + c) = *(const GAS f32x4*)(lnb + c);
;           if (hmod >= 0) { *(LAS f32x4*)(V + 3 * 2048 + c) = *(const GAS f32x4*)(mh + (hmod + 1) * 2048 + c) + 1.0f; *(LAS f32x4*)(V + 4 * 2048 + c) = *(const GAS f32x4*)(mh + hmod * 2048 + c); } }
;         LDS_WAIT(); __syncthreads();
.LBB0_1479:
	v_readlane_b32 s6, v245, 50
	v_readlane_b32 s7, v245, 51
	s_and_b64 s[2:3], s[6:7], s[2:3]
	s_and_b64 vcc, exec, s[2:3]
	s_mov_b64 s[6:7], -1
	s_cbranch_vccnz .LBB0_1478
	s_xor_b64 s[6:7], s[0:1], -1
	s_and_b64 s[0:1], s[0:1], exec
	v_readlane_b32 s1, v247, 48
	v_readlane_b32 s2, v245, 52
	v_readlane_b32 s0, v247, 49
	s_cselect_b32 s1, s1, 4
	s_mul_i32 s2, s2, 5
	s_cselect_b32 s0, s0, 0
	s_add_u32 s1, s1, s2
	s_addc_u32 s0, s0, 0
	v_readlane_b32 s3, v245, 53
	s_mul_i32 s2, s0, 0xc000
	s_mul_hi_u32 s0, s1, 0xc000
	s_add_i32 s3, s0, s2
	s_mul_i32 s8, s1, 0xc000
	v_mad_u64_u32 v[0:1], s[0:1], s1, v207, v[180:181]
	v_add_u32_e32 v1, s2, v1
	s_waitcnt vmcnt(0)
	s_barrier
	global_load_dwordx4 v[0:3], v[0:1], off
	v_readlane_b32 s0, v247, 32
	s_add_u32 s0, s0, s8
	v_readlane_b32 s1, v247, 33
	s_addc_u32 s1, s1, s3
	global_load_dwordx4 v[8:11], v[182:183], off
	v_lshl_add_u64 v[4:5], v[178:179], 2, s[0:1]
	s_mov_b64 s[0:1], -1
	global_load_dwordx4 v[12:15], v[184:185], off
	v_add_co_u32_e32 v6, vcc, 0x8000, v4
	s_nop 1
	v_addc_co_u32_e32 v7, vcc, 0, v5, vcc
	global_load_dwordx4 v[32:35], v[6:7], off
	v_add_co_u32_e32 v40, vcc, 0x6000, v4
	s_nop 1
	v_addc_co_u32_e32 v41, vcc, 0, v5, vcc
	global_load_dwordx4 v[36:39], v[40:41], off
	s_and_b64 vcc, exec, s[6:7]
	s_waitcnt vmcnt(4)
	ds_write_b128 v192, v[0:3]
	s_waitcnt vmcnt(3)
	ds_write_b128 v192, v[8:11] offset:8192
	s_waitcnt vmcnt(2)
	ds_write_b128 v192, v[12:15] offset:16384
	s_waitcnt vmcnt(1)
	v_pk_add_f32 v[34:35], v[34:35], 1.0 op_sel_hi:[1,0]
	v_pk_add_f32 v[32:33], v[32:33], 1.0 op_sel_hi:[1,0]
	ds_write_b128 v192, v[32:35] offset:24576
	s_waitcnt vmcnt(0)
	ds_write_b128 v192, v[36:39] offset:32768
	s_waitcnt lgkmcnt(0)
	v_cndmask_b32_e64 v0, 0, 1, s[4:5]
	v_cmp_ne_u32_e64 s[42:43], 1, v0
	s_waitcnt lgkmcnt(0)
	s_barrier
	s_cbranch_vccz .LBB0_1489
	v_readlane_b32 s0, v246, 12
	s_and_b64 vcc, exec, s[42:43]
	v_readlane_b32 s1, v246, 13
	s_cbranch_vccz .LBB0_1483
	v_cmp_ne_u32_e32 vcc, 1, v198
	s_cbranch_vccz .LBB0_1484
	s_branch .LBB0_1488

.LBB0_1485:
	s_add_u32 s2, s8, 0
	s_addc_u32 s3, s9, 0
	v_lshl_add_u64 v[66:67], s[2:3], 0, v[186:187]
	global_load_dwordx2 v[72:73], v[66:67], off
	global_load_dwordx2 v[74:75], v[66:67], off offset:512
	global_load_dwordx2 v[76:77], v[66:67], off offset:1024
	global_load_dwordx2 v[78:79], v[66:67], off offset:1536
	global_load_dwordx2 v[80:81], v[66:67], off offset:2048
	global_load_dwordx2 v[82:83], v[66:67], off offset:2560
	global_load_dwordx2 v[84:85], v[66:67], off offset:3072
	global_load_dwordx2 v[86:87], v[66:67], off offset:3584
	s_add_u32 s2, s8, 0x400000
	s_addc_u32 s3, s9, 0
	v_lshl_add_u64 v[68:69], s[2:3], 0, v[186:187]
	global_load_dwordx2 v[88:89], v[68:69], off
	global_load_dwordx2 v[90:91], v[68:69], off offset:512
	global_load_dwordx2 v[92:93], v[68:69], off offset:1024
	global_load_dwordx2 v[94:95], v[68:69], off offset:1536
	global_load_dwordx2 v[96:97], v[68:69], off offset:2048
	global_load_dwordx2 v[98:99], v[68:69], off offset:2560
	global_load_dwordx2 v[100:101], v[68:69], off offset:3072
	global_load_dwordx2 v[102:103], v[68:69], off offset:3584
	s_add_u32 s2, s8, 0x800000
	s_addc_u32 s3, s9, 0
	v_lshl_add_u64 v[70:71], s[2:3], 0, v[186:187]
	global_load_dwordx2 v[104:105], v[70:71], off
	global_load_dwordx2 v[106:107], v[70:71], off offset:512
	global_load_dwordx2 v[108:109], v[70:71], off offset:1024
	global_load_dwordx2 v[110:111], v[70:71], off offset:1536
	global_load_dwordx2 v[112:113], v[70:71], off offset:2048
	global_load_dwordx2 v[114:115], v[70:71], off offset:2560
	global_load_dwordx2 v[116:117], v[70:71], off offset:3072
	global_load_dwordx2 v[118:119], v[70:71], off offset:3584
	s_waitcnt vmcnt(16)
	v_lshlrev_b32_e32 v120, 16, v72
	v_and_b32_e32 v121, 0xffff0000, v72
	v_lshlrev_b32_e32 v72, 16, v73
	v_and_b32_e32 v73, 0xffff0000, v73
	v_pk_add_f32 v[38:39], v[38:39], v[72:73]
	v_pk_add_f32 v[36:37], v[36:37], v[120:121]
	v_lshlrev_b32_e32 v122, 16, v74
	v_and_b32_e32 v123, 0xffff0000, v74
	v_lshlrev_b32_e32 v74, 16, v75
	v_and_b32_e32 v75, 0xffff0000, v75
	v_pk_add_f32 v[42:43], v[42:43], v[74:75]
	v_pk_add_f32 v[40:41], v[40:41], v[122:123]
	v_lshlrev_b32_e32 v120, 16, v76
	v_and_b32_e32 v121, 0xffff0000, v76
	v_lshlrev_b32_e32 v76, 16, v77
	v_and_b32_e32 v77, 0xffff0000, v77
	v_pk_add_f32 v[46:47], v[46:47], v[76:77]
	v_pk_add_f32 v[44:45], v[44:45], v[120:121]
	v_lshlrev_b32_e32 v122, 16, v78
	v_and_b32_e32 v123, 0xffff0000, v78
	v_lshlrev_b32_e32 v78, 16, v79
	v_and_b32_e32 v79, 0xffff0000, v79
	v_pk_add_f32 v[50:51], v[50:51], v[78:79]
	v_pk_add_f32 v[48:49], v[48:49], v[122:123]
	v_lshlrev_b32_e32 v120, 16, v80
	v_and_b32_e32 v121, 0xffff0000, v80
	v_lshlrev_b32_e32 v80, 16, v81
	v_and_b32_e32 v81, 0xffff0000, v81
	v_pk_add_f32 v[54:55], v[54:55], v[80:81]
	v_pk_add_f32 v[52:53], v[52:53], v[120:121]
	v_lshlrev_b32_e32 v122, 16, v82
	v_and_b32_e32 v123, 0xffff0000, v82
	v_lshlrev_b32_e32 v82, 16, v83
	v_and_b32_e32 v83, 0xffff0000, v83
	v_pk_add_f32 v[58:59], v[58:59], v[82:83]
	v_pk_add_f32 v[56:57], v[56:57], v[122:123]
	v_lshlrev_b32_e32 v120, 16, v84
	v_and_b32_e32 v121, 0xffff0000, v84
	v_lshlrev_b32_e32 v84, 16, v85
	v_and_b32_e32 v85, 0xffff0000, v85
	v_pk_add_f32 v[62:63], v[62:63], v[84:85]
	v_pk_add_f32 v[60:61], v[60:61], v[120:121]
	v_lshlrev_b32_e32 v122, 16, v86
	v_and_b32_e32 v123, 0xffff0000, v86
	v_lshlrev_b32_e32 v86, 16, v87
	v_and_b32_e32 v87, 0xffff0000, v87
	v_pk_add_f32 v[34:35], v[34:35], v[86:87]
	v_pk_add_f32 v[32:33], v[32:33], v[122:123]
	s_add_u32 s2, s8, 0xc00000
	s_addc_u32 s3, s9, 0
	v_lshl_add_u64 v[66:67], s[2:3], 0, v[186:187]
	global_load_dwordx2 v[72:73], v[66:67], off
	global_load_dwordx2 v[74:75], v[66:67], off offset:512
	global_load_dwordx2 v[76:77], v[66:67], off offset:1024
	global_load_dwordx2 v[78:79], v[66:67], off offset:1536
	global_load_dwordx2 v[80:81], v[66:67], off offset:2048
	global_load_dwordx2 v[82:83], v[66:67], off offset:2560
	global_load_dwordx2 v[84:85], v[66:67], off offset:3072
	global_load_dwordx2 v[86:87], v[66:67], off offset:3584
	s_waitcnt vmcnt(16)
	v_lshlrev_b32_e32 v120, 16, v88
	v_and_b32_e32 v121, 0xffff0000, v88
	v_lshlrev_b32_e32 v88, 16, v89
	v_and_b32_e32 v89, 0xffff0000, v89
	v_pk_add_f32 v[38:39], v[38:39], v[88:89]
	v_pk_add_f32 v[36:37], v[36:37], v[120:121]
	v_lshlrev_b32_e32 v122, 16, v90
	v_and_b32_e32 v123, 0xffff0000, v90
	v_lshlrev_b32_e32 v90, 16, v91
	v_and_b32_e32 v91, 0xffff0000, v91
	v_pk_add_f32 v[42:43], v[42:43], v[90:91]
	v_pk_add_f32 v[40:41], v[40:41], v[122:123]
	v_lshlrev_b32_e32 v120, 16, v92
	v_and_b32_e32 v121, 0xffff0000, v92
	v_lshlrev_b32_e32 v92, 16, v93
	v_and_b32_e32 v93, 0xffff0000, v93
	v_pk_add_f32 v[46:47], v[46:47], v[92:93]
	v_pk_add_f32 v[44:45], v[44:45], v[120:121]
	v_lshlrev_b32_e32 v122, 16, v94
	v_and_b32_e32 v123, 0xffff0000, v94
	v_lshlrev_b32_e32 v94, 16, v95
	v_and_b32_e32 v95, 0xffff0000, v95
	v_pk_add_f32 v[50:51], v[50:51], v[94:95]
	v_pk_add_f32 v[48:49], v[48:49], v[122:123]
	v_lshlrev_b32_e32 v120, 16, v96
	v_and_b32_e32 v121, 0xffff0000, v96
	v_lshlrev_b32_e32 v96, 16, v97
	v_and_b32_e32 v97, 0xffff0000, v97
	v_pk_add_f32 v[54:55], v[54:55], v[96:97]
	v_pk_add_f32 v[52:53], v[52:53], v[120:121]
	v_lshlrev_b32_e32 v122, 16, v98
	v_and_b32_e32 v123, 0xffff0000, v98
	v_lshlrev_b32_e32 v98, 16, v99
	v_and_b32_e32 v99, 0xffff0000, v99
	v_pk_add_f32 v[58:59], v[58:59], v[98:99]
	v_pk_add_f32 v[56:57], v[56:57], v[122:123]
	v_lshlrev_b32_e32 v120, 16, v100
	v_and_b32_e32 v121, 0xffff0000, v100
	v_lshlrev_b32_e32 v100, 16, v101
	v_and_b32_e32 v101, 0xffff0000, v101
	v_pk_add_f32 v[62:63], v[62:63], v[100:101]
	v_pk_add_f32 v[60:61], v[60:61], v[120:121]
	v_lshlrev_b32_e32 v122, 16, v102
	v_and_b32_e32 v123, 0xffff0000, v102
	v_lshlrev_b32_e32 v102, 16, v103
	v_and_b32_e32 v103, 0xffff0000, v103
	v_pk_add_f32 v[34:35], v[34:35], v[102:103]
	v_pk_add_f32 v[32:33], v[32:33], v[122:123]
	s_add_u32 s2, s8, 0x1000000
	s_addc_u32 s3, s9, 0
	v_lshl_add_u64 v[68:69], s[2:3], 0, v[186:187]
	global_load_dwordx2 v[88:89], v[68:69], off
	global_load_dwordx2 v[90:91], v[68:69], off offset:512
	global_load_dwordx2 v[92:93], v[68:69], off offset:1024
	global_load_dwordx2 v[94:95], v[68:69], off offset:1536
	global_load_dwordx2 v[96:97], v[68:69], off offset:2048
	global_load_dwordx2 v[98:99], v[68:69], off offset:2560
	global_load_dwordx2 v[100:101], v[68:69], off offset:3072
	global_load_dwordx2 v[102:103], v[68:69], off offset:3584
	s_waitcnt vmcnt(16)
	v_lshlrev_b32_e32 v120, 16, v104
	v_and_b32_e32 v121, 0xffff0000, v104
	v_lshlrev_b32_e32 v104, 16, v105
	v_and_b32_e32 v105, 0xffff0000, v105
	v_pk_add_f32 v[38:39], v[38:39], v[104:105]
	v_pk_add_f32 v[36:37], v[36:37], v[120:121]
	v_lshlrev_b32_e32 v122, 16, v106
	v_and_b32_e32 v123, 0xffff0000, v106
	v_lshlrev_b32_e32 v106, 16, v107
	v_and_b32_e32 v107, 0xffff0000, v107
	v_pk_add_f32 v[42:43], v[42:43], v[106:107]
	v_pk_add_f32 v[40:41], v[40:41], v[122:123]
	v_lshlrev_b32_e32 v120, 16, v108
	v_and_b32_e32 v121, 0xffff0000, v108
	v_lshlrev_b32_e32 v108, 16, v109
	v_and_b32_e32 v109, 0xffff0000, v109
	v_pk_add_f32 v[46:47], v[46:47], v[108:109]
	v_pk_add_f32 v[44:45], v[44:45], v[120:121]
	v_lshlrev_b32_e32 v122, 16, v110
	v_and_b32_e32 v123, 0xffff0000, v110
	v_lshlrev_b32_e32 v110, 16, v111
	v_and_b32_e32 v111, 0xffff0000, v111
	v_pk_add_f32 v[50:51], v[50:51], v[110:111]
	v_pk_add_f32 v[48:49], v[48:49], v[122:123]
	v_lshlrev_b32_e32 v120, 16, v112
	v_and_b32_e32 v121, 0xffff0000, v112
	v_lshlrev_b32_e32 v112, 16, v113
	v_and_b32_e32 v113, 0xffff0000, v113
	v_pk_add_f32 v[54:55], v[54:55], v[112:113]
	v_pk_add_f32 v[52:53], v[52:53], v[120:121]
	v_lshlrev_b32_e32 v122, 16, v114
	v_and_b32_e32 v123, 0xffff0000, v114
	v_lshlrev_b32_e32 v114, 16, v115
	v_and_b32_e32 v115, 0xffff0000, v115
	v_pk_add_f32 v[58:59], v[58:59], v[114:115]
	v_pk_add_f32 v[56:57], v[56:57], v[122:123]
	v_lshlrev_b32_e32 v120, 16, v116
	v_and_b32_e32 v121, 0xffff0000, v116
	v_lshlrev_b32_e32 v116, 16, v117
	v_and_b32_e32 v117, 0xffff0000, v117
	v_pk_add_f32 v[62:63], v[62:63], v[116:117]
	v_pk_add_f32 v[60:61], v[60:61], v[120:121]
	v_lshlrev_b32_e32 v122, 16, v118
	v_and_b32_e32 v123, 0xffff0000, v118
	v_lshlrev_b32_e32 v118, 16, v119
	v_and_b32_e32 v119, 0xffff0000, v119
	v_pk_add_f32 v[34:35], v[34:35], v[118:119]
	v_pk_add_f32 v[32:33], v[32:33], v[122:123]
	s_add_u32 s2, s8, 0x1400000
	s_addc_u32 s3, s9, 0
	v_lshl_add_u64 v[70:71], s[2:3], 0, v[186:187]
	global_load_dwordx2 v[104:105], v[70:71], off
	global_load_dwordx2 v[106:107], v[70:71], off offset:512
	global_load_dwordx2 v[108:109], v[70:71], off offset:1024
	global_load_dwordx2 v[110:111], v[70:71], off offset:1536
	global_load_dwordx2 v[112:113], v[70:71], off offset:2048
	global_load_dwordx2 v[114:115], v[70:71], off offset:2560
	global_load_dwordx2 v[116:117], v[70:71], off offset:3072
	global_load_dwordx2 v[118:119], v[70:71], off offset:3584
	s_waitcnt vmcnt(16)
	v_lshlrev_b32_e32 v120, 16, v72
	v_and_b32_e32 v121, 0xffff0000, v72
	v_lshlrev_b32_e32 v72, 16, v73
	v_and_b32_e32 v73, 0xffff0000, v73
	v_pk_add_f32 v[38:39], v[38:39], v[72:73]
	v_pk_add_f32 v[36:37], v[36:37], v[120:121]
	v_lshlrev_b32_e32 v122, 16, v74
	v_and_b32_e32 v123, 0xffff0000, v74
	v_lshlrev_b32_e32 v74, 16, v75
	v_and_b32_e32 v75, 0xffff0000, v75
	v_pk_add_f32 v[42:43], v[42:43], v[74:75]
	v_pk_add_f32 v[40:41], v[40:41], v[122:123]
	v_lshlrev_b32_e32 v120, 16, v76
	v_and_b32_e32 v121, 0xffff0000, v76
	v_lshlrev_b32_e32 v76, 16, v77
	v_and_b32_e32 v77, 0xffff0000, v77
	v_pk_add_f32 v[46:47], v[46:47], v[76:77]
	v_pk_add_f32 v[44:45], v[44:45], v[120:121]
	v_lshlrev_b32_e32 v122, 16, v78
	v_and_b32_e32 v123, 0xffff0000, v78
	v_lshlrev_b32_e32 v78, 16, v79
	v_and_b32_e32 v79, 0xffff0000, v79
	v_pk_add_f32 v[50:51], v[50:51], v[78:79]
	v_pk_add_f32 v[48:49], v[48:49], v[122:123]
	v_lshlrev_b32_e32 v120, 16, v80
	v_and_b32_e32 v121, 0xffff0000, v80
	v_lshlrev_b32_e32 v80, 16, v81
	v_and_b32_e32 v81, 0xffff0000, v81
	v_pk_add_f32 v[54:55], v[54:55], v[80:81]
	v_pk_add_f32 v[52:53], v[52:53], v[120:121]
	v_lshlrev_b32_e32 v122, 16, v82
	v_and_b32_e32 v123, 0xffff0000, v82
	v_lshlrev_b32_e32 v82, 16, v83
	v_and_b32_e32 v83, 0xffff0000, v83
	v_pk_add_f32 v[58:59], v[58:59], v[82:83]
	v_pk_add_f32 v[56:57], v[56:57], v[122:123]
	v_lshlrev_b32_e32 v120, 16, v84
	v_and_b32_e32 v121, 0xffff0000, v84
	v_lshlrev_b32_e32 v84, 16, v85
	v_and_b32_e32 v85, 0xffff0000, v85
	v_pk_add_f32 v[62:63], v[62:63], v[84:85]
	v_pk_add_f32 v[60:61], v[60:61], v[120:121]
	v_lshlrev_b32_e32 v122, 16, v86
	v_and_b32_e32 v123, 0xffff0000, v86
	v_lshlrev_b32_e32 v86, 16, v87
	v_and_b32_e32 v87, 0xffff0000, v87
	v_pk_add_f32 v[34:35], v[34:35], v[86:87]
	v_pk_add_f32 v[32:33], v[32:33], v[122:123]
	s_waitcnt vmcnt(8)
; #define LAS __attribute__((address_space(3)))
; __device__ __forceinline__ void ln_rows(Frame& F, const float* xbase, const float* mixbase, int nslab, float* obase, bf16* hbase, int row0, int nr, bool hm, LAS float* V, int lane, int wave) {
;     ...
;         for (int j = 0; j < 8; ++j) { const f32x4 g = *(const LAS f32x4*)(V + 0 * 2048 + 4 * lane + 256 * j); v[j] = xn[j] * DN_ALPHA + g * mn[j]; s += (v[j][0] + v[j][1]) + (v[j][2] + v[j][3]); }
	v_lshlrev_b32_e32 v120, 16, v88
	v_and_b32_e32 v121, 0xffff0000, v88
	v_lshlrev_b32_e32 v88, 16, v89
	v_and_b32_e32 v89, 0xffff0000, v89
	v_pk_add_f32 v[38:39], v[38:39], v[88:89]
	v_pk_add_f32 v[36:37], v[36:37], v[120:121]
	v_lshlrev_b32_e32 v122, 16, v90
	v_and_b32_e32 v123, 0xffff0000, v90
	v_lshlrev_b32_e32 v90, 16, v91
	v_and_b32_e32 v91, 0xffff0000, v91
	v_pk_add_f32 v[42:43], v[42:43], v[90:91]
	v_pk_add_f32 v[40:41], v[40:41], v[122:123]
	v_lshlrev_b32_e32 v120, 16, v92
	v_and_b32_e32 v121, 0xffff0000, v92
	v_lshlrev_b32_e32 v92, 16, v93
	v_and_b32_e32 v93, 0xffff0000, v93
	v_pk_add_f32 v[46:47], v[46:47], v[92:93]
	v_pk_add_f32 v[44:45], v[44:45], v[120:121]
	v_lshlrev_b32_e32 v122, 16, v94
	v_and_b32_e32 v123, 0xffff0000, v94
	v_lshlrev_b32_e32 v94, 16, v95
	v_and_b32_e32 v95, 0xffff0000, v95
	v_pk_add_f32 v[50:51], v[50:51], v[94:95]
	v_pk_add_f32 v[48:49], v[48:49], v[122:123]
	v_lshlrev_b32_e32 v120, 16, v96
	v_and_b32_e32 v121, 0xffff0000, v96
	v_lshlrev_b32_e32 v96, 16, v97
	v_and_b32_e32 v97, 0xffff0000, v97
	v_pk_add_f32 v[54:55], v[54:55], v[96:97]
	v_pk_add_f32 v[52:53], v[52:53], v[120:121]
	v_lshlrev_b32_e32 v122, 16, v98
	v_and_b32_e32 v123, 0xffff0000, v98
	v_lshlrev_b32_e32 v98, 16, v99
	v_and_b32_e32 v99, 0xffff0000, v99
	v_pk_add_f32 v[58:59], v[58:59], v[98:99]
	v_pk_add_f32 v[56:57], v[56:57], v[122:123]
	v_lshlrev_b32_e32 v120, 16, v100
	v_and_b32_e32 v121, 0xffff0000, v100
	v_lshlrev_b32_e32 v100, 16, v101
	v_and_b32_e32 v101, 0xffff0000, v101
	v_pk_add_f32 v[62:63], v[62:63], v[100:101]
	v_pk_add_f32 v[60:61], v[60:61], v[120:121]
	v_lshlrev_b32_e32 v122, 16, v102
	v_and_b32_e32 v123, 0xffff0000, v102
	v_lshlrev_b32_e32 v102, 16, v103
	v_and_b32_e32 v103, 0xffff0000, v103
	v_pk_add_f32 v[34:35], v[34:35], v[102:103]
	v_pk_add_f32 v[32:33], v[32:33], v[122:123]
	s_waitcnt vmcnt(0)
	v_lshlrev_b32_e32 v120, 16, v104
	v_and_b32_e32 v121, 0xffff0000, v104
	v_lshlrev_b32_e32 v104, 16, v105
	v_and_b32_e32 v105, 0xffff0000, v105
	v_pk_add_f32 v[38:39], v[38:39], v[104:105]
	v_pk_add_f32 v[36:37], v[36:37], v[120:121]
	v_lshlrev_b32_e32 v122, 16, v106
	v_and_b32_e32 v123, 0xffff0000, v106
	v_lshlrev_b32_e32 v106, 16, v107
	v_and_b32_e32 v107, 0xffff0000, v107
	v_pk_add_f32 v[42:43], v[42:43], v[106:107]
	v_pk_add_f32 v[40:41], v[40:41], v[122:123]
	v_lshlrev_b32_e32 v120, 16, v108
	v_and_b32_e32 v121, 0xffff0000, v108
	v_lshlrev_b32_e32 v108, 16, v109
	v_and_b32_e32 v109, 0xffff0000, v109
	v_pk_add_f32 v[46:47], v[46:47], v[108:109]
	v_pk_add_f32 v[44:45], v[44:45], v[120:121]
	v_lshlrev_b32_e32 v122, 16, v110
	v_and_b32_e32 v123, 0xffff0000, v110
	v_lshlrev_b32_e32 v110, 16, v111
	v_and_b32_e32 v111, 0xffff0000, v111
	v_pk_add_f32 v[50:51], v[50:51], v[110:111]
	v_pk_add_f32 v[48:49], v[48:49], v[122:123]
	v_lshlrev_b32_e32 v120, 16, v112
	v_and_b32_e32 v121, 0xffff0000, v112
	v_lshlrev_b32_e32 v112, 16, v113
	v_and_b32_e32 v113, 0xffff0000, v113
	v_pk_add_f32 v[54:55], v[54:55], v[112:113]
	v_pk_add_f32 v[52:53], v[52:53], v[120:121]
	v_lshlrev_b32_e32 v122, 16, v114
	v_and_b32_e32 v123, 0xffff0000, v114
	v_lshlrev_b32_e32 v114, 16, v115
	v_and_b32_e32 v115, 0xffff0000, v115
	v_pk_add_f32 v[58:59], v[58:59], v[114:115]
	v_pk_add_f32 v[56:57], v[56:57], v[122:123]
	v_lshlrev_b32_e32 v120, 16, v116
	v_and_b32_e32 v121, 0xffff0000, v116
	v_lshlrev_b32_e32 v116, 16, v117
	v_and_b32_e32 v117, 0xffff0000, v117
	v_pk_add_f32 v[62:63], v[62:63], v[116:117]
	v_pk_add_f32 v[60:61], v[60:61], v[120:121]
	v_lshlrev_b32_e32 v122, 16, v118
	v_and_b32_e32 v123, 0xffff0000, v118
	v_lshlrev_b32_e32 v118, 16, v119
	v_and_b32_e32 v119, 0xffff0000, v119
	v_pk_add_f32 v[34:35], v[34:35], v[118:119]
	v_pk_add_f32 v[32:33], v[32:33], v[122:123]
	s_add_u32 s2, s8, 0x1400000
	s_addc_u32 s3, s9, 0
	s_mov_b32 s0, 0x1800000
	s_mov_b32 s1, 0
	s_cmp_lg_u32 s0, 0x1800000
	v_and_b32_e32 v66, 64, v201
	v_add_u32_e32 v66, 64, v66
	v_xor_b32_e32 v67, 1, v201
	v_cmp_lt_i32_e32 vcc, v67, v66
	s_mov_b32 s0, 0x3fd744fd
	v_pk_mul_f32 v[30:31], v[30:31], s[0:1] op_sel_hi:[1,0]
	v_cndmask_b32_e32 v67, v201, v67, vcc
	v_lshlrev_b32_e32 v89, 2, v67
	v_xor_b32_e32 v67, 2, v201
	v_cmp_lt_i32_e32 vcc, v67, v66
	v_pk_mul_f32 v[28:29], v[28:29], s[0:1] op_sel_hi:[1,0]
	v_pk_mul_f32 v[26:27], v[26:27], s[0:1] op_sel_hi:[1,0]
	v_cndmask_b32_e32 v67, v201, v67, vcc
	v_lshlrev_b32_e32 v104, 2, v67
	v_xor_b32_e32 v67, 4, v201
	v_cmp_lt_i32_e32 vcc, v67, v66
	v_pk_mul_f32 v[24:25], v[24:25], s[0:1] op_sel_hi:[1,0]
	v_pk_mul_f32 v[22:23], v[22:23], s[0:1] op_sel_hi:[1,0]
	v_cndmask_b32_e32 v67, v201, v67, vcc
	v_lshlrev_b32_e32 v105, 2, v67
	v_xor_b32_e32 v67, 8, v201
	v_cmp_lt_i32_e32 vcc, v67, v66
	v_pk_mul_f32 v[20:21], v[20:21], s[0:1] op_sel_hi:[1,0]
	v_pk_mul_f32 v[18:19], v[18:19], s[0:1] op_sel_hi:[1,0]
	v_cndmask_b32_e32 v67, v201, v67, vcc
	v_lshlrev_b32_e32 v106, 2, v67
	v_xor_b32_e32 v67, 16, v201
	v_cmp_lt_i32_e32 vcc, v67, v66
	v_pk_mul_f32 v[16:17], v[16:17], s[0:1] op_sel_hi:[1,0]
	v_pk_mul_f32 v[14:15], v[14:15], s[0:1] op_sel_hi:[1,0]
	v_cndmask_b32_e32 v67, v201, v67, vcc
	v_lshlrev_b32_e32 v107, 2, v67
	v_xor_b32_e32 v67, 32, v201
	v_cmp_lt_i32_e32 vcc, v67, v66
	v_pk_mul_f32 v[12:13], v[12:13], s[0:1] op_sel_hi:[1,0]
	v_pk_mul_f32 v[10:11], v[10:11], s[0:1] op_sel_hi:[1,0]
	v_cndmask_b32_e32 v66, v201, v67, vcc
	v_pk_mul_f32 v[8:9], v[8:9], s[0:1] op_sel_hi:[1,0]
	v_pk_mul_f32 v[6:7], v[6:7], s[0:1] op_sel_hi:[1,0]
	v_pk_mul_f32 v[4:5], v[4:5], s[0:1] op_sel_hi:[1,0]
	v_pk_mul_f32 v[2:3], v[2:3], s[0:1] op_sel_hi:[1,0]
	v_pk_mul_f32 v[0:1], v[0:1], s[0:1] op_sel_hi:[1,0]
	v_lshlrev_b32_e32 v108, 2, v66
	v_readlane_b32 s0, v245, 14
	v_readlane_b32 s8, v247, 36
	v_readlane_b32 s9, v247, 37

; #define GAS __attribute__((address_space(1)))
; #define LAS __attribute__((address_space(3)))
; #define LDS_WAIT() asm volatile("s_waitcnt lgkmcnt(0)" ::: "memory")
; __device__ __forceinline__ void ln_phase(Frame& FF, int l, int gi, const float* lng, const float* lnb, int lh, int hmod, bool first, bool to_out, int nrows, bool dry, int nslab) {
;     ...
;         __syncthreads();
;         { const float* gv = mo + ((size_t)l * 5 + mb) * 12288 + gi * 2048; const float* mh = mo + ((size_t)(hmod >= 0 ? lh : l) * 5 + mb) * 12288; const int c = 4 * F.tid;
;           *(LAS f32x4*)(V + 0 * 2048 + c) = *(const GAS f32x4*)(gv + c); *(LAS f32x4*)(V + 1 * 2048 + c) = *(const GAS f32x4*)(lng + c); *(LAS f32x4*)(V + 2 * 2048 + c) = *(const GAS f32x4*)(lnb + c);
;           if (hmod >= 0) { *(LAS f32x4*)(V + 3 * 2048 + c) = *(const GAS f32x4*)(mh + (hmod + 1) * 2048 + c) + 1.0f; *(LAS f32x4*)(V + 4 * 2048 + c) = *(const GAS f32x4*)(mh + hmod * 2048 + c); } }
;         LDS_WAIT(); __syncthreads();
.LBB0_1815:
	v_readlane_b32 s4, v245, 50
	v_readlane_b32 s5, v245, 51
	s_and_b64 s[2:3], s[4:5], s[2:3]
	s_and_b64 vcc, exec, s[2:3]
	s_mov_b64 s[4:5], -1
	s_cbranch_vccnz .LBB0_1814
	s_and_b64 s[2:3], s[0:1], exec
	v_readlane_b32 s3, v247, 48
	v_readlane_b32 s2, v247, 49
	s_cselect_b32 s3, s3, 4
	s_cselect_b32 s2, s2, 0
	s_add_u32 s4, s3, s8
	s_addc_u32 s5, s2, 0
	s_mul_i32 s6, s5, 0xc000
	v_mad_u64_u32 v[0:1], s[4:5], s4, v207, v[180:181]
	v_add_u32_e32 v1, s6, v1
	s_waitcnt vmcnt(0)
	s_barrier
	global_load_dwordx4 v[0:3], v[0:1], off
	global_load_dwordx4 v[8:11], v[182:183], off
	global_load_dwordx4 v[12:15], v[184:185], off
	v_readlane_b32 s4, v245, 54
	v_readlane_b32 s5, v245, 55
	s_andn2_b64 vcc, exec, s[4:5]
	s_nop 1
	v_cndmask_b32_e64 v6, 0, 1, s[4:5]
	v_cmp_ne_u32_e64 s[38:39], 1, v6
	s_cbranch_vccnz .Lln2_stage_short
	s_add_u32 s3, s3, s9
	s_addc_u32 s2, s2, 0
	s_mul_i32 s2, s2, 0xc000
	s_mul_hi_u32 s4, s3, 0xc000
	s_add_i32 s4, s4, s2
	s_mul_i32 s3, s3, 0xc000
	s_add_u32 s2, s10, s3
	s_addc_u32 s3, s11, s4
	v_lshl_add_u64 v[4:5], v[178:179], 2, s[2:3]
	v_add_co_u32_e32 v6, vcc, 0x2000, v4
	s_nop 1
	v_addc_co_u32_e32 v7, vcc, 0, v5, vcc
	global_load_dwordx4 v[32:35], v[6:7], off
	global_load_dwordx4 v[36:39], v[4:5], off
	s_waitcnt vmcnt(4)
	ds_write_b128 v192, v[0:3]
	s_waitcnt vmcnt(3)
	ds_write_b128 v192, v[8:11] offset:8192
	s_waitcnt vmcnt(2)
	ds_write_b128 v192, v[12:15] offset:16384
	s_waitcnt vmcnt(1)
	v_pk_add_f32 v[34:35], v[34:35], 1.0 op_sel_hi:[1,0]
	v_pk_add_f32 v[32:33], v[32:33], 1.0 op_sel_hi:[1,0]
	ds_write_b128 v192, v[32:35] offset:24576
	s_waitcnt vmcnt(0)
	ds_write_b128 v192, v[36:39] offset:32768
	s_branch .LBB0_1818
.Lln2_stage_short:
	s_waitcnt vmcnt(2)
	ds_write_b128 v192, v[0:3]
	s_waitcnt vmcnt(1)
	ds_write_b128 v192, v[8:11] offset:8192
	s_waitcnt vmcnt(0)
	ds_write_b128 v192, v[12:15] offset:16384

.LBB0_1821:
	s_add_u32 s2, s23, 0
	s_addc_u32 s3, s24, 0
	v_lshl_add_u64 v[66:67], s[2:3], 0, v[186:187]
	global_load_dwordx2 v[72:73], v[66:67], off
	global_load_dwordx2 v[74:75], v[66:67], off offset:512
	global_load_dwordx2 v[76:77], v[66:67], off offset:1024
	global_load_dwordx2 v[78:79], v[66:67], off offset:1536
	global_load_dwordx2 v[80:81], v[66:67], off offset:2048
	global_load_dwordx2 v[82:83], v[66:67], off offset:2560
	global_load_dwordx2 v[84:85], v[66:67], off offset:3072
	global_load_dwordx2 v[86:87], v[66:67], off offset:3584
	s_add_u32 s2, s23, 0x400000
	s_addc_u32 s3, s24, 0
	v_lshl_add_u64 v[68:69], s[2:3], 0, v[186:187]
	global_load_dwordx2 v[88:89], v[68:69], off
	global_load_dwordx2 v[90:91], v[68:69], off offset:512
	global_load_dwordx2 v[92:93], v[68:69], off offset:1024
	global_load_dwordx2 v[94:95], v[68:69], off offset:1536
	global_load_dwordx2 v[96:97], v[68:69], off offset:2048
	global_load_dwordx2 v[98:99], v[68:69], off offset:2560
	global_load_dwordx2 v[100:101], v[68:69], off offset:3072
	global_load_dwordx2 v[102:103], v[68:69], off offset:3584
	s_add_u32 s2, s23, 0x800000
	s_addc_u32 s3, s24, 0
	v_lshl_add_u64 v[70:71], s[2:3], 0, v[186:187]
	global_load_dwordx2 v[104:105], v[70:71], off
	global_load_dwordx2 v[106:107], v[70:71], off offset:512
	global_load_dwordx2 v[108:109], v[70:71], off offset:1024
	global_load_dwordx2 v[110:111], v[70:71], off offset:1536
	global_load_dwordx2 v[112:113], v[70:71], off offset:2048
	global_load_dwordx2 v[114:115], v[70:71], off offset:2560
	global_load_dwordx2 v[116:117], v[70:71], off offset:3072
	global_load_dwordx2 v[118:119], v[70:71], off offset:3584
	s_waitcnt vmcnt(16)
	v_lshlrev_b32_e32 v120, 16, v72
	v_and_b32_e32 v121, 0xffff0000, v72
	v_lshlrev_b32_e32 v72, 16, v73
	v_and_b32_e32 v73, 0xffff0000, v73
	v_pk_add_f32 v[38:39], v[38:39], v[72:73]
	v_pk_add_f32 v[36:37], v[36:37], v[120:121]
	v_lshlrev_b32_e32 v122, 16, v74
	v_and_b32_e32 v123, 0xffff0000, v74
	v_lshlrev_b32_e32 v74, 16, v75
	v_and_b32_e32 v75, 0xffff0000, v75
	v_pk_add_f32 v[42:43], v[42:43], v[74:75]
	v_pk_add_f32 v[40:41], v[40:41], v[122:123]
	v_lshlrev_b32_e32 v120, 16, v76
	v_and_b32_e32 v121, 0xffff0000, v76
	v_lshlrev_b32_e32 v76, 16, v77
	v_and_b32_e32 v77, 0xffff0000, v77
	v_pk_add_f32 v[46:47], v[46:47], v[76:77]
	v_pk_add_f32 v[44:45], v[44:45], v[120:121]
	v_lshlrev_b32_e32 v122, 16, v78
	v_and_b32_e32 v123, 0xffff0000, v78
	v_lshlrev_b32_e32 v78, 16, v79
	v_and_b32_e32 v79, 0xffff0000, v79
	v_pk_add_f32 v[50:51], v[50:51], v[78:79]
	v_pk_add_f32 v[48:49], v[48:49], v[122:123]
	v_lshlrev_b32_e32 v120, 16, v80
	v_and_b32_e32 v121, 0xffff0000, v80
	v_lshlrev_b32_e32 v80, 16, v81
	v_and_b32_e32 v81, 0xffff0000, v81
	v_pk_add_f32 v[54:55], v[54:55], v[80:81]
	v_pk_add_f32 v[52:53], v[52:53], v[120:121]
	v_lshlrev_b32_e32 v122, 16, v82
	v_and_b32_e32 v123, 0xffff0000, v82
	v_lshlrev_b32_e32 v82, 16, v83
	v_and_b32_e32 v83, 0xffff0000, v83
	v_pk_add_f32 v[58:59], v[58:59], v[82:83]
	v_pk_add_f32 v[56:57], v[56:57], v[122:123]
	v_lshlrev_b32_e32 v120, 16, v84
	v_and_b32_e32 v121, 0xffff0000, v84
	v_lshlrev_b32_e32 v84, 16, v85
	v_and_b32_e32 v85, 0xffff0000, v85
	v_pk_add_f32 v[62:63], v[62:63], v[84:85]
	v_pk_add_f32 v[60:61], v[60:61], v[120:121]
	v_lshlrev_b32_e32 v122, 16, v86
	v_and_b32_e32 v123, 0xffff0000, v86
	v_lshlrev_b32_e32 v86, 16, v87
	v_and_b32_e32 v87, 0xffff0000, v87
	v_pk_add_f32 v[34:35], v[34:35], v[86:87]
	v_pk_add_f32 v[32:33], v[32:33], v[122:123]
	s_add_u32 s2, s23, 0xc00000
	s_addc_u32 s3, s24, 0
	v_lshl_add_u64 v[66:67], s[2:3], 0, v[186:187]
	global_load_dwordx2 v[72:73], v[66:67], off
	global_load_dwordx2 v[74:75], v[66:67], off offset:512
	global_load_dwordx2 v[76:77], v[66:67], off offset:1024
	global_load_dwordx2 v[78:79], v[66:67], off offset:1536
	global_load_dwordx2 v[80:81], v[66:67], off offset:2048
	global_load_dwordx2 v[82:83], v[66:67], off offset:2560
	global_load_dwordx2 v[84:85], v[66:67], off offset:3072
	global_load_dwordx2 v[86:87], v[66:67], off offset:3584
	s_waitcnt vmcnt(16)
	v_lshlrev_b32_e32 v120, 16, v88
	v_and_b32_e32 v121, 0xffff0000, v88
	v_lshlrev_b32_e32 v88, 16, v89
	v_and_b32_e32 v89, 0xffff0000, v89
	v_pk_add_f32 v[38:39], v[38:39], v[88:89]
	v_pk_add_f32 v[36:37], v[36:37], v[120:121]
	v_lshlrev_b32_e32 v122, 16, v90
	v_and_b32_e32 v123, 0xffff0000, v90
	v_lshlrev_b32_e32 v90, 16, v91
	v_and_b32_e32 v91, 0xffff0000, v91
	v_pk_add_f32 v[42:43], v[42:43], v[90:91]
	v_pk_add_f32 v[40:41], v[40:41], v[122:123]
	v_lshlrev_b32_e32 v120, 16, v92
	v_and_b32_e32 v121, 0xffff0000, v92
	v_lshlrev_b32_e32 v92, 16, v93
	v_and_b32_e32 v93, 0xffff0000, v93
	v_pk_add_f32 v[46:47], v[46:47], v[92:93]
	v_pk_add_f32 v[44:45], v[44:45], v[120:121]
	v_lshlrev_b32_e32 v122, 16, v94
	v_and_b32_e32 v123, 0xffff0000, v94
	v_lshlrev_b32_e32 v94, 16, v95
	v_and_b32_e32 v95, 0xffff0000, v95
	v_pk_add_f32 v[50:51], v[50:51], v[94:95]
	v_pk_add_f32 v[48:49], v[48:49], v[122:123]
	v_lshlrev_b32_e32 v120, 16, v96
	v_and_b32_e32 v121, 0xffff0000, v96
	v_lshlrev_b32_e32 v96, 16, v97
	v_and_b32_e32 v97, 0xffff0000, v97
	v_pk_add_f32 v[54:55], v[54:55], v[96:97]
	v_pk_add_f32 v[52:53], v[52:53], v[120:121]
	v_lshlrev_b32_e32 v122, 16, v98
	v_and_b32_e32 v123, 0xffff0000, v98
	v_lshlrev_b32_e32 v98, 16, v99
	v_and_b32_e32 v99, 0xffff0000, v99
	v_pk_add_f32 v[58:59], v[58:59], v[98:99]
	v_pk_add_f32 v[56:57], v[56:57], v[122:123]
	v_lshlrev_b32_e32 v120, 16, v100
	v_and_b32_e32 v121, 0xffff0000, v100
	v_lshlrev_b32_e32 v100, 16, v101
	v_and_b32_e32 v101, 0xffff0000, v101
	v_pk_add_f32 v[62:63], v[62:63], v[100:101]
	v_pk_add_f32 v[60:61], v[60:61], v[120:121]
	v_lshlrev_b32_e32 v122, 16, v102
	v_and_b32_e32 v123, 0xffff0000, v102
	v_lshlrev_b32_e32 v102, 16, v103
	v_and_b32_e32 v103, 0xffff0000, v103
	v_pk_add_f32 v[34:35], v[34:35], v[102:103]
	v_pk_add_f32 v[32:33], v[32:33], v[122:123]
	s_add_u32 s2, s23, 0x1000000
	s_addc_u32 s3, s24, 0
	v_lshl_add_u64 v[68:69], s[2:3], 0, v[186:187]
	global_load_dwordx2 v[88:89], v[68:69], off
	global_load_dwordx2 v[90:91], v[68:69], off offset:512
	global_load_dwordx2 v[92:93], v[68:69], off offset:1024
	global_load_dwordx2 v[94:95], v[68:69], off offset:1536
	global_load_dwordx2 v[96:97], v[68:69], off offset:2048
	global_load_dwordx2 v[98:99], v[68:69], off offset:2560
	global_load_dwordx2 v[100:101], v[68:69], off offset:3072
	global_load_dwordx2 v[102:103], v[68:69], off offset:3584
	s_waitcnt vmcnt(16)
	v_lshlrev_b32_e32 v120, 16, v104
	v_and_b32_e32 v121, 0xffff0000, v104
	v_lshlrev_b32_e32 v104, 16, v105
	v_and_b32_e32 v105, 0xffff0000, v105
	v_pk_add_f32 v[38:39], v[38:39], v[104:105]
	v_pk_add_f32 v[36:37], v[36:37], v[120:121]
	v_lshlrev_b32_e32 v122, 16, v106
	v_and_b32_e32 v123, 0xffff0000, v106
	v_lshlrev_b32_e32 v106, 16, v107
	v_and_b32_e32 v107, 0xffff0000, v107
	v_pk_add_f32 v[42:43], v[42:43], v[106:107]
	v_pk_add_f32 v[40:41], v[40:41], v[122:123]
	v_lshlrev_b32_e32 v120, 16, v108
	v_and_b32_e32 v121, 0xffff0000, v108
	v_lshlrev_b32_e32 v108, 16, v109
	v_and_b32_e32 v109, 0xffff0000, v109
	v_pk_add_f32 v[46:47], v[46:47], v[108:109]
	v_pk_add_f32 v[44:45], v[44:45], v[120:121]
	v_lshlrev_b32_e32 v122, 16, v110
	v_and_b32_e32 v123, 0xffff0000, v110
	v_lshlrev_b32_e32 v110, 16, v111
	v_and_b32_e32 v111, 0xffff0000, v111
	v_pk_add_f32 v[50:51], v[50:51], v[110:111]
	v_pk_add_f32 v[48:49], v[48:49], v[122:123]
	v_lshlrev_b32_e32 v120, 16, v112
	v_and_b32_e32 v121, 0xffff0000, v112
	v_lshlrev_b32_e32 v112, 16, v113
	v_and_b32_e32 v113, 0xffff0000, v113
	v_pk_add_f32 v[54:55], v[54:55], v[112:113]
	v_pk_add_f32 v[52:53], v[52:53], v[120:121]
	v_lshlrev_b32_e32 v122, 16, v114
	v_and_b32_e32 v123, 0xffff0000, v114
	v_lshlrev_b32_e32 v114, 16, v115
	v_and_b32_e32 v115, 0xffff0000, v115
	v_pk_add_f32 v[58:59], v[58:59], v[114:115]
	v_pk_add_f32 v[56:57], v[56:57], v[122:123]
	v_lshlrev_b32_e32 v120, 16, v116
	v_and_b32_e32 v121, 0xffff0000, v116
	v_lshlrev_b32_e32 v116, 16, v117
	v_and_b32_e32 v117, 0xffff0000, v117
	v_pk_add_f32 v[62:63], v[62:63], v[116:117]
	v_pk_add_f32 v[60:61], v[60:61], v[120:121]
	v_lshlrev_b32_e32 v122, 16, v118
	v_and_b32_e32 v123, 0xffff0000, v118
	v_lshlrev_b32_e32 v118, 16, v119
	v_and_b32_e32 v119, 0xffff0000, v119
	v_pk_add_f32 v[34:35], v[34:35], v[118:119]
	v_pk_add_f32 v[32:33], v[32:33], v[122:123]
	s_add_u32 s2, s23, 0x1400000
	s_addc_u32 s3, s24, 0
	v_lshl_add_u64 v[70:71], s[2:3], 0, v[186:187]
	global_load_dwordx2 v[104:105], v[70:71], off
	global_load_dwordx2 v[106:107], v[70:71], off offset:512
	global_load_dwordx2 v[108:109], v[70:71], off offset:1024
	global_load_dwordx2 v[110:111], v[70:71], off offset:1536
	global_load_dwordx2 v[112:113], v[70:71], off offset:2048
	global_load_dwordx2 v[114:115], v[70:71], off offset:2560
	global_load_dwordx2 v[116:117], v[70:71], off offset:3072
	global_load_dwordx2 v[118:119], v[70:71], off offset:3584
	s_waitcnt vmcnt(16)
	v_lshlrev_b32_e32 v120, 16, v72
	v_and_b32_e32 v121, 0xffff0000, v72
	v_lshlrev_b32_e32 v72, 16, v73
	v_and_b32_e32 v73, 0xffff0000, v73
	v_pk_add_f32 v[38:39], v[38:39], v[72:73]
	v_pk_add_f32 v[36:37], v[36:37], v[120:121]
	v_lshlrev_b32_e32 v122, 16, v74
	v_and_b32_e32 v123, 0xffff0000, v74
	v_lshlrev_b32_e32 v74, 16, v75
	v_and_b32_e32 v75, 0xffff0000, v75
	v_pk_add_f32 v[42:43], v[42:43], v[74:75]
	v_pk_add_f32 v[40:41], v[40:41], v[122:123]
	v_lshlrev_b32_e32 v120, 16, v76
	v_and_b32_e32 v121, 0xffff0000, v76
	v_lshlrev_b32_e32 v76, 16, v77
	v_and_b32_e32 v77, 0xffff0000, v77
	v_pk_add_f32 v[46:47], v[46:47], v[76:77]
	v_pk_add_f32 v[44:45], v[44:45], v[120:121]
	v_lshlrev_b32_e32 v122, 16, v78
	v_and_b32_e32 v123, 0xffff0000, v78
	v_lshlrev_b32_e32 v78, 16, v79
	v_and_b32_e32 v79, 0xffff0000, v79
	v_pk_add_f32 v[50:51], v[50:51], v[78:79]
	v_pk_add_f32 v[48:49], v[48:49], v[122:123]
	v_lshlrev_b32_e32 v120, 16, v80
	v_and_b32_e32 v121, 0xffff0000, v80
	v_lshlrev_b32_e32 v80, 16, v81
	v_and_b32_e32 v81, 0xffff0000, v81
	v_pk_add_f32 v[54:55], v[54:55], v[80:81]
	v_pk_add_f32 v[52:53], v[52:53], v[120:121]
	v_lshlrev_b32_e32 v122, 16, v82
	v_and_b32_e32 v123, 0xffff0000, v82
	v_lshlrev_b32_e32 v82, 16, v83
	v_and_b32_e32 v83, 0xffff0000, v83
	v_pk_add_f32 v[58:59], v[58:59], v[82:83]
	v_pk_add_f32 v[56:57], v[56:57], v[122:123]
	v_lshlrev_b32_e32 v120, 16, v84
	v_and_b32_e32 v121, 0xffff0000, v84
	v_lshlrev_b32_e32 v84, 16, v85
	v_and_b32_e32 v85, 0xffff0000, v85
	v_pk_add_f32 v[62:63], v[62:63], v[84:85]
	v_pk_add_f32 v[60:61], v[60:61], v[120:121]
	v_lshlrev_b32_e32 v122, 16, v86
	v_and_b32_e32 v123, 0xffff0000, v86
	v_lshlrev_b32_e32 v86, 16, v87
	v_and_b32_e32 v87, 0xffff0000, v87
	v_pk_add_f32 v[34:35], v[34:35], v[86:87]
	v_pk_add_f32 v[32:33], v[32:33], v[122:123]
	s_add_u32 s2, s23, 0x1800000
	s_addc_u32 s3, s24, 0
	v_lshl_add_u64 v[66:67], s[2:3], 0, v[186:187]
	global_load_dwordx2 v[72:73], v[66:67], off
	global_load_dwordx2 v[74:75], v[66:67], off offset:512
	global_load_dwordx2 v[76:77], v[66:67], off offset:1024
	global_load_dwordx2 v[78:79], v[66:67], off offset:1536
	global_load_dwordx2 v[80:81], v[66:67], off offset:2048
	global_load_dwordx2 v[82:83], v[66:67], off offset:2560
	global_load_dwordx2 v[84:85], v[66:67], off offset:3072
	global_load_dwordx2 v[86:87], v[66:67], off offset:3584
	s_waitcnt vmcnt(16)
	v_lshlrev_b32_e32 v120, 16, v88
	v_and_b32_e32 v121, 0xffff0000, v88
	v_lshlrev_b32_e32 v88, 16, v89
	v_and_b32_e32 v89, 0xffff0000, v89
	v_pk_add_f32 v[38:39], v[38:39], v[88:89]
	v_pk_add_f32 v[36:37], v[36:37], v[120:121]
	v_lshlrev_b32_e32 v122, 16, v90
	v_and_b32_e32 v123, 0xffff0000, v90
	v_lshlrev_b32_e32 v90, 16, v91
	v_and_b32_e32 v91, 0xffff0000, v91
	v_pk_add_f32 v[42:43], v[42:43], v[90:91]
	v_pk_add_f32 v[40:41], v[40:41], v[122:123]
	v_lshlrev_b32_e32 v120, 16, v92
	v_and_b32_e32 v121, 0xffff0000, v92
	v_lshlrev_b32_e32 v92, 16, v93
	v_and_b32_e32 v93, 0xffff0000, v93
	v_pk_add_f32 v[46:47], v[46:47], v[92:93]
	v_pk_add_f32 v[44:45], v[44:45], v[120:121]
	v_lshlrev_b32_e32 v122, 16, v94
	v_and_b32_e32 v123, 0xffff0000, v94
	v_lshlrev_b32_e32 v94, 16, v95
	v_and_b32_e32 v95, 0xffff0000, v95
	v_pk_add_f32 v[50:51], v[50:51], v[94:95]
	v_pk_add_f32 v[48:49], v[48:49], v[122:123]
	v_lshlrev_b32_e32 v120, 16, v96
	v_and_b32_e32 v121, 0xffff0000, v96
	v_lshlrev_b32_e32 v96, 16, v97
	v_and_b32_e32 v97, 0xffff0000, v97
	v_pk_add_f32 v[54:55], v[54:55], v[96:97]
	v_pk_add_f32 v[52:53], v[52:53], v[120:121]
	v_lshlrev_b32_e32 v122, 16, v98
	v_and_b32_e32 v123, 0xffff0000, v98
	v_lshlrev_b32_e32 v98, 16, v99
	v_and_b32_e32 v99, 0xffff0000, v99
	v_pk_add_f32 v[58:59], v[58:59], v[98:99]
	v_pk_add_f32 v[56:57], v[56:57], v[122:123]
	v_lshlrev_b32_e32 v120, 16, v100
	v_and_b32_e32 v121, 0xffff0000, v100
	v_lshlrev_b32_e32 v100, 16, v101
	v_and_b32_e32 v101, 0xffff0000, v101
	v_pk_add_f32 v[62:63], v[62:63], v[100:101]
	v_pk_add_f32 v[60:61], v[60:61], v[120:121]
	v_lshlrev_b32_e32 v122, 16, v102
	v_and_b32_e32 v123, 0xffff0000, v102
	v_lshlrev_b32_e32 v102, 16, v103
	v_and_b32_e32 v103, 0xffff0000, v103
	v_pk_add_f32 v[34:35], v[34:35], v[102:103]
	v_pk_add_f32 v[32:33], v[32:33], v[122:123]
	s_add_u32 s2, s23, 0x1c00000
	s_addc_u32 s3, s24, 0
	v_lshl_add_u64 v[68:69], s[2:3], 0, v[186:187]
	global_load_dwordx2 v[88:89], v[68:69], off
	global_load_dwordx2 v[90:91], v[68:69], off offset:512
	global_load_dwordx2 v[92:93], v[68:69], off offset:1024
	global_load_dwordx2 v[94:95], v[68:69], off offset:1536
	global_load_dwordx2 v[96:97], v[68:69], off offset:2048
	global_load_dwordx2 v[98:99], v[68:69], off offset:2560
	global_load_dwordx2 v[100:101], v[68:69], off offset:3072
	global_load_dwordx2 v[102:103], v[68:69], off offset:3584
	s_waitcnt vmcnt(16)
	v_lshlrev_b32_e32 v120, 16, v104
	v_and_b32_e32 v121, 0xffff0000, v104
	v_lshlrev_b32_e32 v104, 16, v105
	v_and_b32_e32 v105, 0xffff0000, v105
	v_pk_add_f32 v[38:39], v[38:39], v[104:105]
	v_pk_add_f32 v[36:37], v[36:37], v[120:121]
	v_lshlrev_b32_e32 v122, 16, v106
	v_and_b32_e32 v123, 0xffff0000, v106
	v_lshlrev_b32_e32 v106, 16, v107
	v_and_b32_e32 v107, 0xffff0000, v107
	v_pk_add_f32 v[42:43], v[42:43], v[106:107]
	v_pk_add_f32 v[40:41], v[40:41], v[122:123]
	v_lshlrev_b32_e32 v120, 16, v108
	v_and_b32_e32 v121, 0xffff0000, v108
	v_lshlrev_b32_e32 v108, 16, v109
	v_and_b32_e32 v109, 0xffff0000, v109
	v_pk_add_f32 v[46:47], v[46:47], v[108:109]
	v_pk_add_f32 v[44:45], v[44:45], v[120:121]
	v_lshlrev_b32_e32 v122, 16, v110
	v_and_b32_e32 v123, 0xffff0000, v110
	v_lshlrev_b32_e32 v110, 16, v111
	v_and_b32_e32 v111, 0xffff0000, v111
	v_pk_add_f32 v[50:51], v[50:51], v[110:111]
	v_pk_add_f32 v[48:49], v[48:49], v[122:123]
	v_lshlrev_b32_e32 v120, 16, v112
	v_and_b32_e32 v121, 0xffff0000, v112
	v_lshlrev_b32_e32 v112, 16, v113
	v_and_b32_e32 v113, 0xffff0000, v113
	v_pk_add_f32 v[54:55], v[54:55], v[112:113]
	v_pk_add_f32 v[52:53], v[52:53], v[120:121]
	v_lshlrev_b32_e32 v122, 16, v114
	v_and_b32_e32 v123, 0xffff0000, v114
	v_lshlrev_b32_e32 v114, 16, v115
	v_and_b32_e32 v115, 0xffff0000, v115
	v_pk_add_f32 v[58:59], v[58:59], v[114:115]
	v_pk_add_f32 v[56:57], v[56:57], v[122:123]
	v_lshlrev_b32_e32 v120, 16, v116
	v_and_b32_e32 v121, 0xffff0000, v116
	v_lshlrev_b32_e32 v116, 16, v117
	v_and_b32_e32 v117, 0xffff0000, v117
	v_pk_add_f32 v[62:63], v[62:63], v[116:117]
	v_pk_add_f32 v[60:61], v[60:61], v[120:121]
	v_lshlrev_b32_e32 v122, 16, v118
	v_and_b32_e32 v123, 0xffff0000, v118
	v_lshlrev_b32_e32 v118, 16, v119
	v_and_b32_e32 v119, 0xffff0000, v119
	v_pk_add_f32 v[34:35], v[34:35], v[118:119]
	v_pk_add_f32 v[32:33], v[32:33], v[122:123]
	s_waitcnt vmcnt(8)
; #define LAS __attribute__((address_space(3)))
; __device__ __forceinline__ void ln_rows(Frame& F, const float* xbase, const float* mixbase, int nslab, float* obase, bf16* hbase, int row0, int nr, bool hm, LAS float* V, int lane, int wave) {
;     ...
;     if (nr > 0) LN_LOAD(row0 + wave);
;     for (int i = 0; i < nr; ++i) { const int row = row0 + wave + 8 * i;
;         f32x4 v[8]; float s = 0.f;
; #pragma unroll
;         for (int j = 0; j < 8; ++j) { const f32x4 g = *(const LAS f32x4*)(V + 0 * 2048 + 4 * lane + 256 * j); v[j] = xn[j] * DN_ALPHA + g * mn[j]; s += (v[j][0] + v[j][1]) + (v[j][2] + v[j][3]); }
;         __builtin_amdgcn_sched_barrier(0);
;         if (i + 1 < nr) LN_LOAD(row + 8);
;         __builtin_amdgcn_sched_barrier(0);
;         const float mean = wave_sum(s) * (1.f / DM); float q = 0.f;
	v_lshlrev_b32_e32 v120, 16, v72
	v_and_b32_e32 v121, 0xffff0000, v72
	v_lshlrev_b32_e32 v72, 16, v73
	v_and_b32_e32 v73, 0xffff0000, v73
	v_pk_add_f32 v[38:39], v[38:39], v[72:73]
	v_pk_add_f32 v[36:37], v[36:37], v[120:121]
	v_lshlrev_b32_e32 v122, 16, v74
	v_and_b32_e32 v123, 0xffff0000, v74
	v_lshlrev_b32_e32 v74, 16, v75
	v_and_b32_e32 v75, 0xffff0000, v75
	v_pk_add_f32 v[42:43], v[42:43], v[74:75]
	v_pk_add_f32 v[40:41], v[40:41], v[122:123]
	v_lshlrev_b32_e32 v120, 16, v76
	v_and_b32_e32 v121, 0xffff0000, v76
	v_lshlrev_b32_e32 v76, 16, v77
	v_and_b32_e32 v77, 0xffff0000, v77
	v_pk_add_f32 v[46:47], v[46:47], v[76:77]
	v_pk_add_f32 v[44:45], v[44:45], v[120:121]
	v_lshlrev_b32_e32 v122, 16, v78
	v_and_b32_e32 v123, 0xffff0000, v78
	v_lshlrev_b32_e32 v78, 16, v79
	v_and_b32_e32 v79, 0xffff0000, v79
	v_pk_add_f32 v[50:51], v[50:51], v[78:79]
	v_pk_add_f32 v[48:49], v[48:49], v[122:123]
	v_lshlrev_b32_e32 v120, 16, v80
	v_and_b32_e32 v121, 0xffff0000, v80
	v_lshlrev_b32_e32 v80, 16, v81
	v_and_b32_e32 v81, 0xffff0000, v81
	v_pk_add_f32 v[54:55], v[54:55], v[80:81]
	v_pk_add_f32 v[52:53], v[52:53], v[120:121]
	v_lshlrev_b32_e32 v122, 16, v82
	v_and_b32_e32 v123, 0xffff0000, v82
	v_lshlrev_b32_e32 v82, 16, v83
	v_and_b32_e32 v83, 0xffff0000, v83
	v_pk_add_f32 v[58:59], v[58:59], v[82:83]
	v_pk_add_f32 v[56:57], v[56:57], v[122:123]
	v_lshlrev_b32_e32 v120, 16, v84
	v_and_b32_e32 v121, 0xffff0000, v84
	v_lshlrev_b32_e32 v84, 16, v85
	v_and_b32_e32 v85, 0xffff0000, v85
	v_pk_add_f32 v[62:63], v[62:63], v[84:85]
	v_pk_add_f32 v[60:61], v[60:61], v[120:121]
	v_lshlrev_b32_e32 v122, 16, v86
	v_and_b32_e32 v123, 0xffff0000, v86
	v_lshlrev_b32_e32 v86, 16, v87
	v_and_b32_e32 v87, 0xffff0000, v87
	v_pk_add_f32 v[34:35], v[34:35], v[86:87]
	v_pk_add_f32 v[32:33], v[32:33], v[122:123]
	s_waitcnt vmcnt(0)
	v_lshlrev_b32_e32 v120, 16, v88
	v_and_b32_e32 v121, 0xffff0000, v88
	v_lshlrev_b32_e32 v88, 16, v89
	v_and_b32_e32 v89, 0xffff0000, v89
	v_pk_add_f32 v[38:39], v[38:39], v[88:89]
	v_pk_add_f32 v[36:37], v[36:37], v[120:121]
	v_lshlrev_b32_e32 v122, 16, v90
	v_and_b32_e32 v123, 0xffff0000, v90
	v_lshlrev_b32_e32 v90, 16, v91
	v_and_b32_e32 v91, 0xffff0000, v91
	v_pk_add_f32 v[42:43], v[42:43], v[90:91]
	v_pk_add_f32 v[40:41], v[40:41], v[122:123]
	v_lshlrev_b32_e32 v120, 16, v92
	v_and_b32_e32 v121, 0xffff0000, v92
	v_lshlrev_b32_e32 v92, 16, v93
	v_and_b32_e32 v93, 0xffff0000, v93
	v_pk_add_f32 v[46:47], v[46:47], v[92:93]
	v_pk_add_f32 v[44:45], v[44:45], v[120:121]
	v_lshlrev_b32_e32 v122, 16, v94
	v_and_b32_e32 v123, 0xffff0000, v94
	v_lshlrev_b32_e32 v94, 16, v95
	v_and_b32_e32 v95, 0xffff0000, v95
	v_pk_add_f32 v[50:51], v[50:51], v[94:95]
	v_pk_add_f32 v[48:49], v[48:49], v[122:123]
	v_lshlrev_b32_e32 v120, 16, v96
	v_and_b32_e32 v121, 0xffff0000, v96
	v_lshlrev_b32_e32 v96, 16, v97
	v_and_b32_e32 v97, 0xffff0000, v97
	v_pk_add_f32 v[54:55], v[54:55], v[96:97]
	v_pk_add_f32 v[52:53], v[52:53], v[120:121]
	v_lshlrev_b32_e32 v122, 16, v98
	v_and_b32_e32 v123, 0xffff0000, v98
	v_lshlrev_b32_e32 v98, 16, v99
	v_and_b32_e32 v99, 0xffff0000, v99
	v_pk_add_f32 v[58:59], v[58:59], v[98:99]
	v_pk_add_f32 v[56:57], v[56:57], v[122:123]
	v_lshlrev_b32_e32 v120, 16, v100
	v_and_b32_e32 v121, 0xffff0000, v100
	v_lshlrev_b32_e32 v100, 16, v101
	v_and_b32_e32 v101, 0xffff0000, v101
	v_pk_add_f32 v[62:63], v[62:63], v[100:101]
	v_pk_add_f32 v[60:61], v[60:61], v[120:121]
	v_lshlrev_b32_e32 v122, 16, v102
	v_and_b32_e32 v123, 0xffff0000, v102
	v_lshlrev_b32_e32 v102, 16, v103
	v_and_b32_e32 v103, 0xffff0000, v103
	v_pk_add_f32 v[34:35], v[34:35], v[102:103]
	v_pk_add_f32 v[32:33], v[32:33], v[122:123]
	s_add_u32 s2, s23, 0x1c00000
	s_addc_u32 s3, s24, 0
	s_mov_b32 s0, 0x2000000
	s_mov_b32 s1, 0
	s_cmp_lg_u32 s0, 0x2000000
	s_mov_b32 s0, 0x3fd744fd
	v_pk_mul_f32 v[68:69], v[0:1], s[0:1] op_sel_hi:[1,0]
	v_and_b32_e32 v0, 64, v201
	v_add_u32_e32 v0, 64, v0
	v_xor_b32_e32 v1, 1, v201
	v_cmp_lt_i32_e32 vcc, v1, v0
	v_pk_mul_f32 v[30:31], v[30:31], s[0:1] op_sel_hi:[1,0]
	v_pk_mul_f32 v[28:29], v[28:29], s[0:1] op_sel_hi:[1,0]
	v_cndmask_b32_e32 v1, v201, v1, vcc
	v_lshlrev_b32_e32 v106, 2, v1
	v_xor_b32_e32 v1, 2, v201
	v_cmp_lt_i32_e32 vcc, v1, v0
	v_pk_mul_f32 v[26:27], v[26:27], s[0:1] op_sel_hi:[1,0]
	v_pk_mul_f32 v[24:25], v[24:25], s[0:1] op_sel_hi:[1,0]
	v_cndmask_b32_e32 v1, v201, v1, vcc
	v_lshlrev_b32_e32 v107, 2, v1
	v_xor_b32_e32 v1, 4, v201
	v_cmp_lt_i32_e32 vcc, v1, v0
	v_pk_mul_f32 v[22:23], v[22:23], s[0:1] op_sel_hi:[1,0]
	v_pk_mul_f32 v[20:21], v[20:21], s[0:1] op_sel_hi:[1,0]
	v_cndmask_b32_e32 v1, v201, v1, vcc
	v_lshlrev_b32_e32 v108, 2, v1
	v_xor_b32_e32 v1, 8, v201
	v_cmp_lt_i32_e32 vcc, v1, v0
	v_pk_mul_f32 v[18:19], v[18:19], s[0:1] op_sel_hi:[1,0]
	v_pk_mul_f32 v[16:17], v[16:17], s[0:1] op_sel_hi:[1,0]
	v_cndmask_b32_e32 v1, v201, v1, vcc
	v_lshlrev_b32_e32 v109, 2, v1
	v_xor_b32_e32 v1, 16, v201
	v_cmp_lt_i32_e32 vcc, v1, v0
	v_pk_mul_f32 v[14:15], v[14:15], s[0:1] op_sel_hi:[1,0]
	v_pk_mul_f32 v[12:13], v[12:13], s[0:1] op_sel_hi:[1,0]
	v_cndmask_b32_e32 v1, v201, v1, vcc
	v_lshlrev_b32_e32 v110, 2, v1
	v_xor_b32_e32 v1, 32, v201
	v_cmp_lt_i32_e32 vcc, v1, v0
	v_pk_mul_f32 v[10:11], v[10:11], s[0:1] op_sel_hi:[1,0]
	v_pk_mul_f32 v[8:9], v[8:9], s[0:1] op_sel_hi:[1,0]
	v_cndmask_b32_e32 v0, v201, v1, vcc
	v_pk_mul_f32 v[6:7], v[6:7], s[0:1] op_sel_hi:[1,0]
	v_pk_mul_f32 v[4:5], v[4:5], s[0:1] op_sel_hi:[1,0]
	v_pk_mul_f32 v[66:67], v[2:3], s[0:1] op_sel_hi:[1,0]
	v_lshlrev_b32_e32 v111, 2, v0
	v_readlane_b32 s12, v245, 14
	v_readlane_b32 s6, v247, 36
	v_readlane_b32 s7, v247, 37
	s_branch .LBB0_1824

; __global__ void __launch_bounds__(NWAVES * 64, 2) fwd_kernel(Args args) {
;     extern __shared__ __attribute__((aligned(16))) unsigned char lds[];
	.amdhsa_kernel _Z10fwd_kernel4Args
		.amdhsa_group_segment_fixed_size 0
		.amdhsa_private_segment_fixed_size 0
		.amdhsa_kernarg_size 456
		.amdhsa_user_sgpr_count 2
		.amdhsa_user_sgpr_dispatch_ptr 0
		.amdhsa_user_sgpr_queue_ptr 0
		.amdhsa_user_sgpr_kernarg_segment_ptr 1
		.amdhsa_user_sgpr_dispatch_id 0
		.amdhsa_user_sgpr_kernarg_preload_length 0
		.amdhsa_user_sgpr_kernarg_preload_offset 0
		.amdhsa_user_sgpr_private_segment_size 0
		.amdhsa_uses_dynamic_stack 0
		.amdhsa_enable_private_segment 0
		.amdhsa_system_sgpr_workgroup_id_x 1
		.amdhsa_system_sgpr_workgroup_id_y 0
		.amdhsa_system_sgpr_workgroup_id_z 0
		.amdhsa_system_sgpr_workgroup_info 0
		.amdhsa_system_vgpr_workitem_id 0
		.amdhsa_next_free_vgpr 256
		.amdhsa_next_free_sgpr 102
		.amdhsa_accum_offset 256
		.amdhsa_reserve_vcc 1
		.amdhsa_float_round_mode_32 0
		.amdhsa_float_round_mode_16_64 0
		.amdhsa_float_denorm_mode_32 3
		.amdhsa_float_denorm_mode_16_64 3
		.amdhsa_dx10_clamp 1
		.amdhsa_ieee_mode 1
		.amdhsa_fp16_overflow 0
		.amdhsa_tg_split 0
		.amdhsa_exception_fp_ieee_invalid_op 0
		.amdhsa_exception_fp_denorm_src 0
		.amdhsa_exception_fp_ieee_div_zero 0
		.amdhsa_exception_fp_ieee_overflow 0
		.amdhsa_exception_fp_ieee_underflow 0
		.amdhsa_exception_fp_ieee_inexact 0
		.amdhsa_exception_int_div_zero 0
	.end_amdhsa_kernel

; __global__ void __launch_bounds__(NWAVES * 64, 2) fwd_kernel(Args args) {
;     extern __shared__ __attribute__((aligned(16))) unsigned char lds[];
amdhsa.kernels:
  - .agpr_count:     0
    .args:
      - .offset:         0
        .size:           200
        .value_kind:     by_value
      - .offset:         200
        .size:           4
        .value_kind:     hidden_block_count_x
      - .offset:         204
        .size:           4
        .value_kind:     hidden_block_count_y
      - .offset:         208
        .size:           4
        .value_kind:     hidden_block_count_z
      - .offset:         212
        .size:           2
        .value_kind:     hidden_group_size_x
      - .offset:         214
        .size:           2
        .value_kind:     hidden_group_size_y
      - .offset:         216
        .size:           2
        .value_kind:     hidden_group_size_z
      - .offset:         218
        .size:           2
        .value_kind:     hidden_remainder_x
      - .offset:         220
        .size:           2
        .value_kind:     hidden_remainder_y
      - .offset:         222
        .size:           2
        .value_kind:     hidden_remainder_z
      - .offset:         240
        .size:           8
        .value_kind:     hidden_global_offset_x
      - .offset:         248
        .size:           8
        .value_kind:     hidden_global_offset_y
      - .offset:         256
        .size:           8
        .value_kind:     hidden_global_offset_z
      - .offset:         264
        .size:           2
        .value_kind:     hidden_grid_dims
      - .offset:         320
        .size:           4
        .value_kind:     hidden_dynamic_lds_size
    .group_segment_fixed_size: 0
    .kernarg_segment_align: 8
    .kernarg_segment_size: 456
    .language:       OpenCL C
    .language_version:
      - 2
      - 0
    .max_flat_workgroup_size: 512
    .name:           _Z10fwd_kernel4Args
    .private_segment_fixed_size: 0
    .sgpr_count:     108
    .sgpr_spill_count: 492
    .symbol:         _Z10fwd_kernel4Args.kd
    .uniform_work_group_size: 1
    .uses_dynamic_stack: false
    .vgpr_count:     256
    .vgpr_spill_count: 0
    .wavefront_size: 64
